# adds: down-proj K-loop (K=2816, 44 k-tiles) replaced by the same hand-scheduled interleaved loop, fully unrolled, pointer bump at k-tile 32
# speedup vs baseline: 1.1010x; 1.0255x over previous
.LBB0_581:
	s_or_b64 exec, exec, s[20:21]
	s_lshl_b32 s0, s36, 1
	s_and_b32 s20, s0, 0xffffff80
	s_mul_i32 s0, s37, 0x1600
	v_readlane_b32 s22, v252, 60
	v_readlane_b32 s23, v252, 61
	s_add_u32 s0, s22, s0
	s_addc_u32 s1, s23, 0
	s_mul_i32 s22, s20, 0x1600
	s_mul_hi_i32 s21, s20, 0x1600
	s_add_u32 s22, s34, s22
	v_mov_b32_e32 v141, v0
	s_waitcnt vmcnt(0)
	s_addc_u32 s23, s35, s21
	v_mov_b64_e32 v[4:5], s[0:1]
	v_ashrrev_i32_e32 v6, 3, v141
	v_mad_i64_i32 v[132:133], s[0:1], v6, s73, v[4:5]
	v_lshlrev_b32_e32 v2, 4, v141
	v_mov_b64_e32 v[4:5], s[22:23]
	v_and_b32_e32 v2, 0x70, v2
	v_mad_i64_i32 v[134:135], s[0:1], v6, s73, v[4:5]
	s_waitcnt vmcnt(13)
	v_lshl_add_u64 v[72:73], v[132:133], 0, v[2:3]
	s_mov_b32 s0, 0x2c000
	s_waitcnt vmcnt(9)
	v_add_co_u32_e32 v80, vcc, s0, v72
	s_mov_b32 s1, 0x58000
	s_nop 0
	v_addc_co_u32_e32 v81, vcc, 0, v73, vcc
	s_waitcnt vmcnt(5)
	v_add_co_u32_e32 v88, vcc, s1, v72
	s_mov_b32 s21, 0x84000
	s_nop 0
	v_addc_co_u32_e32 v89, vcc, 0, v73, vcc
	s_waitcnt vmcnt(1)
	v_add_co_u32_e32 v96, vcc, s21, v72
	v_lshl_add_u64 v[104:105], v[134:135], 0, v[2:3]
	s_nop 0
	v_addc_co_u32_e32 v97, vcc, 0, v73, vcc
	s_mov_b32 s0, 0x2c000
	s_mov_b32 s1, 0
	v_lshl_add_u64 v[74:75], s[0:1], 0, v[72:73]
	s_mov_b32 s0, 0x58000
	s_mov_b32 s1, 0
	v_lshl_add_u64 v[106:107], s[0:1], 0, v[72:73]
	s_mov_b32 s0, 0x84000
	s_mov_b32 s1, 0
	v_lshl_add_u64 v[176:177], s[0:1], 0, v[72:73]
	s_mov_b32 s0, 0x2c000
	s_mov_b32 s1, 0
	v_lshl_add_u64 v[178:179], s[0:1], 0, v[104:105]
	s_mov_b32 s0, 0x58000
	s_mov_b32 s1, 0
	v_lshl_add_u64 v[180:181], s[0:1], 0, v[104:105]
	s_mov_b32 s0, 0x84000
	s_mov_b32 s1, 0
	v_lshl_add_u64 v[182:183], s[0:1], 0, v[104:105]
	v_lshrrev_b32_e32 v172, 3, v0
	v_lshlrev_b32_e32 v173, 4, v0
	v_mul_u32_u24_e32 v172, 0x90, v172
	v_and_b32_e32 v173, 0x70, v173
	v_add_u32_e32 v184, v172, v173
	v_add_u32_e32 v185, 0x9000, v184
	v_lshrrev_b32_e32 v172, 1, v0
	v_and_b32_e32 v173, 31, v0
	v_and_b32_e32 v174, 16, v172
	v_and_b32_e32 v172, 64, v172
	v_add_u32_e32 v172, v172, v173
	v_mul_u32_u24_e32 v172, 0x90, v172
	v_add_u32_e32 v186, v172, v174
	v_and_b32_e32 v172, 64, v0
	v_add_u32_e32 v172, v172, v173
	v_mul_u32_u24_e32 v172, 0x90, v172
	v_add_u32_e32 v187, v172, v174
	global_load_dwordx4 v[68:71], v[72:73], off
	global_load_dwordx4 v[76:79], v[74:75], off
	global_load_dwordx4 v[80:83], v[106:107], off
	global_load_dwordx4 v[84:87], v[176:177], off
	global_load_dwordx4 v[88:91], v[104:105], off
	global_load_dwordx4 v[92:95], v[178:179], off
	global_load_dwordx4 v[96:99], v[180:181], off
	global_load_dwordx4 v[100:103], v[182:183], off
	global_load_dwordx4 v[108:111], v[72:73], off offset:128
	global_load_dwordx4 v[112:115], v[74:75], off offset:128
	global_load_dwordx4 v[116:119], v[106:107], off offset:128
	global_load_dwordx4 v[120:123], v[176:177], off offset:128
	global_load_dwordx4 v[124:127], v[104:105], off offset:128
	global_load_dwordx4 v[128:131], v[178:179], off offset:128
	global_load_dwordx4 v[136:139], v[180:181], off offset:128
	global_load_dwordx4 v[140:143], v[182:183], off offset:128
	s_barrier
	s_waitcnt vmcnt(15)
	ds_write_b128 v184, v[68:71]
	s_waitcnt vmcnt(14)
	ds_write_b128 v184, v[76:79] offset:4608
	s_waitcnt vmcnt(13)
	ds_write_b128 v184, v[80:83] offset:9216
	s_waitcnt vmcnt(12)
	ds_write_b128 v184, v[84:87] offset:13824
	s_waitcnt vmcnt(11)
	ds_write_b128 v184, v[88:91] offset:18432
	s_waitcnt vmcnt(10)
	ds_write_b128 v184, v[92:95] offset:23040
	s_waitcnt vmcnt(9)
	ds_write_b128 v184, v[96:99] offset:27648
	s_waitcnt vmcnt(8)
	ds_write_b128 v184, v[100:103] offset:32256
	global_load_dwordx4 v[68:71], v[72:73], off offset:256
	global_load_dwordx4 v[76:79], v[74:75], off offset:256
	global_load_dwordx4 v[80:83], v[106:107], off offset:256
	global_load_dwordx4 v[84:87], v[176:177], off offset:256
	global_load_dwordx4 v[88:91], v[104:105], off offset:256
	global_load_dwordx4 v[92:95], v[178:179], off offset:256
	global_load_dwordx4 v[96:99], v[180:181], off offset:256
	global_load_dwordx4 v[100:103], v[182:183], off offset:256
	s_waitcnt lgkmcnt(0)
	s_barrier
	ds_read_b128 v[144:147], v186
	ds_read_b128 v[148:151], v187 offset:18432
	ds_read_b128 v[152:155], v187 offset:23040
	ds_read_b128 v[156:159], v186 offset:4608
	ds_read_b128 v[160:163], v186 offset:32
	ds_read_b128 v[164:167], v187 offset:18464
	ds_read_b128 v[168:171], v187 offset:23072
	ds_read_b128 v[172:175], v186 offset:4640
	s_setprio 1
	s_waitcnt lgkmcnt(6)
	v_mfma_f32_32x32x16_bf16 v[52:67], v[148:151], v[144:147], 0
	s_waitcnt vmcnt(15)
	ds_write_b128 v185, v[108:111]
	s_waitcnt lgkmcnt(6)
	v_mfma_f32_32x32x16_bf16 v[36:51], v[152:155], v[144:147], 0
	s_waitcnt vmcnt(14)
	ds_write_b128 v185, v[112:115] offset:4608
	s_waitcnt lgkmcnt(6)
	v_mfma_f32_32x32x16_bf16 v[20:35], v[148:151], v[156:159], 0
	s_waitcnt vmcnt(13)
	ds_write_b128 v185, v[116:119] offset:9216
	global_load_dwordx4 v[108:111], v[72:73], off offset:384
	v_mfma_f32_32x32x16_bf16 v[4:19], v[152:155], v[156:159], 0
	ds_read_b128 v[144:147], v186 offset:64
	ds_read_b128 v[148:151], v187 offset:18496
	s_waitcnt lgkmcnt(7)
	v_mfma_f32_32x32x16_bf16 v[52:67], v[164:167], v[160:163], v[52:67]
	ds_read_b128 v[152:155], v187 offset:23104
	ds_read_b128 v[156:159], v186 offset:4672
	s_waitcnt lgkmcnt(8)
	v_mfma_f32_32x32x16_bf16 v[36:51], v[168:171], v[160:163], v[36:51]
	s_waitcnt vmcnt(13)
	ds_write_b128 v185, v[120:123] offset:13824
	global_load_dwordx4 v[112:115], v[74:75], off offset:384
	s_waitcnt lgkmcnt(8)
	v_mfma_f32_32x32x16_bf16 v[20:35], v[164:167], v[172:175], v[20:35]
	s_waitcnt vmcnt(13)
	ds_write_b128 v185, v[124:127] offset:18432
	global_load_dwordx4 v[116:119], v[106:107], off offset:384
	v_mfma_f32_32x32x16_bf16 v[4:19], v[168:171], v[172:175], v[4:19]
	ds_read_b128 v[160:163], v186 offset:96
	ds_read_b128 v[164:167], v187 offset:18528
	s_waitcnt lgkmcnt(6)
	v_mfma_f32_32x32x16_bf16 v[52:67], v[148:151], v[144:147], v[52:67]
	ds_read_b128 v[168:171], v187 offset:23136
	ds_read_b128 v[172:175], v186 offset:4704
	s_waitcnt lgkmcnt(7)
	v_mfma_f32_32x32x16_bf16 v[36:51], v[152:155], v[144:147], v[36:51]
	s_waitcnt vmcnt(13)
	ds_write_b128 v185, v[128:131] offset:23040
	global_load_dwordx4 v[120:123], v[176:177], off offset:384
	s_waitcnt lgkmcnt(7)
	v_mfma_f32_32x32x16_bf16 v[20:35], v[148:151], v[156:159], v[20:35]
	s_waitcnt vmcnt(13)
	ds_write_b128 v185, v[136:139] offset:27648
	global_load_dwordx4 v[124:127], v[104:105], off offset:384
	v_mfma_f32_32x32x16_bf16 v[4:19], v[152:155], v[156:159], v[4:19]
	s_waitcnt vmcnt(13)
	ds_write_b128 v185, v[140:143] offset:32256
	global_load_dwordx4 v[128:131], v[178:179], off offset:384
	s_waitcnt lgkmcnt(5)
	v_mfma_f32_32x32x16_bf16 v[52:67], v[164:167], v[160:163], v[52:67]
	global_load_dwordx4 v[136:139], v[180:181], off offset:384
	s_waitcnt lgkmcnt(4)
	v_mfma_f32_32x32x16_bf16 v[36:51], v[168:171], v[160:163], v[36:51]
	global_load_dwordx4 v[140:143], v[182:183], off offset:384
	s_waitcnt lgkmcnt(3)
	v_mfma_f32_32x32x16_bf16 v[20:35], v[164:167], v[172:175], v[20:35]
	v_mfma_f32_32x32x16_bf16 v[4:19], v[168:171], v[172:175], v[4:19]
	s_setprio 0
	s_waitcnt lgkmcnt(0)
	s_barrier
	ds_read_b128 v[144:147], v186 offset:36864
	ds_read_b128 v[148:151], v187 offset:55296
	ds_read_b128 v[152:155], v187 offset:59904
	ds_read_b128 v[156:159], v186 offset:41472
	ds_read_b128 v[160:163], v186 offset:36896
	ds_read_b128 v[164:167], v187 offset:55328
	ds_read_b128 v[168:171], v187 offset:59936
	ds_read_b128 v[172:175], v186 offset:41504
	s_setprio 1
	s_waitcnt lgkmcnt(6)
	v_mfma_f32_32x32x16_bf16 v[52:67], v[148:151], v[144:147], v[52:67]
	s_waitcnt vmcnt(15)
	ds_write_b128 v184, v[68:71]
	s_waitcnt lgkmcnt(6)
	v_mfma_f32_32x32x16_bf16 v[36:51], v[152:155], v[144:147], v[36:51]
	s_waitcnt vmcnt(14)
	ds_write_b128 v184, v[76:79] offset:4608
	s_waitcnt lgkmcnt(6)
	v_mfma_f32_32x32x16_bf16 v[20:35], v[148:151], v[156:159], v[20:35]
	s_waitcnt vmcnt(13)
	ds_write_b128 v184, v[80:83] offset:9216
	global_load_dwordx4 v[68:71], v[72:73], off offset:512
	v_mfma_f32_32x32x16_bf16 v[4:19], v[152:155], v[156:159], v[4:19]
	ds_read_b128 v[144:147], v186 offset:36928
	ds_read_b128 v[148:151], v187 offset:55360
	s_waitcnt lgkmcnt(7)
	v_mfma_f32_32x32x16_bf16 v[52:67], v[164:167], v[160:163], v[52:67]
	ds_read_b128 v[152:155], v187 offset:59968
	ds_read_b128 v[156:159], v186 offset:41536
	s_waitcnt lgkmcnt(8)
	v_mfma_f32_32x32x16_bf16 v[36:51], v[168:171], v[160:163], v[36:51]
	s_waitcnt vmcnt(13)
	ds_write_b128 v184, v[84:87] offset:13824
	global_load_dwordx4 v[76:79], v[74:75], off offset:512
	s_waitcnt lgkmcnt(8)
	v_mfma_f32_32x32x16_bf16 v[20:35], v[164:167], v[172:175], v[20:35]
	s_waitcnt vmcnt(13)
	ds_write_b128 v184, v[88:91] offset:18432
	global_load_dwordx4 v[80:83], v[106:107], off offset:512
	v_mfma_f32_32x32x16_bf16 v[4:19], v[168:171], v[172:175], v[4:19]
	ds_read_b128 v[160:163], v186 offset:36960
	ds_read_b128 v[164:167], v187 offset:55392
	s_waitcnt lgkmcnt(6)
	v_mfma_f32_32x32x16_bf16 v[52:67], v[148:151], v[144:147], v[52:67]
	ds_read_b128 v[168:171], v187 offset:60000
	ds_read_b128 v[172:175], v186 offset:41568
	s_waitcnt lgkmcnt(7)
	v_mfma_f32_32x32x16_bf16 v[36:51], v[152:155], v[144:147], v[36:51]
	s_waitcnt vmcnt(13)
	ds_write_b128 v184, v[92:95] offset:23040
	global_load_dwordx4 v[84:87], v[176:177], off offset:512
	s_waitcnt lgkmcnt(7)
	v_mfma_f32_32x32x16_bf16 v[20:35], v[148:151], v[156:159], v[20:35]
	s_waitcnt vmcnt(13)
	ds_write_b128 v184, v[96:99] offset:27648
	global_load_dwordx4 v[88:91], v[104:105], off offset:512
	v_mfma_f32_32x32x16_bf16 v[4:19], v[152:155], v[156:159], v[4:19]
	s_waitcnt vmcnt(13)
	ds_write_b128 v184, v[100:103] offset:32256
	global_load_dwordx4 v[92:95], v[178:179], off offset:512
	s_waitcnt lgkmcnt(5)
	v_mfma_f32_32x32x16_bf16 v[52:67], v[164:167], v[160:163], v[52:67]
	global_load_dwordx4 v[96:99], v[180:181], off offset:512
	s_waitcnt lgkmcnt(4)
	v_mfma_f32_32x32x16_bf16 v[36:51], v[168:171], v[160:163], v[36:51]
	global_load_dwordx4 v[100:103], v[182:183], off offset:512
	s_waitcnt lgkmcnt(3)
	v_mfma_f32_32x32x16_bf16 v[20:35], v[164:167], v[172:175], v[20:35]
	v_mfma_f32_32x32x16_bf16 v[4:19], v[168:171], v[172:175], v[4:19]
	s_setprio 0
	s_waitcnt lgkmcnt(0)
	s_barrier
	ds_read_b128 v[144:147], v186
	ds_read_b128 v[148:151], v187 offset:18432
	ds_read_b128 v[152:155], v187 offset:23040
	ds_read_b128 v[156:159], v186 offset:4608
	ds_read_b128 v[160:163], v186 offset:32
	ds_read_b128 v[164:167], v187 offset:18464
	ds_read_b128 v[168:171], v187 offset:23072
	ds_read_b128 v[172:175], v186 offset:4640
	s_setprio 1
	s_waitcnt lgkmcnt(6)
	v_mfma_f32_32x32x16_bf16 v[52:67], v[148:151], v[144:147], v[52:67]
	s_waitcnt vmcnt(15)
	ds_write_b128 v185, v[108:111]
	s_waitcnt lgkmcnt(6)
	v_mfma_f32_32x32x16_bf16 v[36:51], v[152:155], v[144:147], v[36:51]
	s_waitcnt vmcnt(14)
	ds_write_b128 v185, v[112:115] offset:4608
	s_waitcnt lgkmcnt(6)
	v_mfma_f32_32x32x16_bf16 v[20:35], v[148:151], v[156:159], v[20:35]
	s_waitcnt vmcnt(13)
	ds_write_b128 v185, v[116:119] offset:9216
	global_load_dwordx4 v[108:111], v[72:73], off offset:640
	v_mfma_f32_32x32x16_bf16 v[4:19], v[152:155], v[156:159], v[4:19]
	ds_read_b128 v[144:147], v186 offset:64
	ds_read_b128 v[148:151], v187 offset:18496
	s_waitcnt lgkmcnt(7)
	v_mfma_f32_32x32x16_bf16 v[52:67], v[164:167], v[160:163], v[52:67]
	ds_read_b128 v[152:155], v187 offset:23104
	ds_read_b128 v[156:159], v186 offset:4672
	s_waitcnt lgkmcnt(8)
	v_mfma_f32_32x32x16_bf16 v[36:51], v[168:171], v[160:163], v[36:51]
	s_waitcnt vmcnt(13)
	ds_write_b128 v185, v[120:123] offset:13824
	global_load_dwordx4 v[112:115], v[74:75], off offset:640
	s_waitcnt lgkmcnt(8)
	v_mfma_f32_32x32x16_bf16 v[20:35], v[164:167], v[172:175], v[20:35]
	s_waitcnt vmcnt(13)
	ds_write_b128 v185, v[124:127] offset:18432
	global_load_dwordx4 v[116:119], v[106:107], off offset:640
	v_mfma_f32_32x32x16_bf16 v[4:19], v[168:171], v[172:175], v[4:19]
	ds_read_b128 v[160:163], v186 offset:96
	ds_read_b128 v[164:167], v187 offset:18528
	s_waitcnt lgkmcnt(6)
	v_mfma_f32_32x32x16_bf16 v[52:67], v[148:151], v[144:147], v[52:67]
	ds_read_b128 v[168:171], v187 offset:23136
	ds_read_b128 v[172:175], v186 offset:4704
	s_waitcnt lgkmcnt(7)
	v_mfma_f32_32x32x16_bf16 v[36:51], v[152:155], v[144:147], v[36:51]
	s_waitcnt vmcnt(13)
	ds_write_b128 v185, v[128:131] offset:23040
	global_load_dwordx4 v[120:123], v[176:177], off offset:640
	s_waitcnt lgkmcnt(7)
	v_mfma_f32_32x32x16_bf16 v[20:35], v[148:151], v[156:159], v[20:35]
	s_waitcnt vmcnt(13)
	ds_write_b128 v185, v[136:139] offset:27648
	global_load_dwordx4 v[124:127], v[104:105], off offset:640
	v_mfma_f32_32x32x16_bf16 v[4:19], v[152:155], v[156:159], v[4:19]
	s_waitcnt vmcnt(13)
	ds_write_b128 v185, v[140:143] offset:32256
	global_load_dwordx4 v[128:131], v[178:179], off offset:640
	s_waitcnt lgkmcnt(5)
	v_mfma_f32_32x32x16_bf16 v[52:67], v[164:167], v[160:163], v[52:67]
	global_load_dwordx4 v[136:139], v[180:181], off offset:640
	s_waitcnt lgkmcnt(4)
	v_mfma_f32_32x32x16_bf16 v[36:51], v[168:171], v[160:163], v[36:51]
	global_load_dwordx4 v[140:143], v[182:183], off offset:640
	s_waitcnt lgkmcnt(3)
	v_mfma_f32_32x32x16_bf16 v[20:35], v[164:167], v[172:175], v[20:35]
	v_mfma_f32_32x32x16_bf16 v[4:19], v[168:171], v[172:175], v[4:19]
	s_setprio 0
	s_waitcnt lgkmcnt(0)
	s_barrier
	ds_read_b128 v[144:147], v186 offset:36864
	ds_read_b128 v[148:151], v187 offset:55296
	ds_read_b128 v[152:155], v187 offset:59904
	ds_read_b128 v[156:159], v186 offset:41472
	ds_read_b128 v[160:163], v186 offset:36896
	ds_read_b128 v[164:167], v187 offset:55328
	ds_read_b128 v[168:171], v187 offset:59936
	ds_read_b128 v[172:175], v186 offset:41504
	s_setprio 1
	s_waitcnt lgkmcnt(6)
	v_mfma_f32_32x32x16_bf16 v[52:67], v[148:151], v[144:147], v[52:67]
	s_waitcnt vmcnt(15)
	ds_write_b128 v184, v[68:71]
	s_waitcnt lgkmcnt(6)
	v_mfma_f32_32x32x16_bf16 v[36:51], v[152:155], v[144:147], v[36:51]
	s_waitcnt vmcnt(14)
	ds_write_b128 v184, v[76:79] offset:4608
	s_waitcnt lgkmcnt(6)
	v_mfma_f32_32x32x16_bf16 v[20:35], v[148:151], v[156:159], v[20:35]
	s_waitcnt vmcnt(13)
	ds_write_b128 v184, v[80:83] offset:9216
	global_load_dwordx4 v[68:71], v[72:73], off offset:768
	v_mfma_f32_32x32x16_bf16 v[4:19], v[152:155], v[156:159], v[4:19]
	ds_read_b128 v[144:147], v186 offset:36928
	ds_read_b128 v[148:151], v187 offset:55360
	s_waitcnt lgkmcnt(7)
	v_mfma_f32_32x32x16_bf16 v[52:67], v[164:167], v[160:163], v[52:67]
	ds_read_b128 v[152:155], v187 offset:59968
	ds_read_b128 v[156:159], v186 offset:41536
	s_waitcnt lgkmcnt(8)
	v_mfma_f32_32x32x16_bf16 v[36:51], v[168:171], v[160:163], v[36:51]
	s_waitcnt vmcnt(13)
	ds_write_b128 v184, v[84:87] offset:13824
	global_load_dwordx4 v[76:79], v[74:75], off offset:768
	s_waitcnt lgkmcnt(8)
	v_mfma_f32_32x32x16_bf16 v[20:35], v[164:167], v[172:175], v[20:35]
	s_waitcnt vmcnt(13)
	ds_write_b128 v184, v[88:91] offset:18432
	global_load_dwordx4 v[80:83], v[106:107], off offset:768
	v_mfma_f32_32x32x16_bf16 v[4:19], v[168:171], v[172:175], v[4:19]
	ds_read_b128 v[160:163], v186 offset:36960
	ds_read_b128 v[164:167], v187 offset:55392
	s_waitcnt lgkmcnt(6)
	v_mfma_f32_32x32x16_bf16 v[52:67], v[148:151], v[144:147], v[52:67]
	ds_read_b128 v[168:171], v187 offset:60000
	ds_read_b128 v[172:175], v186 offset:41568
	s_waitcnt lgkmcnt(7)
	v_mfma_f32_32x32x16_bf16 v[36:51], v[152:155], v[144:147], v[36:51]
	s_waitcnt vmcnt(13)
	ds_write_b128 v184, v[92:95] offset:23040
	global_load_dwordx4 v[84:87], v[176:177], off offset:768
	s_waitcnt lgkmcnt(7)
	v_mfma_f32_32x32x16_bf16 v[20:35], v[148:151], v[156:159], v[20:35]
	s_waitcnt vmcnt(13)
	ds_write_b128 v184, v[96:99] offset:27648
	global_load_dwordx4 v[88:91], v[104:105], off offset:768
	v_mfma_f32_32x32x16_bf16 v[4:19], v[152:155], v[156:159], v[4:19]
	s_waitcnt vmcnt(13)
	ds_write_b128 v184, v[100:103] offset:32256
	global_load_dwordx4 v[92:95], v[178:179], off offset:768
	s_waitcnt lgkmcnt(5)
	v_mfma_f32_32x32x16_bf16 v[52:67], v[164:167], v[160:163], v[52:67]
	global_load_dwordx4 v[96:99], v[180:181], off offset:768
	s_waitcnt lgkmcnt(4)
	v_mfma_f32_32x32x16_bf16 v[36:51], v[168:171], v[160:163], v[36:51]
	global_load_dwordx4 v[100:103], v[182:183], off offset:768
	s_waitcnt lgkmcnt(3)
	v_mfma_f32_32x32x16_bf16 v[20:35], v[164:167], v[172:175], v[20:35]
	v_mfma_f32_32x32x16_bf16 v[4:19], v[168:171], v[172:175], v[4:19]
	s_setprio 0
	s_waitcnt lgkmcnt(0)
	s_barrier
	ds_read_b128 v[144:147], v186
	ds_read_b128 v[148:151], v187 offset:18432
	ds_read_b128 v[152:155], v187 offset:23040
	ds_read_b128 v[156:159], v186 offset:4608
	ds_read_b128 v[160:163], v186 offset:32
	ds_read_b128 v[164:167], v187 offset:18464
	ds_read_b128 v[168:171], v187 offset:23072
	ds_read_b128 v[172:175], v186 offset:4640
	s_setprio 1
	s_waitcnt lgkmcnt(6)
	v_mfma_f32_32x32x16_bf16 v[52:67], v[148:151], v[144:147], v[52:67]
	s_waitcnt vmcnt(15)
	ds_write_b128 v185, v[108:111]
	s_waitcnt lgkmcnt(6)
	v_mfma_f32_32x32x16_bf16 v[36:51], v[152:155], v[144:147], v[36:51]
	s_waitcnt vmcnt(14)
	ds_write_b128 v185, v[112:115] offset:4608
	s_waitcnt lgkmcnt(6)
	v_mfma_f32_32x32x16_bf16 v[20:35], v[148:151], v[156:159], v[20:35]
	s_waitcnt vmcnt(13)
	ds_write_b128 v185, v[116:119] offset:9216
	global_load_dwordx4 v[108:111], v[72:73], off offset:896
	v_mfma_f32_32x32x16_bf16 v[4:19], v[152:155], v[156:159], v[4:19]
	ds_read_b128 v[144:147], v186 offset:64
	ds_read_b128 v[148:151], v187 offset:18496
	s_waitcnt lgkmcnt(7)
	v_mfma_f32_32x32x16_bf16 v[52:67], v[164:167], v[160:163], v[52:67]
	ds_read_b128 v[152:155], v187 offset:23104
	ds_read_b128 v[156:159], v186 offset:4672
	s_waitcnt lgkmcnt(8)
	v_mfma_f32_32x32x16_bf16 v[36:51], v[168:171], v[160:163], v[36:51]
	s_waitcnt vmcnt(13)
	ds_write_b128 v185, v[120:123] offset:13824
	global_load_dwordx4 v[112:115], v[74:75], off offset:896
	s_waitcnt lgkmcnt(8)
	v_mfma_f32_32x32x16_bf16 v[20:35], v[164:167], v[172:175], v[20:35]
	s_waitcnt vmcnt(13)
	ds_write_b128 v185, v[124:127] offset:18432
	global_load_dwordx4 v[116:119], v[106:107], off offset:896
	v_mfma_f32_32x32x16_bf16 v[4:19], v[168:171], v[172:175], v[4:19]
	ds_read_b128 v[160:163], v186 offset:96
	ds_read_b128 v[164:167], v187 offset:18528
	s_waitcnt lgkmcnt(6)
	v_mfma_f32_32x32x16_bf16 v[52:67], v[148:151], v[144:147], v[52:67]
	ds_read_b128 v[168:171], v187 offset:23136
	ds_read_b128 v[172:175], v186 offset:4704
	s_waitcnt lgkmcnt(7)
	v_mfma_f32_32x32x16_bf16 v[36:51], v[152:155], v[144:147], v[36:51]
	s_waitcnt vmcnt(13)
	ds_write_b128 v185, v[128:131] offset:23040
	global_load_dwordx4 v[120:123], v[176:177], off offset:896
	s_waitcnt lgkmcnt(7)
	v_mfma_f32_32x32x16_bf16 v[20:35], v[148:151], v[156:159], v[20:35]
	s_waitcnt vmcnt(13)
	ds_write_b128 v185, v[136:139] offset:27648
	global_load_dwordx4 v[124:127], v[104:105], off offset:896
	v_mfma_f32_32x32x16_bf16 v[4:19], v[152:155], v[156:159], v[4:19]
	s_waitcnt vmcnt(13)
	ds_write_b128 v185, v[140:143] offset:32256
	global_load_dwordx4 v[128:131], v[178:179], off offset:896
	s_waitcnt lgkmcnt(5)
	v_mfma_f32_32x32x16_bf16 v[52:67], v[164:167], v[160:163], v[52:67]
	global_load_dwordx4 v[136:139], v[180:181], off offset:896
	s_waitcnt lgkmcnt(4)
	v_mfma_f32_32x32x16_bf16 v[36:51], v[168:171], v[160:163], v[36:51]
	global_load_dwordx4 v[140:143], v[182:183], off offset:896
	s_waitcnt lgkmcnt(3)
	v_mfma_f32_32x32x16_bf16 v[20:35], v[164:167], v[172:175], v[20:35]
	v_mfma_f32_32x32x16_bf16 v[4:19], v[168:171], v[172:175], v[4:19]
	s_setprio 0
	s_waitcnt lgkmcnt(0)
	s_barrier
	ds_read_b128 v[144:147], v186 offset:36864
	ds_read_b128 v[148:151], v187 offset:55296
	ds_read_b128 v[152:155], v187 offset:59904
	ds_read_b128 v[156:159], v186 offset:41472
	ds_read_b128 v[160:163], v186 offset:36896
	ds_read_b128 v[164:167], v187 offset:55328
	ds_read_b128 v[168:171], v187 offset:59936
	ds_read_b128 v[172:175], v186 offset:41504
	s_setprio 1
	s_waitcnt lgkmcnt(6)
	v_mfma_f32_32x32x16_bf16 v[52:67], v[148:151], v[144:147], v[52:67]
	s_waitcnt vmcnt(15)
	ds_write_b128 v184, v[68:71]
	s_waitcnt lgkmcnt(6)
	v_mfma_f32_32x32x16_bf16 v[36:51], v[152:155], v[144:147], v[36:51]
	s_waitcnt vmcnt(14)
	ds_write_b128 v184, v[76:79] offset:4608
	s_waitcnt lgkmcnt(6)
	v_mfma_f32_32x32x16_bf16 v[20:35], v[148:151], v[156:159], v[20:35]
	s_waitcnt vmcnt(13)
	ds_write_b128 v184, v[80:83] offset:9216
	global_load_dwordx4 v[68:71], v[72:73], off offset:1024
	v_mfma_f32_32x32x16_bf16 v[4:19], v[152:155], v[156:159], v[4:19]
	ds_read_b128 v[144:147], v186 offset:36928
	ds_read_b128 v[148:151], v187 offset:55360
	s_waitcnt lgkmcnt(7)
	v_mfma_f32_32x32x16_bf16 v[52:67], v[164:167], v[160:163], v[52:67]
	ds_read_b128 v[152:155], v187 offset:59968
	ds_read_b128 v[156:159], v186 offset:41536
	s_waitcnt lgkmcnt(8)
	v_mfma_f32_32x32x16_bf16 v[36:51], v[168:171], v[160:163], v[36:51]
	s_waitcnt vmcnt(13)
	ds_write_b128 v184, v[84:87] offset:13824
	global_load_dwordx4 v[76:79], v[74:75], off offset:1024
	s_waitcnt lgkmcnt(8)
	v_mfma_f32_32x32x16_bf16 v[20:35], v[164:167], v[172:175], v[20:35]
	s_waitcnt vmcnt(13)
	ds_write_b128 v184, v[88:91] offset:18432
	global_load_dwordx4 v[80:83], v[106:107], off offset:1024
	v_mfma_f32_32x32x16_bf16 v[4:19], v[168:171], v[172:175], v[4:19]
	ds_read_b128 v[160:163], v186 offset:36960
	ds_read_b128 v[164:167], v187 offset:55392
	s_waitcnt lgkmcnt(6)
	v_mfma_f32_32x32x16_bf16 v[52:67], v[148:151], v[144:147], v[52:67]
	ds_read_b128 v[168:171], v187 offset:60000
	ds_read_b128 v[172:175], v186 offset:41568
	s_waitcnt lgkmcnt(7)
	v_mfma_f32_32x32x16_bf16 v[36:51], v[152:155], v[144:147], v[36:51]
	s_waitcnt vmcnt(13)
	ds_write_b128 v184, v[92:95] offset:23040
	global_load_dwordx4 v[84:87], v[176:177], off offset:1024
	s_waitcnt lgkmcnt(7)
	v_mfma_f32_32x32x16_bf16 v[20:35], v[148:151], v[156:159], v[20:35]
	s_waitcnt vmcnt(13)
	ds_write_b128 v184, v[96:99] offset:27648
	global_load_dwordx4 v[88:91], v[104:105], off offset:1024
	v_mfma_f32_32x32x16_bf16 v[4:19], v[152:155], v[156:159], v[4:19]
	s_waitcnt vmcnt(13)
	ds_write_b128 v184, v[100:103] offset:32256
	global_load_dwordx4 v[92:95], v[178:179], off offset:1024
	s_waitcnt lgkmcnt(5)
	v_mfma_f32_32x32x16_bf16 v[52:67], v[164:167], v[160:163], v[52:67]
	global_load_dwordx4 v[96:99], v[180:181], off offset:1024
	s_waitcnt lgkmcnt(4)
	v_mfma_f32_32x32x16_bf16 v[36:51], v[168:171], v[160:163], v[36:51]
	global_load_dwordx4 v[100:103], v[182:183], off offset:1024
	s_waitcnt lgkmcnt(3)
	v_mfma_f32_32x32x16_bf16 v[20:35], v[164:167], v[172:175], v[20:35]
	v_mfma_f32_32x32x16_bf16 v[4:19], v[168:171], v[172:175], v[4:19]
	s_setprio 0
	s_waitcnt lgkmcnt(0)
	s_barrier
	ds_read_b128 v[144:147], v186
	ds_read_b128 v[148:151], v187 offset:18432
	ds_read_b128 v[152:155], v187 offset:23040
	ds_read_b128 v[156:159], v186 offset:4608
	ds_read_b128 v[160:163], v186 offset:32
	ds_read_b128 v[164:167], v187 offset:18464
	ds_read_b128 v[168:171], v187 offset:23072
	ds_read_b128 v[172:175], v186 offset:4640
	s_setprio 1
	s_waitcnt lgkmcnt(6)
	v_mfma_f32_32x32x16_bf16 v[52:67], v[148:151], v[144:147], v[52:67]
	s_waitcnt vmcnt(15)
	ds_write_b128 v185, v[108:111]
	s_waitcnt lgkmcnt(6)
	v_mfma_f32_32x32x16_bf16 v[36:51], v[152:155], v[144:147], v[36:51]
	s_waitcnt vmcnt(14)
	ds_write_b128 v185, v[112:115] offset:4608
	s_waitcnt lgkmcnt(6)
	v_mfma_f32_32x32x16_bf16 v[20:35], v[148:151], v[156:159], v[20:35]
	s_waitcnt vmcnt(13)
	ds_write_b128 v185, v[116:119] offset:9216
	global_load_dwordx4 v[108:111], v[72:73], off offset:1152
	v_mfma_f32_32x32x16_bf16 v[4:19], v[152:155], v[156:159], v[4:19]
	ds_read_b128 v[144:147], v186 offset:64
	ds_read_b128 v[148:151], v187 offset:18496
	s_waitcnt lgkmcnt(7)
	v_mfma_f32_32x32x16_bf16 v[52:67], v[164:167], v[160:163], v[52:67]
	ds_read_b128 v[152:155], v187 offset:23104
	ds_read_b128 v[156:159], v186 offset:4672
	s_waitcnt lgkmcnt(8)
	v_mfma_f32_32x32x16_bf16 v[36:51], v[168:171], v[160:163], v[36:51]
	s_waitcnt vmcnt(13)
	ds_write_b128 v185, v[120:123] offset:13824
	global_load_dwordx4 v[112:115], v[74:75], off offset:1152
	s_waitcnt lgkmcnt(8)
	v_mfma_f32_32x32x16_bf16 v[20:35], v[164:167], v[172:175], v[20:35]
	s_waitcnt vmcnt(13)
	ds_write_b128 v185, v[124:127] offset:18432
	global_load_dwordx4 v[116:119], v[106:107], off offset:1152
	v_mfma_f32_32x32x16_bf16 v[4:19], v[168:171], v[172:175], v[4:19]
	ds_read_b128 v[160:163], v186 offset:96
	ds_read_b128 v[164:167], v187 offset:18528
	s_waitcnt lgkmcnt(6)
	v_mfma_f32_32x32x16_bf16 v[52:67], v[148:151], v[144:147], v[52:67]
	ds_read_b128 v[168:171], v187 offset:23136
	ds_read_b128 v[172:175], v186 offset:4704
	s_waitcnt lgkmcnt(7)
	v_mfma_f32_32x32x16_bf16 v[36:51], v[152:155], v[144:147], v[36:51]
	s_waitcnt vmcnt(13)
	ds_write_b128 v185, v[128:131] offset:23040
	global_load_dwordx4 v[120:123], v[176:177], off offset:1152
	s_waitcnt lgkmcnt(7)
	v_mfma_f32_32x32x16_bf16 v[20:35], v[148:151], v[156:159], v[20:35]
	s_waitcnt vmcnt(13)
	ds_write_b128 v185, v[136:139] offset:27648
	global_load_dwordx4 v[124:127], v[104:105], off offset:1152
	v_mfma_f32_32x32x16_bf16 v[4:19], v[152:155], v[156:159], v[4:19]
	s_waitcnt vmcnt(13)
	ds_write_b128 v185, v[140:143] offset:32256
	global_load_dwordx4 v[128:131], v[178:179], off offset:1152
	s_waitcnt lgkmcnt(5)
	v_mfma_f32_32x32x16_bf16 v[52:67], v[164:167], v[160:163], v[52:67]
	global_load_dwordx4 v[136:139], v[180:181], off offset:1152
	s_waitcnt lgkmcnt(4)
	v_mfma_f32_32x32x16_bf16 v[36:51], v[168:171], v[160:163], v[36:51]
	global_load_dwordx4 v[140:143], v[182:183], off offset:1152
	s_waitcnt lgkmcnt(3)
	v_mfma_f32_32x32x16_bf16 v[20:35], v[164:167], v[172:175], v[20:35]
	v_mfma_f32_32x32x16_bf16 v[4:19], v[168:171], v[172:175], v[4:19]
	s_setprio 0
	s_waitcnt lgkmcnt(0)
	s_barrier
	ds_read_b128 v[144:147], v186 offset:36864
	ds_read_b128 v[148:151], v187 offset:55296
	ds_read_b128 v[152:155], v187 offset:59904
	ds_read_b128 v[156:159], v186 offset:41472
	ds_read_b128 v[160:163], v186 offset:36896
	ds_read_b128 v[164:167], v187 offset:55328
	ds_read_b128 v[168:171], v187 offset:59936
	ds_read_b128 v[172:175], v186 offset:41504
	s_setprio 1
	s_waitcnt lgkmcnt(6)
	v_mfma_f32_32x32x16_bf16 v[52:67], v[148:151], v[144:147], v[52:67]
	s_waitcnt vmcnt(15)
	ds_write_b128 v184, v[68:71]
	s_waitcnt lgkmcnt(6)
	v_mfma_f32_32x32x16_bf16 v[36:51], v[152:155], v[144:147], v[36:51]
	s_waitcnt vmcnt(14)
	ds_write_b128 v184, v[76:79] offset:4608
	s_waitcnt lgkmcnt(6)
	v_mfma_f32_32x32x16_bf16 v[20:35], v[148:151], v[156:159], v[20:35]
	s_waitcnt vmcnt(13)
	ds_write_b128 v184, v[80:83] offset:9216
	global_load_dwordx4 v[68:71], v[72:73], off offset:1280
	v_mfma_f32_32x32x16_bf16 v[4:19], v[152:155], v[156:159], v[4:19]
	ds_read_b128 v[144:147], v186 offset:36928
	ds_read_b128 v[148:151], v187 offset:55360
	s_waitcnt lgkmcnt(7)
	v_mfma_f32_32x32x16_bf16 v[52:67], v[164:167], v[160:163], v[52:67]
	ds_read_b128 v[152:155], v187 offset:59968
	ds_read_b128 v[156:159], v186 offset:41536
	s_waitcnt lgkmcnt(8)
	v_mfma_f32_32x32x16_bf16 v[36:51], v[168:171], v[160:163], v[36:51]
	s_waitcnt vmcnt(13)
	ds_write_b128 v184, v[84:87] offset:13824
	global_load_dwordx4 v[76:79], v[74:75], off offset:1280
	s_waitcnt lgkmcnt(8)
	v_mfma_f32_32x32x16_bf16 v[20:35], v[164:167], v[172:175], v[20:35]
	s_waitcnt vmcnt(13)
	ds_write_b128 v184, v[88:91] offset:18432
	global_load_dwordx4 v[80:83], v[106:107], off offset:1280
	v_mfma_f32_32x32x16_bf16 v[4:19], v[168:171], v[172:175], v[4:19]
	ds_read_b128 v[160:163], v186 offset:36960
	ds_read_b128 v[164:167], v187 offset:55392
	s_waitcnt lgkmcnt(6)
	v_mfma_f32_32x32x16_bf16 v[52:67], v[148:151], v[144:147], v[52:67]
	ds_read_b128 v[168:171], v187 offset:60000
	ds_read_b128 v[172:175], v186 offset:41568
	s_waitcnt lgkmcnt(7)
	v_mfma_f32_32x32x16_bf16 v[36:51], v[152:155], v[144:147], v[36:51]
	s_waitcnt vmcnt(13)
	ds_write_b128 v184, v[92:95] offset:23040
	global_load_dwordx4 v[84:87], v[176:177], off offset:1280
	s_waitcnt lgkmcnt(7)
	v_mfma_f32_32x32x16_bf16 v[20:35], v[148:151], v[156:159], v[20:35]
	s_waitcnt vmcnt(13)
	ds_write_b128 v184, v[96:99] offset:27648
	global_load_dwordx4 v[88:91], v[104:105], off offset:1280
	v_mfma_f32_32x32x16_bf16 v[4:19], v[152:155], v[156:159], v[4:19]
	s_waitcnt vmcnt(13)
	ds_write_b128 v184, v[100:103] offset:32256
	global_load_dwordx4 v[92:95], v[178:179], off offset:1280
	s_waitcnt lgkmcnt(5)
	v_mfma_f32_32x32x16_bf16 v[52:67], v[164:167], v[160:163], v[52:67]
	global_load_dwordx4 v[96:99], v[180:181], off offset:1280
	s_waitcnt lgkmcnt(4)
	v_mfma_f32_32x32x16_bf16 v[36:51], v[168:171], v[160:163], v[36:51]
	global_load_dwordx4 v[100:103], v[182:183], off offset:1280
	s_waitcnt lgkmcnt(3)
	v_mfma_f32_32x32x16_bf16 v[20:35], v[164:167], v[172:175], v[20:35]
	v_mfma_f32_32x32x16_bf16 v[4:19], v[168:171], v[172:175], v[4:19]
	s_setprio 0
	s_waitcnt lgkmcnt(0)
	s_barrier
	ds_read_b128 v[144:147], v186
	ds_read_b128 v[148:151], v187 offset:18432
	ds_read_b128 v[152:155], v187 offset:23040
	ds_read_b128 v[156:159], v186 offset:4608
	ds_read_b128 v[160:163], v186 offset:32
	ds_read_b128 v[164:167], v187 offset:18464
	ds_read_b128 v[168:171], v187 offset:23072
	ds_read_b128 v[172:175], v186 offset:4640
	s_setprio 1
	s_waitcnt lgkmcnt(6)
	v_mfma_f32_32x32x16_bf16 v[52:67], v[148:151], v[144:147], v[52:67]
	s_waitcnt vmcnt(15)
	ds_write_b128 v185, v[108:111]
	s_waitcnt lgkmcnt(6)
	v_mfma_f32_32x32x16_bf16 v[36:51], v[152:155], v[144:147], v[36:51]
	s_waitcnt vmcnt(14)
	ds_write_b128 v185, v[112:115] offset:4608
	s_waitcnt lgkmcnt(6)
	v_mfma_f32_32x32x16_bf16 v[20:35], v[148:151], v[156:159], v[20:35]
	s_waitcnt vmcnt(13)
	ds_write_b128 v185, v[116:119] offset:9216
	global_load_dwordx4 v[108:111], v[72:73], off offset:1408
	v_mfma_f32_32x32x16_bf16 v[4:19], v[152:155], v[156:159], v[4:19]
	ds_read_b128 v[144:147], v186 offset:64
	ds_read_b128 v[148:151], v187 offset:18496
	s_waitcnt lgkmcnt(7)
	v_mfma_f32_32x32x16_bf16 v[52:67], v[164:167], v[160:163], v[52:67]
	ds_read_b128 v[152:155], v187 offset:23104
	ds_read_b128 v[156:159], v186 offset:4672
	s_waitcnt lgkmcnt(8)
	v_mfma_f32_32x32x16_bf16 v[36:51], v[168:171], v[160:163], v[36:51]
	s_waitcnt vmcnt(13)
	ds_write_b128 v185, v[120:123] offset:13824
	global_load_dwordx4 v[112:115], v[74:75], off offset:1408
	s_waitcnt lgkmcnt(8)
	v_mfma_f32_32x32x16_bf16 v[20:35], v[164:167], v[172:175], v[20:35]
	s_waitcnt vmcnt(13)
	ds_write_b128 v185, v[124:127] offset:18432
	global_load_dwordx4 v[116:119], v[106:107], off offset:1408
	v_mfma_f32_32x32x16_bf16 v[4:19], v[168:171], v[172:175], v[4:19]
	ds_read_b128 v[160:163], v186 offset:96
	ds_read_b128 v[164:167], v187 offset:18528
	s_waitcnt lgkmcnt(6)
	v_mfma_f32_32x32x16_bf16 v[52:67], v[148:151], v[144:147], v[52:67]
	ds_read_b128 v[168:171], v187 offset:23136
	ds_read_b128 v[172:175], v186 offset:4704
	s_waitcnt lgkmcnt(7)
	v_mfma_f32_32x32x16_bf16 v[36:51], v[152:155], v[144:147], v[36:51]
	s_waitcnt vmcnt(13)
	ds_write_b128 v185, v[128:131] offset:23040
	global_load_dwordx4 v[120:123], v[176:177], off offset:1408
	s_waitcnt lgkmcnt(7)
	v_mfma_f32_32x32x16_bf16 v[20:35], v[148:151], v[156:159], v[20:35]
	s_waitcnt vmcnt(13)
	ds_write_b128 v185, v[136:139] offset:27648
	global_load_dwordx4 v[124:127], v[104:105], off offset:1408
	v_mfma_f32_32x32x16_bf16 v[4:19], v[152:155], v[156:159], v[4:19]
	s_waitcnt vmcnt(13)
	ds_write_b128 v185, v[140:143] offset:32256
	global_load_dwordx4 v[128:131], v[178:179], off offset:1408
	s_waitcnt lgkmcnt(5)
	v_mfma_f32_32x32x16_bf16 v[52:67], v[164:167], v[160:163], v[52:67]
	global_load_dwordx4 v[136:139], v[180:181], off offset:1408
	s_waitcnt lgkmcnt(4)
	v_mfma_f32_32x32x16_bf16 v[36:51], v[168:171], v[160:163], v[36:51]
	global_load_dwordx4 v[140:143], v[182:183], off offset:1408
	s_waitcnt lgkmcnt(3)
	v_mfma_f32_32x32x16_bf16 v[20:35], v[164:167], v[172:175], v[20:35]
	v_mfma_f32_32x32x16_bf16 v[4:19], v[168:171], v[172:175], v[4:19]
	s_setprio 0
	s_waitcnt lgkmcnt(0)
	s_barrier
	ds_read_b128 v[144:147], v186 offset:36864
	ds_read_b128 v[148:151], v187 offset:55296
	ds_read_b128 v[152:155], v187 offset:59904
	ds_read_b128 v[156:159], v186 offset:41472
	ds_read_b128 v[160:163], v186 offset:36896
	ds_read_b128 v[164:167], v187 offset:55328
	ds_read_b128 v[168:171], v187 offset:59936
	ds_read_b128 v[172:175], v186 offset:41504
	s_setprio 1
	s_waitcnt lgkmcnt(6)
	v_mfma_f32_32x32x16_bf16 v[52:67], v[148:151], v[144:147], v[52:67]
	s_waitcnt vmcnt(15)
	ds_write_b128 v184, v[68:71]
	s_waitcnt lgkmcnt(6)
	v_mfma_f32_32x32x16_bf16 v[36:51], v[152:155], v[144:147], v[36:51]
	s_waitcnt vmcnt(14)
	ds_write_b128 v184, v[76:79] offset:4608
	s_waitcnt lgkmcnt(6)
	v_mfma_f32_32x32x16_bf16 v[20:35], v[148:151], v[156:159], v[20:35]
	s_waitcnt vmcnt(13)
	ds_write_b128 v184, v[80:83] offset:9216
	global_load_dwordx4 v[68:71], v[72:73], off offset:1536
	v_mfma_f32_32x32x16_bf16 v[4:19], v[152:155], v[156:159], v[4:19]
	ds_read_b128 v[144:147], v186 offset:36928
	ds_read_b128 v[148:151], v187 offset:55360
	s_waitcnt lgkmcnt(7)
	v_mfma_f32_32x32x16_bf16 v[52:67], v[164:167], v[160:163], v[52:67]
	ds_read_b128 v[152:155], v187 offset:59968
	ds_read_b128 v[156:159], v186 offset:41536
	s_waitcnt lgkmcnt(8)
	v_mfma_f32_32x32x16_bf16 v[36:51], v[168:171], v[160:163], v[36:51]
	s_waitcnt vmcnt(13)
	ds_write_b128 v184, v[84:87] offset:13824
	global_load_dwordx4 v[76:79], v[74:75], off offset:1536
	s_waitcnt lgkmcnt(8)
	v_mfma_f32_32x32x16_bf16 v[20:35], v[164:167], v[172:175], v[20:35]
	s_waitcnt vmcnt(13)
	ds_write_b128 v184, v[88:91] offset:18432
	global_load_dwordx4 v[80:83], v[106:107], off offset:1536
	v_mfma_f32_32x32x16_bf16 v[4:19], v[168:171], v[172:175], v[4:19]
	ds_read_b128 v[160:163], v186 offset:36960
	ds_read_b128 v[164:167], v187 offset:55392
	s_waitcnt lgkmcnt(6)
	v_mfma_f32_32x32x16_bf16 v[52:67], v[148:151], v[144:147], v[52:67]
	ds_read_b128 v[168:171], v187 offset:60000
	ds_read_b128 v[172:175], v186 offset:41568
	s_waitcnt lgkmcnt(7)
	v_mfma_f32_32x32x16_bf16 v[36:51], v[152:155], v[144:147], v[36:51]
	s_waitcnt vmcnt(13)
	ds_write_b128 v184, v[92:95] offset:23040
	global_load_dwordx4 v[84:87], v[176:177], off offset:1536
	s_waitcnt lgkmcnt(7)
	v_mfma_f32_32x32x16_bf16 v[20:35], v[148:151], v[156:159], v[20:35]
	s_waitcnt vmcnt(13)
	ds_write_b128 v184, v[96:99] offset:27648
	global_load_dwordx4 v[88:91], v[104:105], off offset:1536
	v_mfma_f32_32x32x16_bf16 v[4:19], v[152:155], v[156:159], v[4:19]
	s_waitcnt vmcnt(13)
	ds_write_b128 v184, v[100:103] offset:32256
	global_load_dwordx4 v[92:95], v[178:179], off offset:1536
	s_waitcnt lgkmcnt(5)
	v_mfma_f32_32x32x16_bf16 v[52:67], v[164:167], v[160:163], v[52:67]
	global_load_dwordx4 v[96:99], v[180:181], off offset:1536
	s_waitcnt lgkmcnt(4)
	v_mfma_f32_32x32x16_bf16 v[36:51], v[168:171], v[160:163], v[36:51]
	global_load_dwordx4 v[100:103], v[182:183], off offset:1536
	s_waitcnt lgkmcnt(3)
	v_mfma_f32_32x32x16_bf16 v[20:35], v[164:167], v[172:175], v[20:35]
	v_mfma_f32_32x32x16_bf16 v[4:19], v[168:171], v[172:175], v[4:19]
	s_setprio 0
	s_waitcnt lgkmcnt(0)
	s_barrier
	ds_read_b128 v[144:147], v186
	ds_read_b128 v[148:151], v187 offset:18432
	ds_read_b128 v[152:155], v187 offset:23040
	ds_read_b128 v[156:159], v186 offset:4608
	ds_read_b128 v[160:163], v186 offset:32
	ds_read_b128 v[164:167], v187 offset:18464
	ds_read_b128 v[168:171], v187 offset:23072
	ds_read_b128 v[172:175], v186 offset:4640
	s_setprio 1
	s_waitcnt lgkmcnt(6)
	v_mfma_f32_32x32x16_bf16 v[52:67], v[148:151], v[144:147], v[52:67]
	s_waitcnt vmcnt(15)
	ds_write_b128 v185, v[108:111]
	s_waitcnt lgkmcnt(6)
	v_mfma_f32_32x32x16_bf16 v[36:51], v[152:155], v[144:147], v[36:51]
	s_waitcnt vmcnt(14)
	ds_write_b128 v185, v[112:115] offset:4608
	s_waitcnt lgkmcnt(6)
	v_mfma_f32_32x32x16_bf16 v[20:35], v[148:151], v[156:159], v[20:35]
	s_waitcnt vmcnt(13)
	ds_write_b128 v185, v[116:119] offset:9216
	global_load_dwordx4 v[108:111], v[72:73], off offset:1664
	v_mfma_f32_32x32x16_bf16 v[4:19], v[152:155], v[156:159], v[4:19]
	ds_read_b128 v[144:147], v186 offset:64
	ds_read_b128 v[148:151], v187 offset:18496
	s_waitcnt lgkmcnt(7)
	v_mfma_f32_32x32x16_bf16 v[52:67], v[164:167], v[160:163], v[52:67]
	ds_read_b128 v[152:155], v187 offset:23104
	ds_read_b128 v[156:159], v186 offset:4672
	s_waitcnt lgkmcnt(8)
	v_mfma_f32_32x32x16_bf16 v[36:51], v[168:171], v[160:163], v[36:51]
	s_waitcnt vmcnt(13)
	ds_write_b128 v185, v[120:123] offset:13824
	global_load_dwordx4 v[112:115], v[74:75], off offset:1664
	s_waitcnt lgkmcnt(8)
	v_mfma_f32_32x32x16_bf16 v[20:35], v[164:167], v[172:175], v[20:35]
	s_waitcnt vmcnt(13)
	ds_write_b128 v185, v[124:127] offset:18432
	global_load_dwordx4 v[116:119], v[106:107], off offset:1664
	v_mfma_f32_32x32x16_bf16 v[4:19], v[168:171], v[172:175], v[4:19]
	ds_read_b128 v[160:163], v186 offset:96
	ds_read_b128 v[164:167], v187 offset:18528
	s_waitcnt lgkmcnt(6)
	v_mfma_f32_32x32x16_bf16 v[52:67], v[148:151], v[144:147], v[52:67]
	ds_read_b128 v[168:171], v187 offset:23136
	ds_read_b128 v[172:175], v186 offset:4704
	s_waitcnt lgkmcnt(7)
	v_mfma_f32_32x32x16_bf16 v[36:51], v[152:155], v[144:147], v[36:51]
	s_waitcnt vmcnt(13)
	ds_write_b128 v185, v[128:131] offset:23040
	global_load_dwordx4 v[120:123], v[176:177], off offset:1664
	s_waitcnt lgkmcnt(7)
	v_mfma_f32_32x32x16_bf16 v[20:35], v[148:151], v[156:159], v[20:35]
	s_waitcnt vmcnt(13)
	ds_write_b128 v185, v[136:139] offset:27648
	global_load_dwordx4 v[124:127], v[104:105], off offset:1664
	v_mfma_f32_32x32x16_bf16 v[4:19], v[152:155], v[156:159], v[4:19]
	s_waitcnt vmcnt(13)
	ds_write_b128 v185, v[140:143] offset:32256
	global_load_dwordx4 v[128:131], v[178:179], off offset:1664
	s_waitcnt lgkmcnt(5)
	v_mfma_f32_32x32x16_bf16 v[52:67], v[164:167], v[160:163], v[52:67]
	global_load_dwordx4 v[136:139], v[180:181], off offset:1664
	s_waitcnt lgkmcnt(4)
	v_mfma_f32_32x32x16_bf16 v[36:51], v[168:171], v[160:163], v[36:51]
	global_load_dwordx4 v[140:143], v[182:183], off offset:1664
	s_waitcnt lgkmcnt(3)
	v_mfma_f32_32x32x16_bf16 v[20:35], v[164:167], v[172:175], v[20:35]
	v_mfma_f32_32x32x16_bf16 v[4:19], v[168:171], v[172:175], v[4:19]
	s_setprio 0
	s_waitcnt lgkmcnt(0)
	s_barrier
	ds_read_b128 v[144:147], v186 offset:36864
	ds_read_b128 v[148:151], v187 offset:55296
	ds_read_b128 v[152:155], v187 offset:59904
	ds_read_b128 v[156:159], v186 offset:41472
	ds_read_b128 v[160:163], v186 offset:36896
	ds_read_b128 v[164:167], v187 offset:55328
	ds_read_b128 v[168:171], v187 offset:59936
	ds_read_b128 v[172:175], v186 offset:41504
	s_setprio 1
	s_waitcnt lgkmcnt(6)
	v_mfma_f32_32x32x16_bf16 v[52:67], v[148:151], v[144:147], v[52:67]
	s_waitcnt vmcnt(15)
	ds_write_b128 v184, v[68:71]
	s_waitcnt lgkmcnt(6)
	v_mfma_f32_32x32x16_bf16 v[36:51], v[152:155], v[144:147], v[36:51]
	s_waitcnt vmcnt(14)
	ds_write_b128 v184, v[76:79] offset:4608
	s_waitcnt lgkmcnt(6)
	v_mfma_f32_32x32x16_bf16 v[20:35], v[148:151], v[156:159], v[20:35]
	s_waitcnt vmcnt(13)
	ds_write_b128 v184, v[80:83] offset:9216
	global_load_dwordx4 v[68:71], v[72:73], off offset:1792
	v_mfma_f32_32x32x16_bf16 v[4:19], v[152:155], v[156:159], v[4:19]
	ds_read_b128 v[144:147], v186 offset:36928
	ds_read_b128 v[148:151], v187 offset:55360
	s_waitcnt lgkmcnt(7)
	v_mfma_f32_32x32x16_bf16 v[52:67], v[164:167], v[160:163], v[52:67]
	ds_read_b128 v[152:155], v187 offset:59968
	ds_read_b128 v[156:159], v186 offset:41536
	s_waitcnt lgkmcnt(8)
	v_mfma_f32_32x32x16_bf16 v[36:51], v[168:171], v[160:163], v[36:51]
	s_waitcnt vmcnt(13)
	ds_write_b128 v184, v[84:87] offset:13824
	global_load_dwordx4 v[76:79], v[74:75], off offset:1792
	s_waitcnt lgkmcnt(8)
	v_mfma_f32_32x32x16_bf16 v[20:35], v[164:167], v[172:175], v[20:35]
	s_waitcnt vmcnt(13)
	ds_write_b128 v184, v[88:91] offset:18432
	global_load_dwordx4 v[80:83], v[106:107], off offset:1792
	v_mfma_f32_32x32x16_bf16 v[4:19], v[168:171], v[172:175], v[4:19]
	ds_read_b128 v[160:163], v186 offset:36960
	ds_read_b128 v[164:167], v187 offset:55392
	s_waitcnt lgkmcnt(6)
	v_mfma_f32_32x32x16_bf16 v[52:67], v[148:151], v[144:147], v[52:67]
	ds_read_b128 v[168:171], v187 offset:60000
	ds_read_b128 v[172:175], v186 offset:41568
	s_waitcnt lgkmcnt(7)
	v_mfma_f32_32x32x16_bf16 v[36:51], v[152:155], v[144:147], v[36:51]
	s_waitcnt vmcnt(13)
	ds_write_b128 v184, v[92:95] offset:23040
	global_load_dwordx4 v[84:87], v[176:177], off offset:1792
	s_waitcnt lgkmcnt(7)
	v_mfma_f32_32x32x16_bf16 v[20:35], v[148:151], v[156:159], v[20:35]
	s_waitcnt vmcnt(13)
	ds_write_b128 v184, v[96:99] offset:27648
	global_load_dwordx4 v[88:91], v[104:105], off offset:1792
	v_mfma_f32_32x32x16_bf16 v[4:19], v[152:155], v[156:159], v[4:19]
	s_waitcnt vmcnt(13)
	ds_write_b128 v184, v[100:103] offset:32256
	global_load_dwordx4 v[92:95], v[178:179], off offset:1792
	s_waitcnt lgkmcnt(5)
	v_mfma_f32_32x32x16_bf16 v[52:67], v[164:167], v[160:163], v[52:67]
	global_load_dwordx4 v[96:99], v[180:181], off offset:1792
	s_waitcnt lgkmcnt(4)
	v_mfma_f32_32x32x16_bf16 v[36:51], v[168:171], v[160:163], v[36:51]
	global_load_dwordx4 v[100:103], v[182:183], off offset:1792
	s_waitcnt lgkmcnt(3)
	v_mfma_f32_32x32x16_bf16 v[20:35], v[164:167], v[172:175], v[20:35]
	v_mfma_f32_32x32x16_bf16 v[4:19], v[168:171], v[172:175], v[4:19]
	s_setprio 0
	s_waitcnt lgkmcnt(0)
	s_barrier
	ds_read_b128 v[144:147], v186
	ds_read_b128 v[148:151], v187 offset:18432
	ds_read_b128 v[152:155], v187 offset:23040
	ds_read_b128 v[156:159], v186 offset:4608
	ds_read_b128 v[160:163], v186 offset:32
	ds_read_b128 v[164:167], v187 offset:18464
	ds_read_b128 v[168:171], v187 offset:23072
	ds_read_b128 v[172:175], v186 offset:4640
	s_setprio 1
	s_waitcnt lgkmcnt(6)
	v_mfma_f32_32x32x16_bf16 v[52:67], v[148:151], v[144:147], v[52:67]
	s_waitcnt vmcnt(15)
	ds_write_b128 v185, v[108:111]
	s_waitcnt lgkmcnt(6)
	v_mfma_f32_32x32x16_bf16 v[36:51], v[152:155], v[144:147], v[36:51]
	s_waitcnt vmcnt(14)
	ds_write_b128 v185, v[112:115] offset:4608
	s_waitcnt lgkmcnt(6)
	v_mfma_f32_32x32x16_bf16 v[20:35], v[148:151], v[156:159], v[20:35]
	s_waitcnt vmcnt(13)
	ds_write_b128 v185, v[116:119] offset:9216
	global_load_dwordx4 v[108:111], v[72:73], off offset:1920
	v_mfma_f32_32x32x16_bf16 v[4:19], v[152:155], v[156:159], v[4:19]
	ds_read_b128 v[144:147], v186 offset:64
	ds_read_b128 v[148:151], v187 offset:18496
	s_waitcnt lgkmcnt(7)
	v_mfma_f32_32x32x16_bf16 v[52:67], v[164:167], v[160:163], v[52:67]
	ds_read_b128 v[152:155], v187 offset:23104
	ds_read_b128 v[156:159], v186 offset:4672
	s_waitcnt lgkmcnt(8)
	v_mfma_f32_32x32x16_bf16 v[36:51], v[168:171], v[160:163], v[36:51]
	s_waitcnt vmcnt(13)
	ds_write_b128 v185, v[120:123] offset:13824
	global_load_dwordx4 v[112:115], v[74:75], off offset:1920
	s_waitcnt lgkmcnt(8)
	v_mfma_f32_32x32x16_bf16 v[20:35], v[164:167], v[172:175], v[20:35]
	s_waitcnt vmcnt(13)
	ds_write_b128 v185, v[124:127] offset:18432
	global_load_dwordx4 v[116:119], v[106:107], off offset:1920
	v_mfma_f32_32x32x16_bf16 v[4:19], v[168:171], v[172:175], v[4:19]
	ds_read_b128 v[160:163], v186 offset:96
	ds_read_b128 v[164:167], v187 offset:18528
	s_waitcnt lgkmcnt(6)
	v_mfma_f32_32x32x16_bf16 v[52:67], v[148:151], v[144:147], v[52:67]
	ds_read_b128 v[168:171], v187 offset:23136
	ds_read_b128 v[172:175], v186 offset:4704
	s_waitcnt lgkmcnt(7)
	v_mfma_f32_32x32x16_bf16 v[36:51], v[152:155], v[144:147], v[36:51]
	s_waitcnt vmcnt(13)
	ds_write_b128 v185, v[128:131] offset:23040
	global_load_dwordx4 v[120:123], v[176:177], off offset:1920
	s_waitcnt lgkmcnt(7)
	v_mfma_f32_32x32x16_bf16 v[20:35], v[148:151], v[156:159], v[20:35]
	s_waitcnt vmcnt(13)
	ds_write_b128 v185, v[136:139] offset:27648
	global_load_dwordx4 v[124:127], v[104:105], off offset:1920
	v_mfma_f32_32x32x16_bf16 v[4:19], v[152:155], v[156:159], v[4:19]
	s_waitcnt vmcnt(13)
	ds_write_b128 v185, v[140:143] offset:32256
	global_load_dwordx4 v[128:131], v[178:179], off offset:1920
	s_waitcnt lgkmcnt(5)
	v_mfma_f32_32x32x16_bf16 v[52:67], v[164:167], v[160:163], v[52:67]
	global_load_dwordx4 v[136:139], v[180:181], off offset:1920
	s_waitcnt lgkmcnt(4)
	v_mfma_f32_32x32x16_bf16 v[36:51], v[168:171], v[160:163], v[36:51]
	global_load_dwordx4 v[140:143], v[182:183], off offset:1920
	s_waitcnt lgkmcnt(3)
	v_mfma_f32_32x32x16_bf16 v[20:35], v[164:167], v[172:175], v[20:35]
	v_mfma_f32_32x32x16_bf16 v[4:19], v[168:171], v[172:175], v[4:19]
	s_setprio 0
	s_waitcnt lgkmcnt(0)
	s_barrier
	ds_read_b128 v[144:147], v186 offset:36864
	ds_read_b128 v[148:151], v187 offset:55296
	ds_read_b128 v[152:155], v187 offset:59904
	ds_read_b128 v[156:159], v186 offset:41472
	ds_read_b128 v[160:163], v186 offset:36896
	ds_read_b128 v[164:167], v187 offset:55328
	ds_read_b128 v[168:171], v187 offset:59936
	ds_read_b128 v[172:175], v186 offset:41504
	s_setprio 1
	s_waitcnt lgkmcnt(6)
	v_mfma_f32_32x32x16_bf16 v[52:67], v[148:151], v[144:147], v[52:67]
	s_waitcnt vmcnt(15)
	ds_write_b128 v184, v[68:71]
	s_waitcnt lgkmcnt(6)
	v_mfma_f32_32x32x16_bf16 v[36:51], v[152:155], v[144:147], v[36:51]
	s_waitcnt vmcnt(14)
	ds_write_b128 v184, v[76:79] offset:4608
	s_waitcnt lgkmcnt(6)
	v_mfma_f32_32x32x16_bf16 v[20:35], v[148:151], v[156:159], v[20:35]
	s_waitcnt vmcnt(13)
	ds_write_b128 v184, v[80:83] offset:9216
	global_load_dwordx4 v[68:71], v[72:73], off offset:2048
	v_mfma_f32_32x32x16_bf16 v[4:19], v[152:155], v[156:159], v[4:19]
	ds_read_b128 v[144:147], v186 offset:36928
	ds_read_b128 v[148:151], v187 offset:55360
	s_waitcnt lgkmcnt(7)
	v_mfma_f32_32x32x16_bf16 v[52:67], v[164:167], v[160:163], v[52:67]
	ds_read_b128 v[152:155], v187 offset:59968
	ds_read_b128 v[156:159], v186 offset:41536
	s_waitcnt lgkmcnt(8)
	v_mfma_f32_32x32x16_bf16 v[36:51], v[168:171], v[160:163], v[36:51]
	s_waitcnt vmcnt(13)
	ds_write_b128 v184, v[84:87] offset:13824
	global_load_dwordx4 v[76:79], v[74:75], off offset:2048
	s_waitcnt lgkmcnt(8)
	v_mfma_f32_32x32x16_bf16 v[20:35], v[164:167], v[172:175], v[20:35]
	s_waitcnt vmcnt(13)
	ds_write_b128 v184, v[88:91] offset:18432
	global_load_dwordx4 v[80:83], v[106:107], off offset:2048
	v_mfma_f32_32x32x16_bf16 v[4:19], v[168:171], v[172:175], v[4:19]
	ds_read_b128 v[160:163], v186 offset:36960
	ds_read_b128 v[164:167], v187 offset:55392
	s_waitcnt lgkmcnt(6)
	v_mfma_f32_32x32x16_bf16 v[52:67], v[148:151], v[144:147], v[52:67]
	ds_read_b128 v[168:171], v187 offset:60000
	ds_read_b128 v[172:175], v186 offset:41568
	s_waitcnt lgkmcnt(7)
	v_mfma_f32_32x32x16_bf16 v[36:51], v[152:155], v[144:147], v[36:51]
	s_waitcnt vmcnt(13)
	ds_write_b128 v184, v[92:95] offset:23040
	global_load_dwordx4 v[84:87], v[176:177], off offset:2048
	s_waitcnt lgkmcnt(7)
	v_mfma_f32_32x32x16_bf16 v[20:35], v[148:151], v[156:159], v[20:35]
	s_waitcnt vmcnt(13)
	ds_write_b128 v184, v[96:99] offset:27648
	global_load_dwordx4 v[88:91], v[104:105], off offset:2048
	v_mfma_f32_32x32x16_bf16 v[4:19], v[152:155], v[156:159], v[4:19]
	s_waitcnt vmcnt(13)
	ds_write_b128 v184, v[100:103] offset:32256
	global_load_dwordx4 v[92:95], v[178:179], off offset:2048
	s_waitcnt lgkmcnt(5)
	v_mfma_f32_32x32x16_bf16 v[52:67], v[164:167], v[160:163], v[52:67]
	global_load_dwordx4 v[96:99], v[180:181], off offset:2048
	s_waitcnt lgkmcnt(4)
	v_mfma_f32_32x32x16_bf16 v[36:51], v[168:171], v[160:163], v[36:51]
	global_load_dwordx4 v[100:103], v[182:183], off offset:2048
	s_waitcnt lgkmcnt(3)
	v_mfma_f32_32x32x16_bf16 v[20:35], v[164:167], v[172:175], v[20:35]
	v_mfma_f32_32x32x16_bf16 v[4:19], v[168:171], v[172:175], v[4:19]
	s_setprio 0
	s_waitcnt lgkmcnt(0)
	s_barrier
	ds_read_b128 v[144:147], v186
	ds_read_b128 v[148:151], v187 offset:18432
	ds_read_b128 v[152:155], v187 offset:23040
	ds_read_b128 v[156:159], v186 offset:4608
	ds_read_b128 v[160:163], v186 offset:32
	ds_read_b128 v[164:167], v187 offset:18464
	ds_read_b128 v[168:171], v187 offset:23072
	ds_read_b128 v[172:175], v186 offset:4640
	s_setprio 1
	s_waitcnt lgkmcnt(6)
	v_mfma_f32_32x32x16_bf16 v[52:67], v[148:151], v[144:147], v[52:67]
	s_waitcnt vmcnt(15)
	ds_write_b128 v185, v[108:111]
	s_waitcnt lgkmcnt(6)
	v_mfma_f32_32x32x16_bf16 v[36:51], v[152:155], v[144:147], v[36:51]
	s_waitcnt vmcnt(14)
	ds_write_b128 v185, v[112:115] offset:4608
	s_waitcnt lgkmcnt(6)
	v_mfma_f32_32x32x16_bf16 v[20:35], v[148:151], v[156:159], v[20:35]
	s_waitcnt vmcnt(13)
	ds_write_b128 v185, v[116:119] offset:9216
	global_load_dwordx4 v[108:111], v[72:73], off offset:2176
	v_mfma_f32_32x32x16_bf16 v[4:19], v[152:155], v[156:159], v[4:19]
	ds_read_b128 v[144:147], v186 offset:64
	ds_read_b128 v[148:151], v187 offset:18496
	s_waitcnt lgkmcnt(7)
	v_mfma_f32_32x32x16_bf16 v[52:67], v[164:167], v[160:163], v[52:67]
	ds_read_b128 v[152:155], v187 offset:23104
	ds_read_b128 v[156:159], v186 offset:4672
	s_waitcnt lgkmcnt(8)
	v_mfma_f32_32x32x16_bf16 v[36:51], v[168:171], v[160:163], v[36:51]
	s_waitcnt vmcnt(13)
	ds_write_b128 v185, v[120:123] offset:13824
	global_load_dwordx4 v[112:115], v[74:75], off offset:2176
	s_waitcnt lgkmcnt(8)
	v_mfma_f32_32x32x16_bf16 v[20:35], v[164:167], v[172:175], v[20:35]
	s_waitcnt vmcnt(13)
	ds_write_b128 v185, v[124:127] offset:18432
	global_load_dwordx4 v[116:119], v[106:107], off offset:2176
	v_mfma_f32_32x32x16_bf16 v[4:19], v[168:171], v[172:175], v[4:19]
	ds_read_b128 v[160:163], v186 offset:96
	ds_read_b128 v[164:167], v187 offset:18528
	s_waitcnt lgkmcnt(6)
	v_mfma_f32_32x32x16_bf16 v[52:67], v[148:151], v[144:147], v[52:67]
	ds_read_b128 v[168:171], v187 offset:23136
	ds_read_b128 v[172:175], v186 offset:4704
	s_waitcnt lgkmcnt(7)
	v_mfma_f32_32x32x16_bf16 v[36:51], v[152:155], v[144:147], v[36:51]
	s_waitcnt vmcnt(13)
	ds_write_b128 v185, v[128:131] offset:23040
	global_load_dwordx4 v[120:123], v[176:177], off offset:2176
	s_waitcnt lgkmcnt(7)
	v_mfma_f32_32x32x16_bf16 v[20:35], v[148:151], v[156:159], v[20:35]
	s_waitcnt vmcnt(13)
	ds_write_b128 v185, v[136:139] offset:27648
	global_load_dwordx4 v[124:127], v[104:105], off offset:2176
	v_mfma_f32_32x32x16_bf16 v[4:19], v[152:155], v[156:159], v[4:19]
	s_waitcnt vmcnt(13)
	ds_write_b128 v185, v[140:143] offset:32256
	global_load_dwordx4 v[128:131], v[178:179], off offset:2176
	s_waitcnt lgkmcnt(5)
	v_mfma_f32_32x32x16_bf16 v[52:67], v[164:167], v[160:163], v[52:67]
	global_load_dwordx4 v[136:139], v[180:181], off offset:2176
	s_waitcnt lgkmcnt(4)
	v_mfma_f32_32x32x16_bf16 v[36:51], v[168:171], v[160:163], v[36:51]
	global_load_dwordx4 v[140:143], v[182:183], off offset:2176
	s_waitcnt lgkmcnt(3)
	v_mfma_f32_32x32x16_bf16 v[20:35], v[164:167], v[172:175], v[20:35]
	v_mfma_f32_32x32x16_bf16 v[4:19], v[168:171], v[172:175], v[4:19]
	s_setprio 0
	s_waitcnt lgkmcnt(0)
	s_barrier
	ds_read_b128 v[144:147], v186 offset:36864
	ds_read_b128 v[148:151], v187 offset:55296
	ds_read_b128 v[152:155], v187 offset:59904
	ds_read_b128 v[156:159], v186 offset:41472
	ds_read_b128 v[160:163], v186 offset:36896
	ds_read_b128 v[164:167], v187 offset:55328
	ds_read_b128 v[168:171], v187 offset:59936
	ds_read_b128 v[172:175], v186 offset:41504
	s_setprio 1
	s_waitcnt lgkmcnt(6)
	v_mfma_f32_32x32x16_bf16 v[52:67], v[148:151], v[144:147], v[52:67]
	s_waitcnt vmcnt(15)
	ds_write_b128 v184, v[68:71]
	s_waitcnt lgkmcnt(6)
	v_mfma_f32_32x32x16_bf16 v[36:51], v[152:155], v[144:147], v[36:51]
	s_waitcnt vmcnt(14)
	ds_write_b128 v184, v[76:79] offset:4608
	s_waitcnt lgkmcnt(6)
	v_mfma_f32_32x32x16_bf16 v[20:35], v[148:151], v[156:159], v[20:35]
	s_waitcnt vmcnt(13)
	ds_write_b128 v184, v[80:83] offset:9216
	global_load_dwordx4 v[68:71], v[72:73], off offset:2304
	v_mfma_f32_32x32x16_bf16 v[4:19], v[152:155], v[156:159], v[4:19]
	ds_read_b128 v[144:147], v186 offset:36928
	ds_read_b128 v[148:151], v187 offset:55360
	s_waitcnt lgkmcnt(7)
	v_mfma_f32_32x32x16_bf16 v[52:67], v[164:167], v[160:163], v[52:67]
	ds_read_b128 v[152:155], v187 offset:59968
	ds_read_b128 v[156:159], v186 offset:41536
	s_waitcnt lgkmcnt(8)
	v_mfma_f32_32x32x16_bf16 v[36:51], v[168:171], v[160:163], v[36:51]
	s_waitcnt vmcnt(13)
	ds_write_b128 v184, v[84:87] offset:13824
	global_load_dwordx4 v[76:79], v[74:75], off offset:2304
	s_waitcnt lgkmcnt(8)
	v_mfma_f32_32x32x16_bf16 v[20:35], v[164:167], v[172:175], v[20:35]
	s_waitcnt vmcnt(13)
	ds_write_b128 v184, v[88:91] offset:18432
	global_load_dwordx4 v[80:83], v[106:107], off offset:2304
	v_mfma_f32_32x32x16_bf16 v[4:19], v[168:171], v[172:175], v[4:19]
	ds_read_b128 v[160:163], v186 offset:36960
	ds_read_b128 v[164:167], v187 offset:55392
	s_waitcnt lgkmcnt(6)
	v_mfma_f32_32x32x16_bf16 v[52:67], v[148:151], v[144:147], v[52:67]
	ds_read_b128 v[168:171], v187 offset:60000
	ds_read_b128 v[172:175], v186 offset:41568
	s_waitcnt lgkmcnt(7)
	v_mfma_f32_32x32x16_bf16 v[36:51], v[152:155], v[144:147], v[36:51]
	s_waitcnt vmcnt(13)
	ds_write_b128 v184, v[92:95] offset:23040
	global_load_dwordx4 v[84:87], v[176:177], off offset:2304
	s_waitcnt lgkmcnt(7)
	v_mfma_f32_32x32x16_bf16 v[20:35], v[148:151], v[156:159], v[20:35]
	s_waitcnt vmcnt(13)
	ds_write_b128 v184, v[96:99] offset:27648
	global_load_dwordx4 v[88:91], v[104:105], off offset:2304
	v_mfma_f32_32x32x16_bf16 v[4:19], v[152:155], v[156:159], v[4:19]
	s_waitcnt vmcnt(13)
	ds_write_b128 v184, v[100:103] offset:32256
	global_load_dwordx4 v[92:95], v[178:179], off offset:2304
	s_waitcnt lgkmcnt(5)
	v_mfma_f32_32x32x16_bf16 v[52:67], v[164:167], v[160:163], v[52:67]
	global_load_dwordx4 v[96:99], v[180:181], off offset:2304
	s_waitcnt lgkmcnt(4)
	v_mfma_f32_32x32x16_bf16 v[36:51], v[168:171], v[160:163], v[36:51]
	global_load_dwordx4 v[100:103], v[182:183], off offset:2304
	s_waitcnt lgkmcnt(3)
	v_mfma_f32_32x32x16_bf16 v[20:35], v[164:167], v[172:175], v[20:35]
	v_mfma_f32_32x32x16_bf16 v[4:19], v[168:171], v[172:175], v[4:19]
	s_setprio 0
	s_waitcnt lgkmcnt(0)
	s_barrier
	ds_read_b128 v[144:147], v186
	ds_read_b128 v[148:151], v187 offset:18432
	ds_read_b128 v[152:155], v187 offset:23040
	ds_read_b128 v[156:159], v186 offset:4608
	ds_read_b128 v[160:163], v186 offset:32
	ds_read_b128 v[164:167], v187 offset:18464
	ds_read_b128 v[168:171], v187 offset:23072
	ds_read_b128 v[172:175], v186 offset:4640
	s_setprio 1
	s_waitcnt lgkmcnt(6)
	v_mfma_f32_32x32x16_bf16 v[52:67], v[148:151], v[144:147], v[52:67]
	s_waitcnt vmcnt(15)
	ds_write_b128 v185, v[108:111]
	s_waitcnt lgkmcnt(6)
	v_mfma_f32_32x32x16_bf16 v[36:51], v[152:155], v[144:147], v[36:51]
	s_waitcnt vmcnt(14)
	ds_write_b128 v185, v[112:115] offset:4608
	s_waitcnt lgkmcnt(6)
	v_mfma_f32_32x32x16_bf16 v[20:35], v[148:151], v[156:159], v[20:35]
	s_waitcnt vmcnt(13)
	ds_write_b128 v185, v[116:119] offset:9216
	global_load_dwordx4 v[108:111], v[72:73], off offset:2432
	v_mfma_f32_32x32x16_bf16 v[4:19], v[152:155], v[156:159], v[4:19]
	ds_read_b128 v[144:147], v186 offset:64
	ds_read_b128 v[148:151], v187 offset:18496
	s_waitcnt lgkmcnt(7)
	v_mfma_f32_32x32x16_bf16 v[52:67], v[164:167], v[160:163], v[52:67]
	ds_read_b128 v[152:155], v187 offset:23104
	ds_read_b128 v[156:159], v186 offset:4672
	s_waitcnt lgkmcnt(8)
	v_mfma_f32_32x32x16_bf16 v[36:51], v[168:171], v[160:163], v[36:51]
	s_waitcnt vmcnt(13)
	ds_write_b128 v185, v[120:123] offset:13824
	global_load_dwordx4 v[112:115], v[74:75], off offset:2432
	s_waitcnt lgkmcnt(8)
	v_mfma_f32_32x32x16_bf16 v[20:35], v[164:167], v[172:175], v[20:35]
	s_waitcnt vmcnt(13)
	ds_write_b128 v185, v[124:127] offset:18432
	global_load_dwordx4 v[116:119], v[106:107], off offset:2432
	v_mfma_f32_32x32x16_bf16 v[4:19], v[168:171], v[172:175], v[4:19]
	ds_read_b128 v[160:163], v186 offset:96
	ds_read_b128 v[164:167], v187 offset:18528
	s_waitcnt lgkmcnt(6)
	v_mfma_f32_32x32x16_bf16 v[52:67], v[148:151], v[144:147], v[52:67]
	ds_read_b128 v[168:171], v187 offset:23136
	ds_read_b128 v[172:175], v186 offset:4704
	s_waitcnt lgkmcnt(7)
	v_mfma_f32_32x32x16_bf16 v[36:51], v[152:155], v[144:147], v[36:51]
	s_waitcnt vmcnt(13)
	ds_write_b128 v185, v[128:131] offset:23040
	global_load_dwordx4 v[120:123], v[176:177], off offset:2432
	s_waitcnt lgkmcnt(7)
	v_mfma_f32_32x32x16_bf16 v[20:35], v[148:151], v[156:159], v[20:35]
	s_waitcnt vmcnt(13)
	ds_write_b128 v185, v[136:139] offset:27648
	global_load_dwordx4 v[124:127], v[104:105], off offset:2432
	v_mfma_f32_32x32x16_bf16 v[4:19], v[152:155], v[156:159], v[4:19]
	s_waitcnt vmcnt(13)
	ds_write_b128 v185, v[140:143] offset:32256
	global_load_dwordx4 v[128:131], v[178:179], off offset:2432
	s_waitcnt lgkmcnt(5)
	v_mfma_f32_32x32x16_bf16 v[52:67], v[164:167], v[160:163], v[52:67]
	global_load_dwordx4 v[136:139], v[180:181], off offset:2432
	s_waitcnt lgkmcnt(4)
	v_mfma_f32_32x32x16_bf16 v[36:51], v[168:171], v[160:163], v[36:51]
	global_load_dwordx4 v[140:143], v[182:183], off offset:2432
	s_waitcnt lgkmcnt(3)
	v_mfma_f32_32x32x16_bf16 v[20:35], v[164:167], v[172:175], v[20:35]
	v_mfma_f32_32x32x16_bf16 v[4:19], v[168:171], v[172:175], v[4:19]
	s_setprio 0
	s_waitcnt lgkmcnt(0)
	s_barrier
	ds_read_b128 v[144:147], v186 offset:36864
	ds_read_b128 v[148:151], v187 offset:55296
	ds_read_b128 v[152:155], v187 offset:59904
	ds_read_b128 v[156:159], v186 offset:41472
	ds_read_b128 v[160:163], v186 offset:36896
	ds_read_b128 v[164:167], v187 offset:55328
	ds_read_b128 v[168:171], v187 offset:59936
	ds_read_b128 v[172:175], v186 offset:41504
	s_setprio 1
	s_waitcnt lgkmcnt(6)
	v_mfma_f32_32x32x16_bf16 v[52:67], v[148:151], v[144:147], v[52:67]
	s_waitcnt vmcnt(15)
	ds_write_b128 v184, v[68:71]
	s_waitcnt lgkmcnt(6)
	v_mfma_f32_32x32x16_bf16 v[36:51], v[152:155], v[144:147], v[36:51]
	s_waitcnt vmcnt(14)
	ds_write_b128 v184, v[76:79] offset:4608
	s_waitcnt lgkmcnt(6)
	v_mfma_f32_32x32x16_bf16 v[20:35], v[148:151], v[156:159], v[20:35]
	s_waitcnt vmcnt(13)
	ds_write_b128 v184, v[80:83] offset:9216
	global_load_dwordx4 v[68:71], v[72:73], off offset:2560
	v_mfma_f32_32x32x16_bf16 v[4:19], v[152:155], v[156:159], v[4:19]
	ds_read_b128 v[144:147], v186 offset:36928
	ds_read_b128 v[148:151], v187 offset:55360
	s_waitcnt lgkmcnt(7)
	v_mfma_f32_32x32x16_bf16 v[52:67], v[164:167], v[160:163], v[52:67]
	ds_read_b128 v[152:155], v187 offset:59968
	ds_read_b128 v[156:159], v186 offset:41536
	s_waitcnt lgkmcnt(8)
	v_mfma_f32_32x32x16_bf16 v[36:51], v[168:171], v[160:163], v[36:51]
	s_waitcnt vmcnt(13)
	ds_write_b128 v184, v[84:87] offset:13824
	global_load_dwordx4 v[76:79], v[74:75], off offset:2560
	s_waitcnt lgkmcnt(8)
	v_mfma_f32_32x32x16_bf16 v[20:35], v[164:167], v[172:175], v[20:35]
	s_waitcnt vmcnt(13)
	ds_write_b128 v184, v[88:91] offset:18432
	global_load_dwordx4 v[80:83], v[106:107], off offset:2560
	v_mfma_f32_32x32x16_bf16 v[4:19], v[168:171], v[172:175], v[4:19]
	ds_read_b128 v[160:163], v186 offset:36960
	ds_read_b128 v[164:167], v187 offset:55392
	s_waitcnt lgkmcnt(6)
	v_mfma_f32_32x32x16_bf16 v[52:67], v[148:151], v[144:147], v[52:67]
	ds_read_b128 v[168:171], v187 offset:60000
	ds_read_b128 v[172:175], v186 offset:41568
	s_waitcnt lgkmcnt(7)
	v_mfma_f32_32x32x16_bf16 v[36:51], v[152:155], v[144:147], v[36:51]
	s_waitcnt vmcnt(13)
	ds_write_b128 v184, v[92:95] offset:23040
	global_load_dwordx4 v[84:87], v[176:177], off offset:2560
	s_waitcnt lgkmcnt(7)
	v_mfma_f32_32x32x16_bf16 v[20:35], v[148:151], v[156:159], v[20:35]
	s_waitcnt vmcnt(13)
	ds_write_b128 v184, v[96:99] offset:27648
	global_load_dwordx4 v[88:91], v[104:105], off offset:2560
	v_mfma_f32_32x32x16_bf16 v[4:19], v[152:155], v[156:159], v[4:19]
	s_waitcnt vmcnt(13)
	ds_write_b128 v184, v[100:103] offset:32256
	global_load_dwordx4 v[92:95], v[178:179], off offset:2560
	s_waitcnt lgkmcnt(5)
	v_mfma_f32_32x32x16_bf16 v[52:67], v[164:167], v[160:163], v[52:67]
	global_load_dwordx4 v[96:99], v[180:181], off offset:2560
	s_waitcnt lgkmcnt(4)
	v_mfma_f32_32x32x16_bf16 v[36:51], v[168:171], v[160:163], v[36:51]
	global_load_dwordx4 v[100:103], v[182:183], off offset:2560
	s_waitcnt lgkmcnt(3)
	v_mfma_f32_32x32x16_bf16 v[20:35], v[164:167], v[172:175], v[20:35]
	v_mfma_f32_32x32x16_bf16 v[4:19], v[168:171], v[172:175], v[4:19]
	s_setprio 0
	s_waitcnt lgkmcnt(0)
	s_barrier
	ds_read_b128 v[144:147], v186
	ds_read_b128 v[148:151], v187 offset:18432
	ds_read_b128 v[152:155], v187 offset:23040
	ds_read_b128 v[156:159], v186 offset:4608
	ds_read_b128 v[160:163], v186 offset:32
	ds_read_b128 v[164:167], v187 offset:18464
	ds_read_b128 v[168:171], v187 offset:23072
	ds_read_b128 v[172:175], v186 offset:4640
	s_setprio 1
	s_waitcnt lgkmcnt(6)
	v_mfma_f32_32x32x16_bf16 v[52:67], v[148:151], v[144:147], v[52:67]
	s_waitcnt vmcnt(15)
	ds_write_b128 v185, v[108:111]
	s_waitcnt lgkmcnt(6)
	v_mfma_f32_32x32x16_bf16 v[36:51], v[152:155], v[144:147], v[36:51]
	s_waitcnt vmcnt(14)
	ds_write_b128 v185, v[112:115] offset:4608
	s_waitcnt lgkmcnt(6)
	v_mfma_f32_32x32x16_bf16 v[20:35], v[148:151], v[156:159], v[20:35]
	s_waitcnt vmcnt(13)
	ds_write_b128 v185, v[116:119] offset:9216
	global_load_dwordx4 v[108:111], v[72:73], off offset:2688
	v_mfma_f32_32x32x16_bf16 v[4:19], v[152:155], v[156:159], v[4:19]
	ds_read_b128 v[144:147], v186 offset:64
	ds_read_b128 v[148:151], v187 offset:18496
	s_waitcnt lgkmcnt(7)
	v_mfma_f32_32x32x16_bf16 v[52:67], v[164:167], v[160:163], v[52:67]
	ds_read_b128 v[152:155], v187 offset:23104
	ds_read_b128 v[156:159], v186 offset:4672
	s_waitcnt lgkmcnt(8)
	v_mfma_f32_32x32x16_bf16 v[36:51], v[168:171], v[160:163], v[36:51]
	s_waitcnt vmcnt(13)
	ds_write_b128 v185, v[120:123] offset:13824
	global_load_dwordx4 v[112:115], v[74:75], off offset:2688
	s_waitcnt lgkmcnt(8)
	v_mfma_f32_32x32x16_bf16 v[20:35], v[164:167], v[172:175], v[20:35]
	s_waitcnt vmcnt(13)
	ds_write_b128 v185, v[124:127] offset:18432
	global_load_dwordx4 v[116:119], v[106:107], off offset:2688
	v_mfma_f32_32x32x16_bf16 v[4:19], v[168:171], v[172:175], v[4:19]
	ds_read_b128 v[160:163], v186 offset:96
	ds_read_b128 v[164:167], v187 offset:18528
	s_waitcnt lgkmcnt(6)
	v_mfma_f32_32x32x16_bf16 v[52:67], v[148:151], v[144:147], v[52:67]
	ds_read_b128 v[168:171], v187 offset:23136
	ds_read_b128 v[172:175], v186 offset:4704
	s_waitcnt lgkmcnt(7)
	v_mfma_f32_32x32x16_bf16 v[36:51], v[152:155], v[144:147], v[36:51]
	s_waitcnt vmcnt(13)
	ds_write_b128 v185, v[128:131] offset:23040
	global_load_dwordx4 v[120:123], v[176:177], off offset:2688
	s_waitcnt lgkmcnt(7)
	v_mfma_f32_32x32x16_bf16 v[20:35], v[148:151], v[156:159], v[20:35]
	s_waitcnt vmcnt(13)
	ds_write_b128 v185, v[136:139] offset:27648
	global_load_dwordx4 v[124:127], v[104:105], off offset:2688
	v_mfma_f32_32x32x16_bf16 v[4:19], v[152:155], v[156:159], v[4:19]
	s_waitcnt vmcnt(13)
	ds_write_b128 v185, v[140:143] offset:32256
	global_load_dwordx4 v[128:131], v[178:179], off offset:2688
	s_waitcnt lgkmcnt(5)
	v_mfma_f32_32x32x16_bf16 v[52:67], v[164:167], v[160:163], v[52:67]
	global_load_dwordx4 v[136:139], v[180:181], off offset:2688
	s_waitcnt lgkmcnt(4)
	v_mfma_f32_32x32x16_bf16 v[36:51], v[168:171], v[160:163], v[36:51]
	global_load_dwordx4 v[140:143], v[182:183], off offset:2688
	s_waitcnt lgkmcnt(3)
	v_mfma_f32_32x32x16_bf16 v[20:35], v[164:167], v[172:175], v[20:35]
	v_mfma_f32_32x32x16_bf16 v[4:19], v[168:171], v[172:175], v[4:19]
	s_setprio 0
	s_waitcnt lgkmcnt(0)
	s_barrier
	ds_read_b128 v[144:147], v186 offset:36864
	ds_read_b128 v[148:151], v187 offset:55296
	ds_read_b128 v[152:155], v187 offset:59904
	ds_read_b128 v[156:159], v186 offset:41472
	ds_read_b128 v[160:163], v186 offset:36896
	ds_read_b128 v[164:167], v187 offset:55328
	ds_read_b128 v[168:171], v187 offset:59936
	ds_read_b128 v[172:175], v186 offset:41504
	s_setprio 1
	s_waitcnt lgkmcnt(6)
	v_mfma_f32_32x32x16_bf16 v[52:67], v[148:151], v[144:147], v[52:67]
	s_waitcnt vmcnt(15)
	ds_write_b128 v184, v[68:71]
	s_waitcnt lgkmcnt(6)
	v_mfma_f32_32x32x16_bf16 v[36:51], v[152:155], v[144:147], v[36:51]
	s_waitcnt vmcnt(14)
	ds_write_b128 v184, v[76:79] offset:4608
	s_waitcnt lgkmcnt(6)
	v_mfma_f32_32x32x16_bf16 v[20:35], v[148:151], v[156:159], v[20:35]
	s_waitcnt vmcnt(13)
	ds_write_b128 v184, v[80:83] offset:9216
	global_load_dwordx4 v[68:71], v[72:73], off offset:2816
	v_mfma_f32_32x32x16_bf16 v[4:19], v[152:155], v[156:159], v[4:19]
	ds_read_b128 v[144:147], v186 offset:36928
	ds_read_b128 v[148:151], v187 offset:55360
	s_waitcnt lgkmcnt(7)
	v_mfma_f32_32x32x16_bf16 v[52:67], v[164:167], v[160:163], v[52:67]
	ds_read_b128 v[152:155], v187 offset:59968
	ds_read_b128 v[156:159], v186 offset:41536
	s_waitcnt lgkmcnt(8)
	v_mfma_f32_32x32x16_bf16 v[36:51], v[168:171], v[160:163], v[36:51]
	s_waitcnt vmcnt(13)
	ds_write_b128 v184, v[84:87] offset:13824
	global_load_dwordx4 v[76:79], v[74:75], off offset:2816
	s_waitcnt lgkmcnt(8)
	v_mfma_f32_32x32x16_bf16 v[20:35], v[164:167], v[172:175], v[20:35]
	s_waitcnt vmcnt(13)
	ds_write_b128 v184, v[88:91] offset:18432
	global_load_dwordx4 v[80:83], v[106:107], off offset:2816
	v_mfma_f32_32x32x16_bf16 v[4:19], v[168:171], v[172:175], v[4:19]
	ds_read_b128 v[160:163], v186 offset:36960
	ds_read_b128 v[164:167], v187 offset:55392
	s_waitcnt lgkmcnt(6)
	v_mfma_f32_32x32x16_bf16 v[52:67], v[148:151], v[144:147], v[52:67]
	ds_read_b128 v[168:171], v187 offset:60000
	ds_read_b128 v[172:175], v186 offset:41568
	s_waitcnt lgkmcnt(7)
	v_mfma_f32_32x32x16_bf16 v[36:51], v[152:155], v[144:147], v[36:51]
	s_waitcnt vmcnt(13)
	ds_write_b128 v184, v[92:95] offset:23040
	global_load_dwordx4 v[84:87], v[176:177], off offset:2816
	s_waitcnt lgkmcnt(7)
	v_mfma_f32_32x32x16_bf16 v[20:35], v[148:151], v[156:159], v[20:35]
	s_waitcnt vmcnt(13)
	ds_write_b128 v184, v[96:99] offset:27648
	global_load_dwordx4 v[88:91], v[104:105], off offset:2816
	v_mfma_f32_32x32x16_bf16 v[4:19], v[152:155], v[156:159], v[4:19]
	s_waitcnt vmcnt(13)
	ds_write_b128 v184, v[100:103] offset:32256
	global_load_dwordx4 v[92:95], v[178:179], off offset:2816
	s_waitcnt lgkmcnt(5)
	v_mfma_f32_32x32x16_bf16 v[52:67], v[164:167], v[160:163], v[52:67]
	global_load_dwordx4 v[96:99], v[180:181], off offset:2816
	s_waitcnt lgkmcnt(4)
	v_mfma_f32_32x32x16_bf16 v[36:51], v[168:171], v[160:163], v[36:51]
	global_load_dwordx4 v[100:103], v[182:183], off offset:2816
	s_waitcnt lgkmcnt(3)
	v_mfma_f32_32x32x16_bf16 v[20:35], v[164:167], v[172:175], v[20:35]
	v_mfma_f32_32x32x16_bf16 v[4:19], v[168:171], v[172:175], v[4:19]
	s_setprio 0
	s_waitcnt lgkmcnt(0)
	s_barrier
	ds_read_b128 v[144:147], v186
	ds_read_b128 v[148:151], v187 offset:18432
	ds_read_b128 v[152:155], v187 offset:23040
	ds_read_b128 v[156:159], v186 offset:4608
	ds_read_b128 v[160:163], v186 offset:32
	ds_read_b128 v[164:167], v187 offset:18464
	ds_read_b128 v[168:171], v187 offset:23072
	ds_read_b128 v[172:175], v186 offset:4640
	s_setprio 1
	s_waitcnt lgkmcnt(6)
	v_mfma_f32_32x32x16_bf16 v[52:67], v[148:151], v[144:147], v[52:67]
	s_waitcnt vmcnt(15)
	ds_write_b128 v185, v[108:111]
	s_waitcnt lgkmcnt(6)
	v_mfma_f32_32x32x16_bf16 v[36:51], v[152:155], v[144:147], v[36:51]
	s_waitcnt vmcnt(14)
	ds_write_b128 v185, v[112:115] offset:4608
	s_waitcnt lgkmcnt(6)
	v_mfma_f32_32x32x16_bf16 v[20:35], v[148:151], v[156:159], v[20:35]
	s_waitcnt vmcnt(13)
	ds_write_b128 v185, v[116:119] offset:9216
	global_load_dwordx4 v[108:111], v[72:73], off offset:2944
	v_mfma_f32_32x32x16_bf16 v[4:19], v[152:155], v[156:159], v[4:19]
	ds_read_b128 v[144:147], v186 offset:64
	ds_read_b128 v[148:151], v187 offset:18496
	s_waitcnt lgkmcnt(7)
	v_mfma_f32_32x32x16_bf16 v[52:67], v[164:167], v[160:163], v[52:67]
	ds_read_b128 v[152:155], v187 offset:23104
	ds_read_b128 v[156:159], v186 offset:4672
	s_waitcnt lgkmcnt(8)
	v_mfma_f32_32x32x16_bf16 v[36:51], v[168:171], v[160:163], v[36:51]
	s_waitcnt vmcnt(13)
	ds_write_b128 v185, v[120:123] offset:13824
	global_load_dwordx4 v[112:115], v[74:75], off offset:2944
	s_waitcnt lgkmcnt(8)
	v_mfma_f32_32x32x16_bf16 v[20:35], v[164:167], v[172:175], v[20:35]
	s_waitcnt vmcnt(13)
	ds_write_b128 v185, v[124:127] offset:18432
	global_load_dwordx4 v[116:119], v[106:107], off offset:2944
	v_mfma_f32_32x32x16_bf16 v[4:19], v[168:171], v[172:175], v[4:19]
	ds_read_b128 v[160:163], v186 offset:96
	ds_read_b128 v[164:167], v187 offset:18528
	s_waitcnt lgkmcnt(6)
	v_mfma_f32_32x32x16_bf16 v[52:67], v[148:151], v[144:147], v[52:67]
	ds_read_b128 v[168:171], v187 offset:23136
	ds_read_b128 v[172:175], v186 offset:4704
	s_waitcnt lgkmcnt(7)
	v_mfma_f32_32x32x16_bf16 v[36:51], v[152:155], v[144:147], v[36:51]
	s_waitcnt vmcnt(13)
	ds_write_b128 v185, v[128:131] offset:23040
	global_load_dwordx4 v[120:123], v[176:177], off offset:2944
	s_waitcnt lgkmcnt(7)
	v_mfma_f32_32x32x16_bf16 v[20:35], v[148:151], v[156:159], v[20:35]
	s_waitcnt vmcnt(13)
	ds_write_b128 v185, v[136:139] offset:27648
	global_load_dwordx4 v[124:127], v[104:105], off offset:2944
	v_mfma_f32_32x32x16_bf16 v[4:19], v[152:155], v[156:159], v[4:19]
	s_waitcnt vmcnt(13)
	ds_write_b128 v185, v[140:143] offset:32256
	global_load_dwordx4 v[128:131], v[178:179], off offset:2944
	s_waitcnt lgkmcnt(5)
	v_mfma_f32_32x32x16_bf16 v[52:67], v[164:167], v[160:163], v[52:67]
	global_load_dwordx4 v[136:139], v[180:181], off offset:2944
	s_waitcnt lgkmcnt(4)
	v_mfma_f32_32x32x16_bf16 v[36:51], v[168:171], v[160:163], v[36:51]
	global_load_dwordx4 v[140:143], v[182:183], off offset:2944
	s_waitcnt lgkmcnt(3)
	v_mfma_f32_32x32x16_bf16 v[20:35], v[164:167], v[172:175], v[20:35]
	v_mfma_f32_32x32x16_bf16 v[4:19], v[168:171], v[172:175], v[4:19]
	s_setprio 0
	s_waitcnt lgkmcnt(0)
	s_barrier
	ds_read_b128 v[144:147], v186 offset:36864
	ds_read_b128 v[148:151], v187 offset:55296
	ds_read_b128 v[152:155], v187 offset:59904
	ds_read_b128 v[156:159], v186 offset:41472
	ds_read_b128 v[160:163], v186 offset:36896
	ds_read_b128 v[164:167], v187 offset:55328
	ds_read_b128 v[168:171], v187 offset:59936
	ds_read_b128 v[172:175], v186 offset:41504
	s_setprio 1
	s_waitcnt lgkmcnt(6)
	v_mfma_f32_32x32x16_bf16 v[52:67], v[148:151], v[144:147], v[52:67]
	s_waitcnt vmcnt(15)
	ds_write_b128 v184, v[68:71]
	s_waitcnt lgkmcnt(6)
	v_mfma_f32_32x32x16_bf16 v[36:51], v[152:155], v[144:147], v[36:51]
	s_waitcnt vmcnt(14)
	ds_write_b128 v184, v[76:79] offset:4608
	s_waitcnt lgkmcnt(6)
	v_mfma_f32_32x32x16_bf16 v[20:35], v[148:151], v[156:159], v[20:35]
	s_waitcnt vmcnt(13)
	ds_write_b128 v184, v[80:83] offset:9216
	global_load_dwordx4 v[68:71], v[72:73], off offset:3072
	v_mfma_f32_32x32x16_bf16 v[4:19], v[152:155], v[156:159], v[4:19]
	ds_read_b128 v[144:147], v186 offset:36928
	ds_read_b128 v[148:151], v187 offset:55360
	s_waitcnt lgkmcnt(7)
	v_mfma_f32_32x32x16_bf16 v[52:67], v[164:167], v[160:163], v[52:67]
	ds_read_b128 v[152:155], v187 offset:59968
	ds_read_b128 v[156:159], v186 offset:41536
	s_waitcnt lgkmcnt(8)
	v_mfma_f32_32x32x16_bf16 v[36:51], v[168:171], v[160:163], v[36:51]
	s_waitcnt vmcnt(13)
	ds_write_b128 v184, v[84:87] offset:13824
	global_load_dwordx4 v[76:79], v[74:75], off offset:3072
	s_waitcnt lgkmcnt(8)
	v_mfma_f32_32x32x16_bf16 v[20:35], v[164:167], v[172:175], v[20:35]
	s_waitcnt vmcnt(13)
	ds_write_b128 v184, v[88:91] offset:18432
	global_load_dwordx4 v[80:83], v[106:107], off offset:3072
	v_mfma_f32_32x32x16_bf16 v[4:19], v[168:171], v[172:175], v[4:19]
	ds_read_b128 v[160:163], v186 offset:36960
	ds_read_b128 v[164:167], v187 offset:55392
	s_waitcnt lgkmcnt(6)
	v_mfma_f32_32x32x16_bf16 v[52:67], v[148:151], v[144:147], v[52:67]
	ds_read_b128 v[168:171], v187 offset:60000
	ds_read_b128 v[172:175], v186 offset:41568
	s_waitcnt lgkmcnt(7)
	v_mfma_f32_32x32x16_bf16 v[36:51], v[152:155], v[144:147], v[36:51]
	s_waitcnt vmcnt(13)
	ds_write_b128 v184, v[92:95] offset:23040
	global_load_dwordx4 v[84:87], v[176:177], off offset:3072
	s_waitcnt lgkmcnt(7)
	v_mfma_f32_32x32x16_bf16 v[20:35], v[148:151], v[156:159], v[20:35]
	s_waitcnt vmcnt(13)
	ds_write_b128 v184, v[96:99] offset:27648
	global_load_dwordx4 v[88:91], v[104:105], off offset:3072
	v_mfma_f32_32x32x16_bf16 v[4:19], v[152:155], v[156:159], v[4:19]
	s_waitcnt vmcnt(13)
	ds_write_b128 v184, v[100:103] offset:32256
	global_load_dwordx4 v[92:95], v[178:179], off offset:3072
	s_waitcnt lgkmcnt(5)
	v_mfma_f32_32x32x16_bf16 v[52:67], v[164:167], v[160:163], v[52:67]
	global_load_dwordx4 v[96:99], v[180:181], off offset:3072
	s_waitcnt lgkmcnt(4)
	v_mfma_f32_32x32x16_bf16 v[36:51], v[168:171], v[160:163], v[36:51]
	global_load_dwordx4 v[100:103], v[182:183], off offset:3072
	s_waitcnt lgkmcnt(3)
	v_mfma_f32_32x32x16_bf16 v[20:35], v[164:167], v[172:175], v[20:35]
	v_mfma_f32_32x32x16_bf16 v[4:19], v[168:171], v[172:175], v[4:19]
	s_setprio 0
	s_waitcnt lgkmcnt(0)
	s_barrier
	ds_read_b128 v[144:147], v186
	ds_read_b128 v[148:151], v187 offset:18432
	ds_read_b128 v[152:155], v187 offset:23040
	ds_read_b128 v[156:159], v186 offset:4608
	ds_read_b128 v[160:163], v186 offset:32
	ds_read_b128 v[164:167], v187 offset:18464
	ds_read_b128 v[168:171], v187 offset:23072
	ds_read_b128 v[172:175], v186 offset:4640
	s_setprio 1
	s_waitcnt lgkmcnt(6)
	v_mfma_f32_32x32x16_bf16 v[52:67], v[148:151], v[144:147], v[52:67]
	s_waitcnt vmcnt(15)
	ds_write_b128 v185, v[108:111]
	s_waitcnt lgkmcnt(6)
	v_mfma_f32_32x32x16_bf16 v[36:51], v[152:155], v[144:147], v[36:51]
	s_waitcnt vmcnt(14)
	ds_write_b128 v185, v[112:115] offset:4608
	s_waitcnt lgkmcnt(6)
	v_mfma_f32_32x32x16_bf16 v[20:35], v[148:151], v[156:159], v[20:35]
	s_waitcnt vmcnt(13)
	ds_write_b128 v185, v[116:119] offset:9216
	global_load_dwordx4 v[108:111], v[72:73], off offset:3200
	v_mfma_f32_32x32x16_bf16 v[4:19], v[152:155], v[156:159], v[4:19]
	ds_read_b128 v[144:147], v186 offset:64
	ds_read_b128 v[148:151], v187 offset:18496
	s_waitcnt lgkmcnt(7)
	v_mfma_f32_32x32x16_bf16 v[52:67], v[164:167], v[160:163], v[52:67]
	ds_read_b128 v[152:155], v187 offset:23104
	ds_read_b128 v[156:159], v186 offset:4672
	s_waitcnt lgkmcnt(8)
	v_mfma_f32_32x32x16_bf16 v[36:51], v[168:171], v[160:163], v[36:51]
	s_waitcnt vmcnt(13)
	ds_write_b128 v185, v[120:123] offset:13824
	global_load_dwordx4 v[112:115], v[74:75], off offset:3200
	s_waitcnt lgkmcnt(8)
	v_mfma_f32_32x32x16_bf16 v[20:35], v[164:167], v[172:175], v[20:35]
	s_waitcnt vmcnt(13)
	ds_write_b128 v185, v[124:127] offset:18432
	global_load_dwordx4 v[116:119], v[106:107], off offset:3200
	v_mfma_f32_32x32x16_bf16 v[4:19], v[168:171], v[172:175], v[4:19]
	ds_read_b128 v[160:163], v186 offset:96
	ds_read_b128 v[164:167], v187 offset:18528
	s_waitcnt lgkmcnt(6)
	v_mfma_f32_32x32x16_bf16 v[52:67], v[148:151], v[144:147], v[52:67]
	ds_read_b128 v[168:171], v187 offset:23136
	ds_read_b128 v[172:175], v186 offset:4704
	s_waitcnt lgkmcnt(7)
	v_mfma_f32_32x32x16_bf16 v[36:51], v[152:155], v[144:147], v[36:51]
	s_waitcnt vmcnt(13)
	ds_write_b128 v185, v[128:131] offset:23040
	global_load_dwordx4 v[120:123], v[176:177], off offset:3200
	s_waitcnt lgkmcnt(7)
	v_mfma_f32_32x32x16_bf16 v[20:35], v[148:151], v[156:159], v[20:35]
	s_waitcnt vmcnt(13)
	ds_write_b128 v185, v[136:139] offset:27648
	global_load_dwordx4 v[124:127], v[104:105], off offset:3200
	v_mfma_f32_32x32x16_bf16 v[4:19], v[152:155], v[156:159], v[4:19]
	s_waitcnt vmcnt(13)
	ds_write_b128 v185, v[140:143] offset:32256
	global_load_dwordx4 v[128:131], v[178:179], off offset:3200
	s_waitcnt lgkmcnt(5)
	v_mfma_f32_32x32x16_bf16 v[52:67], v[164:167], v[160:163], v[52:67]
	global_load_dwordx4 v[136:139], v[180:181], off offset:3200
	s_waitcnt lgkmcnt(4)
	v_mfma_f32_32x32x16_bf16 v[36:51], v[168:171], v[160:163], v[36:51]
	global_load_dwordx4 v[140:143], v[182:183], off offset:3200
	s_waitcnt lgkmcnt(3)
	v_mfma_f32_32x32x16_bf16 v[20:35], v[164:167], v[172:175], v[20:35]
	v_mfma_f32_32x32x16_bf16 v[4:19], v[168:171], v[172:175], v[4:19]
	s_setprio 0
	s_waitcnt lgkmcnt(0)
	s_barrier
	ds_read_b128 v[144:147], v186 offset:36864
	ds_read_b128 v[148:151], v187 offset:55296
	ds_read_b128 v[152:155], v187 offset:59904
	ds_read_b128 v[156:159], v186 offset:41472
	ds_read_b128 v[160:163], v186 offset:36896
	ds_read_b128 v[164:167], v187 offset:55328
	ds_read_b128 v[168:171], v187 offset:59936
	ds_read_b128 v[172:175], v186 offset:41504
	s_setprio 1
	s_waitcnt lgkmcnt(6)
	v_mfma_f32_32x32x16_bf16 v[52:67], v[148:151], v[144:147], v[52:67]
	s_waitcnt vmcnt(15)
	ds_write_b128 v184, v[68:71]
	s_waitcnt lgkmcnt(6)
	v_mfma_f32_32x32x16_bf16 v[36:51], v[152:155], v[144:147], v[36:51]
	s_waitcnt vmcnt(14)
	ds_write_b128 v184, v[76:79] offset:4608
	s_waitcnt lgkmcnt(6)
	v_mfma_f32_32x32x16_bf16 v[20:35], v[148:151], v[156:159], v[20:35]
	s_waitcnt vmcnt(13)
	ds_write_b128 v184, v[80:83] offset:9216
	global_load_dwordx4 v[68:71], v[72:73], off offset:3328
	v_mfma_f32_32x32x16_bf16 v[4:19], v[152:155], v[156:159], v[4:19]
	ds_read_b128 v[144:147], v186 offset:36928
	ds_read_b128 v[148:151], v187 offset:55360
	s_waitcnt lgkmcnt(7)
	v_mfma_f32_32x32x16_bf16 v[52:67], v[164:167], v[160:163], v[52:67]
	ds_read_b128 v[152:155], v187 offset:59968
	ds_read_b128 v[156:159], v186 offset:41536
	s_waitcnt lgkmcnt(8)
	v_mfma_f32_32x32x16_bf16 v[36:51], v[168:171], v[160:163], v[36:51]
	s_waitcnt vmcnt(13)
	ds_write_b128 v184, v[84:87] offset:13824
	global_load_dwordx4 v[76:79], v[74:75], off offset:3328
	s_waitcnt lgkmcnt(8)
	v_mfma_f32_32x32x16_bf16 v[20:35], v[164:167], v[172:175], v[20:35]
	s_waitcnt vmcnt(13)
	ds_write_b128 v184, v[88:91] offset:18432
	global_load_dwordx4 v[80:83], v[106:107], off offset:3328
	v_mfma_f32_32x32x16_bf16 v[4:19], v[168:171], v[172:175], v[4:19]
	ds_read_b128 v[160:163], v186 offset:36960
	ds_read_b128 v[164:167], v187 offset:55392
	s_waitcnt lgkmcnt(6)
	v_mfma_f32_32x32x16_bf16 v[52:67], v[148:151], v[144:147], v[52:67]
	ds_read_b128 v[168:171], v187 offset:60000
	ds_read_b128 v[172:175], v186 offset:41568
	s_waitcnt lgkmcnt(7)
	v_mfma_f32_32x32x16_bf16 v[36:51], v[152:155], v[144:147], v[36:51]
	s_waitcnt vmcnt(13)
	ds_write_b128 v184, v[92:95] offset:23040
	global_load_dwordx4 v[84:87], v[176:177], off offset:3328
	s_waitcnt lgkmcnt(7)
	v_mfma_f32_32x32x16_bf16 v[20:35], v[148:151], v[156:159], v[20:35]
	s_waitcnt vmcnt(13)
	ds_write_b128 v184, v[96:99] offset:27648
	global_load_dwordx4 v[88:91], v[104:105], off offset:3328
	v_mfma_f32_32x32x16_bf16 v[4:19], v[152:155], v[156:159], v[4:19]
	s_waitcnt vmcnt(13)
	ds_write_b128 v184, v[100:103] offset:32256
	global_load_dwordx4 v[92:95], v[178:179], off offset:3328
	s_waitcnt lgkmcnt(5)
	v_mfma_f32_32x32x16_bf16 v[52:67], v[164:167], v[160:163], v[52:67]
	global_load_dwordx4 v[96:99], v[180:181], off offset:3328
	s_waitcnt lgkmcnt(4)
	v_mfma_f32_32x32x16_bf16 v[36:51], v[168:171], v[160:163], v[36:51]
	global_load_dwordx4 v[100:103], v[182:183], off offset:3328
	s_waitcnt lgkmcnt(3)
	v_mfma_f32_32x32x16_bf16 v[20:35], v[164:167], v[172:175], v[20:35]
	v_mfma_f32_32x32x16_bf16 v[4:19], v[168:171], v[172:175], v[4:19]
	s_setprio 0
	s_waitcnt lgkmcnt(0)
	s_barrier
	ds_read_b128 v[144:147], v186
	ds_read_b128 v[148:151], v187 offset:18432
	ds_read_b128 v[152:155], v187 offset:23040
	ds_read_b128 v[156:159], v186 offset:4608
	ds_read_b128 v[160:163], v186 offset:32
	ds_read_b128 v[164:167], v187 offset:18464
	ds_read_b128 v[168:171], v187 offset:23072
	ds_read_b128 v[172:175], v186 offset:4640
	s_setprio 1
	s_waitcnt lgkmcnt(6)
	v_mfma_f32_32x32x16_bf16 v[52:67], v[148:151], v[144:147], v[52:67]
	s_waitcnt vmcnt(15)
	ds_write_b128 v185, v[108:111]
	s_waitcnt lgkmcnt(6)
	v_mfma_f32_32x32x16_bf16 v[36:51], v[152:155], v[144:147], v[36:51]
	s_waitcnt vmcnt(14)
	ds_write_b128 v185, v[112:115] offset:4608
	s_waitcnt lgkmcnt(6)
	v_mfma_f32_32x32x16_bf16 v[20:35], v[148:151], v[156:159], v[20:35]
	s_waitcnt vmcnt(13)
	ds_write_b128 v185, v[116:119] offset:9216
	global_load_dwordx4 v[108:111], v[72:73], off offset:3456
	v_mfma_f32_32x32x16_bf16 v[4:19], v[152:155], v[156:159], v[4:19]
	ds_read_b128 v[144:147], v186 offset:64
	ds_read_b128 v[148:151], v187 offset:18496
	s_waitcnt lgkmcnt(7)
	v_mfma_f32_32x32x16_bf16 v[52:67], v[164:167], v[160:163], v[52:67]
	ds_read_b128 v[152:155], v187 offset:23104
	ds_read_b128 v[156:159], v186 offset:4672
	s_waitcnt lgkmcnt(8)
	v_mfma_f32_32x32x16_bf16 v[36:51], v[168:171], v[160:163], v[36:51]
	s_waitcnt vmcnt(13)
	ds_write_b128 v185, v[120:123] offset:13824
	global_load_dwordx4 v[112:115], v[74:75], off offset:3456
	s_waitcnt lgkmcnt(8)
	v_mfma_f32_32x32x16_bf16 v[20:35], v[164:167], v[172:175], v[20:35]
	s_waitcnt vmcnt(13)
	ds_write_b128 v185, v[124:127] offset:18432
	global_load_dwordx4 v[116:119], v[106:107], off offset:3456
	v_mfma_f32_32x32x16_bf16 v[4:19], v[168:171], v[172:175], v[4:19]
	ds_read_b128 v[160:163], v186 offset:96
	ds_read_b128 v[164:167], v187 offset:18528
	s_waitcnt lgkmcnt(6)
	v_mfma_f32_32x32x16_bf16 v[52:67], v[148:151], v[144:147], v[52:67]
	ds_read_b128 v[168:171], v187 offset:23136
	ds_read_b128 v[172:175], v186 offset:4704
	s_waitcnt lgkmcnt(7)
	v_mfma_f32_32x32x16_bf16 v[36:51], v[152:155], v[144:147], v[36:51]
	s_waitcnt vmcnt(13)
	ds_write_b128 v185, v[128:131] offset:23040
	global_load_dwordx4 v[120:123], v[176:177], off offset:3456
	s_waitcnt lgkmcnt(7)
	v_mfma_f32_32x32x16_bf16 v[20:35], v[148:151], v[156:159], v[20:35]
	s_waitcnt vmcnt(13)
	ds_write_b128 v185, v[136:139] offset:27648
	global_load_dwordx4 v[124:127], v[104:105], off offset:3456
	v_mfma_f32_32x32x16_bf16 v[4:19], v[152:155], v[156:159], v[4:19]
	s_waitcnt vmcnt(13)
	ds_write_b128 v185, v[140:143] offset:32256
	global_load_dwordx4 v[128:131], v[178:179], off offset:3456
	s_waitcnt lgkmcnt(5)
	v_mfma_f32_32x32x16_bf16 v[52:67], v[164:167], v[160:163], v[52:67]
	global_load_dwordx4 v[136:139], v[180:181], off offset:3456
	s_waitcnt lgkmcnt(4)
	v_mfma_f32_32x32x16_bf16 v[36:51], v[168:171], v[160:163], v[36:51]
	global_load_dwordx4 v[140:143], v[182:183], off offset:3456
	s_waitcnt lgkmcnt(3)
	v_mfma_f32_32x32x16_bf16 v[20:35], v[164:167], v[172:175], v[20:35]
	v_mfma_f32_32x32x16_bf16 v[4:19], v[168:171], v[172:175], v[4:19]
	s_setprio 0
	s_waitcnt lgkmcnt(0)
	s_barrier
	ds_read_b128 v[144:147], v186 offset:36864
	ds_read_b128 v[148:151], v187 offset:55296
	ds_read_b128 v[152:155], v187 offset:59904
	ds_read_b128 v[156:159], v186 offset:41472
	ds_read_b128 v[160:163], v186 offset:36896
	ds_read_b128 v[164:167], v187 offset:55328
	ds_read_b128 v[168:171], v187 offset:59936
	ds_read_b128 v[172:175], v186 offset:41504
	s_setprio 1
	s_waitcnt lgkmcnt(6)
	v_mfma_f32_32x32x16_bf16 v[52:67], v[148:151], v[144:147], v[52:67]
	s_waitcnt vmcnt(15)
	ds_write_b128 v184, v[68:71]
	s_waitcnt lgkmcnt(6)
	v_mfma_f32_32x32x16_bf16 v[36:51], v[152:155], v[144:147], v[36:51]
	s_waitcnt vmcnt(14)
	ds_write_b128 v184, v[76:79] offset:4608
	s_waitcnt lgkmcnt(6)
	v_mfma_f32_32x32x16_bf16 v[20:35], v[148:151], v[156:159], v[20:35]
	s_waitcnt vmcnt(13)
	ds_write_b128 v184, v[80:83] offset:9216
	global_load_dwordx4 v[68:71], v[72:73], off offset:3584
	v_mfma_f32_32x32x16_bf16 v[4:19], v[152:155], v[156:159], v[4:19]
	ds_read_b128 v[144:147], v186 offset:36928
	ds_read_b128 v[148:151], v187 offset:55360
	s_waitcnt lgkmcnt(7)
	v_mfma_f32_32x32x16_bf16 v[52:67], v[164:167], v[160:163], v[52:67]
	ds_read_b128 v[152:155], v187 offset:59968
	ds_read_b128 v[156:159], v186 offset:41536
	s_waitcnt lgkmcnt(8)
	v_mfma_f32_32x32x16_bf16 v[36:51], v[168:171], v[160:163], v[36:51]
	s_waitcnt vmcnt(13)
	ds_write_b128 v184, v[84:87] offset:13824
	global_load_dwordx4 v[76:79], v[74:75], off offset:3584
	s_waitcnt lgkmcnt(8)
	v_mfma_f32_32x32x16_bf16 v[20:35], v[164:167], v[172:175], v[20:35]
	s_waitcnt vmcnt(13)
	ds_write_b128 v184, v[88:91] offset:18432
	global_load_dwordx4 v[80:83], v[106:107], off offset:3584
	v_mfma_f32_32x32x16_bf16 v[4:19], v[168:171], v[172:175], v[4:19]
	ds_read_b128 v[160:163], v186 offset:36960
	ds_read_b128 v[164:167], v187 offset:55392
	s_waitcnt lgkmcnt(6)
	v_mfma_f32_32x32x16_bf16 v[52:67], v[148:151], v[144:147], v[52:67]
	ds_read_b128 v[168:171], v187 offset:60000
	ds_read_b128 v[172:175], v186 offset:41568
	s_waitcnt lgkmcnt(7)
	v_mfma_f32_32x32x16_bf16 v[36:51], v[152:155], v[144:147], v[36:51]
	s_waitcnt vmcnt(13)
	ds_write_b128 v184, v[92:95] offset:23040
	global_load_dwordx4 v[84:87], v[176:177], off offset:3584
	s_waitcnt lgkmcnt(7)
	v_mfma_f32_32x32x16_bf16 v[20:35], v[148:151], v[156:159], v[20:35]
	s_waitcnt vmcnt(13)
	ds_write_b128 v184, v[96:99] offset:27648
	global_load_dwordx4 v[88:91], v[104:105], off offset:3584
	v_mfma_f32_32x32x16_bf16 v[4:19], v[152:155], v[156:159], v[4:19]
	s_waitcnt vmcnt(13)
	ds_write_b128 v184, v[100:103] offset:32256
	global_load_dwordx4 v[92:95], v[178:179], off offset:3584
	s_waitcnt lgkmcnt(5)
	v_mfma_f32_32x32x16_bf16 v[52:67], v[164:167], v[160:163], v[52:67]
	global_load_dwordx4 v[96:99], v[180:181], off offset:3584
	s_waitcnt lgkmcnt(4)
	v_mfma_f32_32x32x16_bf16 v[36:51], v[168:171], v[160:163], v[36:51]
	global_load_dwordx4 v[100:103], v[182:183], off offset:3584
	s_waitcnt lgkmcnt(3)
	v_mfma_f32_32x32x16_bf16 v[20:35], v[164:167], v[172:175], v[20:35]
	v_mfma_f32_32x32x16_bf16 v[4:19], v[168:171], v[172:175], v[4:19]
	s_setprio 0
	s_waitcnt lgkmcnt(0)
	s_barrier
	ds_read_b128 v[144:147], v186
	ds_read_b128 v[148:151], v187 offset:18432
	ds_read_b128 v[152:155], v187 offset:23040
	ds_read_b128 v[156:159], v186 offset:4608
	ds_read_b128 v[160:163], v186 offset:32
	ds_read_b128 v[164:167], v187 offset:18464
	ds_read_b128 v[168:171], v187 offset:23072
	ds_read_b128 v[172:175], v186 offset:4640
	s_setprio 1
	s_waitcnt lgkmcnt(6)
	v_mfma_f32_32x32x16_bf16 v[52:67], v[148:151], v[144:147], v[52:67]
	s_waitcnt vmcnt(15)
	ds_write_b128 v185, v[108:111]
	s_waitcnt lgkmcnt(6)
	v_mfma_f32_32x32x16_bf16 v[36:51], v[152:155], v[144:147], v[36:51]
	s_waitcnt vmcnt(14)
	ds_write_b128 v185, v[112:115] offset:4608
	s_waitcnt lgkmcnt(6)
	v_mfma_f32_32x32x16_bf16 v[20:35], v[148:151], v[156:159], v[20:35]
	s_waitcnt vmcnt(13)
	ds_write_b128 v185, v[116:119] offset:9216
	global_load_dwordx4 v[108:111], v[72:73], off offset:3712
	v_mfma_f32_32x32x16_bf16 v[4:19], v[152:155], v[156:159], v[4:19]
	ds_read_b128 v[144:147], v186 offset:64
	ds_read_b128 v[148:151], v187 offset:18496
	s_waitcnt lgkmcnt(7)
	v_mfma_f32_32x32x16_bf16 v[52:67], v[164:167], v[160:163], v[52:67]
	ds_read_b128 v[152:155], v187 offset:23104
	ds_read_b128 v[156:159], v186 offset:4672
	s_waitcnt lgkmcnt(8)
	v_mfma_f32_32x32x16_bf16 v[36:51], v[168:171], v[160:163], v[36:51]
	s_waitcnt vmcnt(13)
	ds_write_b128 v185, v[120:123] offset:13824
	global_load_dwordx4 v[112:115], v[74:75], off offset:3712
	s_waitcnt lgkmcnt(8)
	v_mfma_f32_32x32x16_bf16 v[20:35], v[164:167], v[172:175], v[20:35]
	s_waitcnt vmcnt(13)
	ds_write_b128 v185, v[124:127] offset:18432
	global_load_dwordx4 v[116:119], v[106:107], off offset:3712
	v_mfma_f32_32x32x16_bf16 v[4:19], v[168:171], v[172:175], v[4:19]
	ds_read_b128 v[160:163], v186 offset:96
	ds_read_b128 v[164:167], v187 offset:18528
	s_waitcnt lgkmcnt(6)
	v_mfma_f32_32x32x16_bf16 v[52:67], v[148:151], v[144:147], v[52:67]
	ds_read_b128 v[168:171], v187 offset:23136
	ds_read_b128 v[172:175], v186 offset:4704
	s_waitcnt lgkmcnt(7)
	v_mfma_f32_32x32x16_bf16 v[36:51], v[152:155], v[144:147], v[36:51]
	s_waitcnt vmcnt(13)
	ds_write_b128 v185, v[128:131] offset:23040
	global_load_dwordx4 v[120:123], v[176:177], off offset:3712
	s_waitcnt lgkmcnt(7)
	v_mfma_f32_32x32x16_bf16 v[20:35], v[148:151], v[156:159], v[20:35]
	s_waitcnt vmcnt(13)
	ds_write_b128 v185, v[136:139] offset:27648
	global_load_dwordx4 v[124:127], v[104:105], off offset:3712
	v_mfma_f32_32x32x16_bf16 v[4:19], v[152:155], v[156:159], v[4:19]
	s_waitcnt vmcnt(13)
	ds_write_b128 v185, v[140:143] offset:32256
	global_load_dwordx4 v[128:131], v[178:179], off offset:3712
	s_waitcnt lgkmcnt(5)
	v_mfma_f32_32x32x16_bf16 v[52:67], v[164:167], v[160:163], v[52:67]
	global_load_dwordx4 v[136:139], v[180:181], off offset:3712
	s_waitcnt lgkmcnt(4)
	v_mfma_f32_32x32x16_bf16 v[36:51], v[168:171], v[160:163], v[36:51]
	global_load_dwordx4 v[140:143], v[182:183], off offset:3712
	s_waitcnt lgkmcnt(3)
	v_mfma_f32_32x32x16_bf16 v[20:35], v[164:167], v[172:175], v[20:35]
	v_mfma_f32_32x32x16_bf16 v[4:19], v[168:171], v[172:175], v[4:19]
	s_setprio 0
	s_waitcnt lgkmcnt(0)
	s_barrier
	ds_read_b128 v[144:147], v186 offset:36864
	ds_read_b128 v[148:151], v187 offset:55296
	ds_read_b128 v[152:155], v187 offset:59904
	ds_read_b128 v[156:159], v186 offset:41472
	ds_read_b128 v[160:163], v186 offset:36896
	ds_read_b128 v[164:167], v187 offset:55328
	ds_read_b128 v[168:171], v187 offset:59936
	ds_read_b128 v[172:175], v186 offset:41504
	s_setprio 1
	s_waitcnt lgkmcnt(6)
	v_mfma_f32_32x32x16_bf16 v[52:67], v[148:151], v[144:147], v[52:67]
	s_waitcnt vmcnt(15)
	ds_write_b128 v184, v[68:71]
	s_waitcnt lgkmcnt(6)
	v_mfma_f32_32x32x16_bf16 v[36:51], v[152:155], v[144:147], v[36:51]
	s_waitcnt vmcnt(14)
	ds_write_b128 v184, v[76:79] offset:4608
	s_waitcnt lgkmcnt(6)
	v_mfma_f32_32x32x16_bf16 v[20:35], v[148:151], v[156:159], v[20:35]
	s_waitcnt vmcnt(13)
	ds_write_b128 v184, v[80:83] offset:9216
	global_load_dwordx4 v[68:71], v[72:73], off offset:3840
	v_mfma_f32_32x32x16_bf16 v[4:19], v[152:155], v[156:159], v[4:19]
	ds_read_b128 v[144:147], v186 offset:36928
	ds_read_b128 v[148:151], v187 offset:55360
	s_waitcnt lgkmcnt(7)
	v_mfma_f32_32x32x16_bf16 v[52:67], v[164:167], v[160:163], v[52:67]
	ds_read_b128 v[152:155], v187 offset:59968
	ds_read_b128 v[156:159], v186 offset:41536
	s_waitcnt lgkmcnt(8)
	v_mfma_f32_32x32x16_bf16 v[36:51], v[168:171], v[160:163], v[36:51]
	s_waitcnt vmcnt(13)
	ds_write_b128 v184, v[84:87] offset:13824
	global_load_dwordx4 v[76:79], v[74:75], off offset:3840
	s_waitcnt lgkmcnt(8)
	v_mfma_f32_32x32x16_bf16 v[20:35], v[164:167], v[172:175], v[20:35]
	s_waitcnt vmcnt(13)
	ds_write_b128 v184, v[88:91] offset:18432
	global_load_dwordx4 v[80:83], v[106:107], off offset:3840
	v_mfma_f32_32x32x16_bf16 v[4:19], v[168:171], v[172:175], v[4:19]
	ds_read_b128 v[160:163], v186 offset:36960
	ds_read_b128 v[164:167], v187 offset:55392
	s_waitcnt lgkmcnt(6)
	v_mfma_f32_32x32x16_bf16 v[52:67], v[148:151], v[144:147], v[52:67]
	ds_read_b128 v[168:171], v187 offset:60000
	ds_read_b128 v[172:175], v186 offset:41568
	s_waitcnt lgkmcnt(7)
	v_mfma_f32_32x32x16_bf16 v[36:51], v[152:155], v[144:147], v[36:51]
	s_waitcnt vmcnt(13)
	ds_write_b128 v184, v[92:95] offset:23040
	global_load_dwordx4 v[84:87], v[176:177], off offset:3840
	s_waitcnt lgkmcnt(7)
	v_mfma_f32_32x32x16_bf16 v[20:35], v[148:151], v[156:159], v[20:35]
	s_waitcnt vmcnt(13)
	ds_write_b128 v184, v[96:99] offset:27648
	global_load_dwordx4 v[88:91], v[104:105], off offset:3840
	v_mfma_f32_32x32x16_bf16 v[4:19], v[152:155], v[156:159], v[4:19]
	s_waitcnt vmcnt(13)
	ds_write_b128 v184, v[100:103] offset:32256
	global_load_dwordx4 v[92:95], v[178:179], off offset:3840
	s_waitcnt lgkmcnt(5)
	v_mfma_f32_32x32x16_bf16 v[52:67], v[164:167], v[160:163], v[52:67]
	global_load_dwordx4 v[96:99], v[180:181], off offset:3840
	s_waitcnt lgkmcnt(4)
	v_mfma_f32_32x32x16_bf16 v[36:51], v[168:171], v[160:163], v[36:51]
	global_load_dwordx4 v[100:103], v[182:183], off offset:3840
	s_waitcnt lgkmcnt(3)
	v_mfma_f32_32x32x16_bf16 v[20:35], v[164:167], v[172:175], v[20:35]
	v_mfma_f32_32x32x16_bf16 v[4:19], v[168:171], v[172:175], v[4:19]
	s_setprio 0
	s_waitcnt lgkmcnt(0)
	s_barrier
	ds_read_b128 v[144:147], v186
	ds_read_b128 v[148:151], v187 offset:18432
	ds_read_b128 v[152:155], v187 offset:23040
	ds_read_b128 v[156:159], v186 offset:4608
	ds_read_b128 v[160:163], v186 offset:32
	ds_read_b128 v[164:167], v187 offset:18464
	ds_read_b128 v[168:171], v187 offset:23072
	ds_read_b128 v[172:175], v186 offset:4640
	s_setprio 1
	s_waitcnt lgkmcnt(6)
	v_mfma_f32_32x32x16_bf16 v[52:67], v[148:151], v[144:147], v[52:67]
	s_waitcnt vmcnt(15)
	ds_write_b128 v185, v[108:111]
	s_waitcnt lgkmcnt(6)
	v_mfma_f32_32x32x16_bf16 v[36:51], v[152:155], v[144:147], v[36:51]
	s_waitcnt vmcnt(14)
	ds_write_b128 v185, v[112:115] offset:4608
	s_waitcnt lgkmcnt(6)
	v_mfma_f32_32x32x16_bf16 v[20:35], v[148:151], v[156:159], v[20:35]
	s_waitcnt vmcnt(13)
	ds_write_b128 v185, v[116:119] offset:9216
	global_load_dwordx4 v[108:111], v[72:73], off offset:3968
	v_mfma_f32_32x32x16_bf16 v[4:19], v[152:155], v[156:159], v[4:19]
	ds_read_b128 v[144:147], v186 offset:64
	ds_read_b128 v[148:151], v187 offset:18496
	s_waitcnt lgkmcnt(7)
	v_mfma_f32_32x32x16_bf16 v[52:67], v[164:167], v[160:163], v[52:67]
	ds_read_b128 v[152:155], v187 offset:23104
	ds_read_b128 v[156:159], v186 offset:4672
	s_waitcnt lgkmcnt(8)
	v_mfma_f32_32x32x16_bf16 v[36:51], v[168:171], v[160:163], v[36:51]
	s_waitcnt vmcnt(13)
	ds_write_b128 v185, v[120:123] offset:13824
	global_load_dwordx4 v[112:115], v[74:75], off offset:3968
	s_waitcnt lgkmcnt(8)
	v_mfma_f32_32x32x16_bf16 v[20:35], v[164:167], v[172:175], v[20:35]
	s_waitcnt vmcnt(13)
	ds_write_b128 v185, v[124:127] offset:18432
	global_load_dwordx4 v[116:119], v[106:107], off offset:3968
	v_mfma_f32_32x32x16_bf16 v[4:19], v[168:171], v[172:175], v[4:19]
	ds_read_b128 v[160:163], v186 offset:96
	ds_read_b128 v[164:167], v187 offset:18528
	s_waitcnt lgkmcnt(6)
	v_mfma_f32_32x32x16_bf16 v[52:67], v[148:151], v[144:147], v[52:67]
	ds_read_b128 v[168:171], v187 offset:23136
	ds_read_b128 v[172:175], v186 offset:4704
	s_waitcnt lgkmcnt(7)
	v_mfma_f32_32x32x16_bf16 v[36:51], v[152:155], v[144:147], v[36:51]
	s_waitcnt vmcnt(13)
	ds_write_b128 v185, v[128:131] offset:23040
	global_load_dwordx4 v[120:123], v[176:177], off offset:3968
	s_waitcnt lgkmcnt(7)
	v_mfma_f32_32x32x16_bf16 v[20:35], v[148:151], v[156:159], v[20:35]
	s_waitcnt vmcnt(13)
	ds_write_b128 v185, v[136:139] offset:27648
	global_load_dwordx4 v[124:127], v[104:105], off offset:3968
	v_mfma_f32_32x32x16_bf16 v[4:19], v[152:155], v[156:159], v[4:19]
	s_waitcnt vmcnt(13)
	ds_write_b128 v185, v[140:143] offset:32256
	global_load_dwordx4 v[128:131], v[178:179], off offset:3968
	s_waitcnt lgkmcnt(5)
	v_mfma_f32_32x32x16_bf16 v[52:67], v[164:167], v[160:163], v[52:67]
	global_load_dwordx4 v[136:139], v[180:181], off offset:3968
	s_waitcnt lgkmcnt(4)
	v_mfma_f32_32x32x16_bf16 v[36:51], v[168:171], v[160:163], v[36:51]
	global_load_dwordx4 v[140:143], v[182:183], off offset:3968
	s_waitcnt lgkmcnt(3)
	v_mfma_f32_32x32x16_bf16 v[20:35], v[164:167], v[172:175], v[20:35]
	v_mfma_f32_32x32x16_bf16 v[4:19], v[168:171], v[172:175], v[4:19]
	s_setprio 0
	s_waitcnt lgkmcnt(0)
	s_barrier
	ds_read_b128 v[144:147], v186 offset:36864
	ds_read_b128 v[148:151], v187 offset:55296
	ds_read_b128 v[152:155], v187 offset:59904
	ds_read_b128 v[156:159], v186 offset:41472
	ds_read_b128 v[160:163], v186 offset:36896
	ds_read_b128 v[164:167], v187 offset:55328
	ds_read_b128 v[168:171], v187 offset:59936
	ds_read_b128 v[172:175], v186 offset:41504
	s_setprio 1
	s_waitcnt lgkmcnt(6)
	v_mfma_f32_32x32x16_bf16 v[52:67], v[148:151], v[144:147], v[52:67]
	s_waitcnt vmcnt(15)
	ds_write_b128 v184, v[68:71]
	s_waitcnt lgkmcnt(6)
	v_mfma_f32_32x32x16_bf16 v[36:51], v[152:155], v[144:147], v[36:51]
	s_waitcnt vmcnt(14)
	ds_write_b128 v184, v[76:79] offset:4608
	s_waitcnt lgkmcnt(6)
	v_mfma_f32_32x32x16_bf16 v[20:35], v[148:151], v[156:159], v[20:35]
	s_waitcnt vmcnt(13)
	ds_write_b128 v184, v[80:83] offset:9216
	v_add_co_u32_e32 v72, vcc, 0x1000, v72
	s_nop 1
	v_addc_co_u32_e32 v73, vcc, 0, v73, vcc
	v_add_co_u32_e32 v74, vcc, 0x1000, v74
	s_nop 1
	v_addc_co_u32_e32 v75, vcc, 0, v75, vcc
	v_add_co_u32_e32 v106, vcc, 0x1000, v106
	s_nop 1
	v_addc_co_u32_e32 v107, vcc, 0, v107, vcc
	v_add_co_u32_e32 v176, vcc, 0x1000, v176
	s_nop 1
	v_addc_co_u32_e32 v177, vcc, 0, v177, vcc
	v_add_co_u32_e32 v104, vcc, 0x1000, v104
	s_nop 1
	v_addc_co_u32_e32 v105, vcc, 0, v105, vcc
	v_add_co_u32_e32 v178, vcc, 0x1000, v178
	s_nop 1
	v_addc_co_u32_e32 v179, vcc, 0, v179, vcc
	v_add_co_u32_e32 v180, vcc, 0x1000, v180
	s_nop 1
	v_addc_co_u32_e32 v181, vcc, 0, v181, vcc
	v_add_co_u32_e32 v182, vcc, 0x1000, v182
	s_nop 1
	v_addc_co_u32_e32 v183, vcc, 0, v183, vcc
	global_load_dwordx4 v[68:71], v[72:73], off
	v_mfma_f32_32x32x16_bf16 v[4:19], v[152:155], v[156:159], v[4:19]
	ds_read_b128 v[144:147], v186 offset:36928
	ds_read_b128 v[148:151], v187 offset:55360
	s_waitcnt lgkmcnt(7)
	v_mfma_f32_32x32x16_bf16 v[52:67], v[164:167], v[160:163], v[52:67]
	ds_read_b128 v[152:155], v187 offset:59968
	ds_read_b128 v[156:159], v186 offset:41536
	s_waitcnt lgkmcnt(8)
	v_mfma_f32_32x32x16_bf16 v[36:51], v[168:171], v[160:163], v[36:51]
	s_waitcnt vmcnt(13)
	ds_write_b128 v184, v[84:87] offset:13824
	global_load_dwordx4 v[76:79], v[74:75], off
	s_waitcnt lgkmcnt(8)
	v_mfma_f32_32x32x16_bf16 v[20:35], v[164:167], v[172:175], v[20:35]
	s_waitcnt vmcnt(13)
	ds_write_b128 v184, v[88:91] offset:18432
	global_load_dwordx4 v[80:83], v[106:107], off
	v_mfma_f32_32x32x16_bf16 v[4:19], v[168:171], v[172:175], v[4:19]
	ds_read_b128 v[160:163], v186 offset:36960
	ds_read_b128 v[164:167], v187 offset:55392
	s_waitcnt lgkmcnt(6)
	v_mfma_f32_32x32x16_bf16 v[52:67], v[148:151], v[144:147], v[52:67]
	ds_read_b128 v[168:171], v187 offset:60000
	ds_read_b128 v[172:175], v186 offset:41568
	s_waitcnt lgkmcnt(7)
	v_mfma_f32_32x32x16_bf16 v[36:51], v[152:155], v[144:147], v[36:51]
	s_waitcnt vmcnt(13)
	ds_write_b128 v184, v[92:95] offset:23040
	global_load_dwordx4 v[84:87], v[176:177], off
	s_waitcnt lgkmcnt(7)
	v_mfma_f32_32x32x16_bf16 v[20:35], v[148:151], v[156:159], v[20:35]
	s_waitcnt vmcnt(13)
	ds_write_b128 v184, v[96:99] offset:27648
	global_load_dwordx4 v[88:91], v[104:105], off
	v_mfma_f32_32x32x16_bf16 v[4:19], v[152:155], v[156:159], v[4:19]
	s_waitcnt vmcnt(13)
	ds_write_b128 v184, v[100:103] offset:32256
	global_load_dwordx4 v[92:95], v[178:179], off
	s_waitcnt lgkmcnt(5)
	v_mfma_f32_32x32x16_bf16 v[52:67], v[164:167], v[160:163], v[52:67]
	global_load_dwordx4 v[96:99], v[180:181], off
	s_waitcnt lgkmcnt(4)
	v_mfma_f32_32x32x16_bf16 v[36:51], v[168:171], v[160:163], v[36:51]
	global_load_dwordx4 v[100:103], v[182:183], off
	s_waitcnt lgkmcnt(3)
	v_mfma_f32_32x32x16_bf16 v[20:35], v[164:167], v[172:175], v[20:35]
	v_mfma_f32_32x32x16_bf16 v[4:19], v[168:171], v[172:175], v[4:19]
	s_setprio 0
	s_waitcnt lgkmcnt(0)
	s_barrier
	ds_read_b128 v[144:147], v186
	ds_read_b128 v[148:151], v187 offset:18432
	ds_read_b128 v[152:155], v187 offset:23040
	ds_read_b128 v[156:159], v186 offset:4608
	ds_read_b128 v[160:163], v186 offset:32
	ds_read_b128 v[164:167], v187 offset:18464
	ds_read_b128 v[168:171], v187 offset:23072
	ds_read_b128 v[172:175], v186 offset:4640
	s_setprio 1
	s_waitcnt lgkmcnt(6)
	v_mfma_f32_32x32x16_bf16 v[52:67], v[148:151], v[144:147], v[52:67]
	s_waitcnt vmcnt(15)
	ds_write_b128 v185, v[108:111]
	s_waitcnt lgkmcnt(6)
	v_mfma_f32_32x32x16_bf16 v[36:51], v[152:155], v[144:147], v[36:51]
	s_waitcnt vmcnt(14)
	ds_write_b128 v185, v[112:115] offset:4608
	s_waitcnt lgkmcnt(6)
	v_mfma_f32_32x32x16_bf16 v[20:35], v[148:151], v[156:159], v[20:35]
	s_waitcnt vmcnt(13)
	ds_write_b128 v185, v[116:119] offset:9216
	global_load_dwordx4 v[108:111], v[72:73], off offset:128
	v_mfma_f32_32x32x16_bf16 v[4:19], v[152:155], v[156:159], v[4:19]
	ds_read_b128 v[144:147], v186 offset:64
	ds_read_b128 v[148:151], v187 offset:18496
	s_waitcnt lgkmcnt(7)
	v_mfma_f32_32x32x16_bf16 v[52:67], v[164:167], v[160:163], v[52:67]
	ds_read_b128 v[152:155], v187 offset:23104
	ds_read_b128 v[156:159], v186 offset:4672
	s_waitcnt lgkmcnt(8)
	v_mfma_f32_32x32x16_bf16 v[36:51], v[168:171], v[160:163], v[36:51]
	s_waitcnt vmcnt(13)
	ds_write_b128 v185, v[120:123] offset:13824
	global_load_dwordx4 v[112:115], v[74:75], off offset:128
	s_waitcnt lgkmcnt(8)
	v_mfma_f32_32x32x16_bf16 v[20:35], v[164:167], v[172:175], v[20:35]
	s_waitcnt vmcnt(13)
	ds_write_b128 v185, v[124:127] offset:18432
	global_load_dwordx4 v[116:119], v[106:107], off offset:128
	v_mfma_f32_32x32x16_bf16 v[4:19], v[168:171], v[172:175], v[4:19]
	ds_read_b128 v[160:163], v186 offset:96
	ds_read_b128 v[164:167], v187 offset:18528
	s_waitcnt lgkmcnt(6)
	v_mfma_f32_32x32x16_bf16 v[52:67], v[148:151], v[144:147], v[52:67]
	ds_read_b128 v[168:171], v187 offset:23136
	ds_read_b128 v[172:175], v186 offset:4704
	s_waitcnt lgkmcnt(7)
	v_mfma_f32_32x32x16_bf16 v[36:51], v[152:155], v[144:147], v[36:51]
	s_waitcnt vmcnt(13)
	ds_write_b128 v185, v[128:131] offset:23040
	global_load_dwordx4 v[120:123], v[176:177], off offset:128
	s_waitcnt lgkmcnt(7)
	v_mfma_f32_32x32x16_bf16 v[20:35], v[148:151], v[156:159], v[20:35]
	s_waitcnt vmcnt(13)
	ds_write_b128 v185, v[136:139] offset:27648
	global_load_dwordx4 v[124:127], v[104:105], off offset:128
	v_mfma_f32_32x32x16_bf16 v[4:19], v[152:155], v[156:159], v[4:19]
	s_waitcnt vmcnt(13)
	ds_write_b128 v185, v[140:143] offset:32256
	global_load_dwordx4 v[128:131], v[178:179], off offset:128
	s_waitcnt lgkmcnt(5)
	v_mfma_f32_32x32x16_bf16 v[52:67], v[164:167], v[160:163], v[52:67]
	global_load_dwordx4 v[136:139], v[180:181], off offset:128
	s_waitcnt lgkmcnt(4)
	v_mfma_f32_32x32x16_bf16 v[36:51], v[168:171], v[160:163], v[36:51]
	global_load_dwordx4 v[140:143], v[182:183], off offset:128
	s_waitcnt lgkmcnt(3)
	v_mfma_f32_32x32x16_bf16 v[20:35], v[164:167], v[172:175], v[20:35]
	v_mfma_f32_32x32x16_bf16 v[4:19], v[168:171], v[172:175], v[4:19]
	s_setprio 0
	s_waitcnt lgkmcnt(0)
	s_barrier
	ds_read_b128 v[144:147], v186 offset:36864
	ds_read_b128 v[148:151], v187 offset:55296
	ds_read_b128 v[152:155], v187 offset:59904
	ds_read_b128 v[156:159], v186 offset:41472
	ds_read_b128 v[160:163], v186 offset:36896
	ds_read_b128 v[164:167], v187 offset:55328
	ds_read_b128 v[168:171], v187 offset:59936
	ds_read_b128 v[172:175], v186 offset:41504
	s_setprio 1
	s_waitcnt lgkmcnt(6)
	v_mfma_f32_32x32x16_bf16 v[52:67], v[148:151], v[144:147], v[52:67]
	s_waitcnt vmcnt(15)
	ds_write_b128 v184, v[68:71]
	s_waitcnt lgkmcnt(6)
	v_mfma_f32_32x32x16_bf16 v[36:51], v[152:155], v[144:147], v[36:51]
	s_waitcnt vmcnt(14)
	ds_write_b128 v184, v[76:79] offset:4608
	s_waitcnt lgkmcnt(6)
	v_mfma_f32_32x32x16_bf16 v[20:35], v[148:151], v[156:159], v[20:35]
	s_waitcnt vmcnt(13)
	ds_write_b128 v184, v[80:83] offset:9216
	global_load_dwordx4 v[68:71], v[72:73], off offset:256
	v_mfma_f32_32x32x16_bf16 v[4:19], v[152:155], v[156:159], v[4:19]
	ds_read_b128 v[144:147], v186 offset:36928
	ds_read_b128 v[148:151], v187 offset:55360
	s_waitcnt lgkmcnt(7)
	v_mfma_f32_32x32x16_bf16 v[52:67], v[164:167], v[160:163], v[52:67]
	ds_read_b128 v[152:155], v187 offset:59968
	ds_read_b128 v[156:159], v186 offset:41536
	s_waitcnt lgkmcnt(8)
	v_mfma_f32_32x32x16_bf16 v[36:51], v[168:171], v[160:163], v[36:51]
	s_waitcnt vmcnt(13)
	ds_write_b128 v184, v[84:87] offset:13824
	global_load_dwordx4 v[76:79], v[74:75], off offset:256
	s_waitcnt lgkmcnt(8)
	v_mfma_f32_32x32x16_bf16 v[20:35], v[164:167], v[172:175], v[20:35]
	s_waitcnt vmcnt(13)
	ds_write_b128 v184, v[88:91] offset:18432
	global_load_dwordx4 v[80:83], v[106:107], off offset:256
	v_mfma_f32_32x32x16_bf16 v[4:19], v[168:171], v[172:175], v[4:19]
	ds_read_b128 v[160:163], v186 offset:36960
	ds_read_b128 v[164:167], v187 offset:55392
	s_waitcnt lgkmcnt(6)
	v_mfma_f32_32x32x16_bf16 v[52:67], v[148:151], v[144:147], v[52:67]
	ds_read_b128 v[168:171], v187 offset:60000
	ds_read_b128 v[172:175], v186 offset:41568
	s_waitcnt lgkmcnt(7)
	v_mfma_f32_32x32x16_bf16 v[36:51], v[152:155], v[144:147], v[36:51]
	s_waitcnt vmcnt(13)
	ds_write_b128 v184, v[92:95] offset:23040
	global_load_dwordx4 v[84:87], v[176:177], off offset:256
	s_waitcnt lgkmcnt(7)
	v_mfma_f32_32x32x16_bf16 v[20:35], v[148:151], v[156:159], v[20:35]
	s_waitcnt vmcnt(13)
	ds_write_b128 v184, v[96:99] offset:27648
	global_load_dwordx4 v[88:91], v[104:105], off offset:256
	v_mfma_f32_32x32x16_bf16 v[4:19], v[152:155], v[156:159], v[4:19]
	s_waitcnt vmcnt(13)
	ds_write_b128 v184, v[100:103] offset:32256
	global_load_dwordx4 v[92:95], v[178:179], off offset:256
	s_waitcnt lgkmcnt(5)
	v_mfma_f32_32x32x16_bf16 v[52:67], v[164:167], v[160:163], v[52:67]
	global_load_dwordx4 v[96:99], v[180:181], off offset:256
	s_waitcnt lgkmcnt(4)
	v_mfma_f32_32x32x16_bf16 v[36:51], v[168:171], v[160:163], v[36:51]
	global_load_dwordx4 v[100:103], v[182:183], off offset:256
	s_waitcnt lgkmcnt(3)
	v_mfma_f32_32x32x16_bf16 v[20:35], v[164:167], v[172:175], v[20:35]
	v_mfma_f32_32x32x16_bf16 v[4:19], v[168:171], v[172:175], v[4:19]
	s_setprio 0
	s_waitcnt lgkmcnt(0)
	s_barrier
	ds_read_b128 v[144:147], v186
	ds_read_b128 v[148:151], v187 offset:18432
	ds_read_b128 v[152:155], v187 offset:23040
	ds_read_b128 v[156:159], v186 offset:4608
	ds_read_b128 v[160:163], v186 offset:32
	ds_read_b128 v[164:167], v187 offset:18464
	ds_read_b128 v[168:171], v187 offset:23072
	ds_read_b128 v[172:175], v186 offset:4640
	s_setprio 1
	s_waitcnt lgkmcnt(6)
	v_mfma_f32_32x32x16_bf16 v[52:67], v[148:151], v[144:147], v[52:67]
	s_waitcnt vmcnt(15)
	ds_write_b128 v185, v[108:111]
	s_waitcnt lgkmcnt(6)
	v_mfma_f32_32x32x16_bf16 v[36:51], v[152:155], v[144:147], v[36:51]
	s_waitcnt vmcnt(14)
	ds_write_b128 v185, v[112:115] offset:4608
	s_waitcnt lgkmcnt(6)
	v_mfma_f32_32x32x16_bf16 v[20:35], v[148:151], v[156:159], v[20:35]
	s_waitcnt vmcnt(13)
	ds_write_b128 v185, v[116:119] offset:9216
	global_load_dwordx4 v[108:111], v[72:73], off offset:384
	v_mfma_f32_32x32x16_bf16 v[4:19], v[152:155], v[156:159], v[4:19]
	ds_read_b128 v[144:147], v186 offset:64
	ds_read_b128 v[148:151], v187 offset:18496
	s_waitcnt lgkmcnt(7)
	v_mfma_f32_32x32x16_bf16 v[52:67], v[164:167], v[160:163], v[52:67]
	ds_read_b128 v[152:155], v187 offset:23104
	ds_read_b128 v[156:159], v186 offset:4672
	s_waitcnt lgkmcnt(8)
	v_mfma_f32_32x32x16_bf16 v[36:51], v[168:171], v[160:163], v[36:51]
	s_waitcnt vmcnt(13)
	ds_write_b128 v185, v[120:123] offset:13824
	global_load_dwordx4 v[112:115], v[74:75], off offset:384
	s_waitcnt lgkmcnt(8)
	v_mfma_f32_32x32x16_bf16 v[20:35], v[164:167], v[172:175], v[20:35]
	s_waitcnt vmcnt(13)
	ds_write_b128 v185, v[124:127] offset:18432
	global_load_dwordx4 v[116:119], v[106:107], off offset:384
	v_mfma_f32_32x32x16_bf16 v[4:19], v[168:171], v[172:175], v[4:19]
	ds_read_b128 v[160:163], v186 offset:96
	ds_read_b128 v[164:167], v187 offset:18528
	s_waitcnt lgkmcnt(6)
	v_mfma_f32_32x32x16_bf16 v[52:67], v[148:151], v[144:147], v[52:67]
	ds_read_b128 v[168:171], v187 offset:23136
	ds_read_b128 v[172:175], v186 offset:4704
	s_waitcnt lgkmcnt(7)
	v_mfma_f32_32x32x16_bf16 v[36:51], v[152:155], v[144:147], v[36:51]
	s_waitcnt vmcnt(13)
	ds_write_b128 v185, v[128:131] offset:23040
	global_load_dwordx4 v[120:123], v[176:177], off offset:384
	s_waitcnt lgkmcnt(7)
	v_mfma_f32_32x32x16_bf16 v[20:35], v[148:151], v[156:159], v[20:35]
	s_waitcnt vmcnt(13)
	ds_write_b128 v185, v[136:139] offset:27648
	global_load_dwordx4 v[124:127], v[104:105], off offset:384
	v_mfma_f32_32x32x16_bf16 v[4:19], v[152:155], v[156:159], v[4:19]
	s_waitcnt vmcnt(13)
	ds_write_b128 v185, v[140:143] offset:32256
	global_load_dwordx4 v[128:131], v[178:179], off offset:384
	s_waitcnt lgkmcnt(5)
	v_mfma_f32_32x32x16_bf16 v[52:67], v[164:167], v[160:163], v[52:67]
	global_load_dwordx4 v[136:139], v[180:181], off offset:384
	s_waitcnt lgkmcnt(4)
	v_mfma_f32_32x32x16_bf16 v[36:51], v[168:171], v[160:163], v[36:51]
	global_load_dwordx4 v[140:143], v[182:183], off offset:384
	s_waitcnt lgkmcnt(3)
	v_mfma_f32_32x32x16_bf16 v[20:35], v[164:167], v[172:175], v[20:35]
	v_mfma_f32_32x32x16_bf16 v[4:19], v[168:171], v[172:175], v[4:19]
	s_setprio 0
	s_waitcnt lgkmcnt(0)
	s_barrier
	ds_read_b128 v[144:147], v186 offset:36864
	ds_read_b128 v[148:151], v187 offset:55296
	ds_read_b128 v[152:155], v187 offset:59904
	ds_read_b128 v[156:159], v186 offset:41472
	ds_read_b128 v[160:163], v186 offset:36896
	ds_read_b128 v[164:167], v187 offset:55328
	ds_read_b128 v[168:171], v187 offset:59936
	ds_read_b128 v[172:175], v186 offset:41504
	s_setprio 1
	s_waitcnt lgkmcnt(6)
	v_mfma_f32_32x32x16_bf16 v[52:67], v[148:151], v[144:147], v[52:67]
	s_waitcnt vmcnt(15)
	ds_write_b128 v184, v[68:71]
	s_waitcnt lgkmcnt(6)
	v_mfma_f32_32x32x16_bf16 v[36:51], v[152:155], v[144:147], v[36:51]
	s_waitcnt vmcnt(14)
	ds_write_b128 v184, v[76:79] offset:4608
	s_waitcnt lgkmcnt(6)
	v_mfma_f32_32x32x16_bf16 v[20:35], v[148:151], v[156:159], v[20:35]
	s_waitcnt vmcnt(13)
	ds_write_b128 v184, v[80:83] offset:9216
	global_load_dwordx4 v[68:71], v[72:73], off offset:512
	v_mfma_f32_32x32x16_bf16 v[4:19], v[152:155], v[156:159], v[4:19]
	ds_read_b128 v[144:147], v186 offset:36928
	ds_read_b128 v[148:151], v187 offset:55360
	s_waitcnt lgkmcnt(7)
	v_mfma_f32_32x32x16_bf16 v[52:67], v[164:167], v[160:163], v[52:67]
	ds_read_b128 v[152:155], v187 offset:59968
	ds_read_b128 v[156:159], v186 offset:41536
	s_waitcnt lgkmcnt(8)
	v_mfma_f32_32x32x16_bf16 v[36:51], v[168:171], v[160:163], v[36:51]
	s_waitcnt vmcnt(13)
	ds_write_b128 v184, v[84:87] offset:13824
	global_load_dwordx4 v[76:79], v[74:75], off offset:512
	s_waitcnt lgkmcnt(8)
	v_mfma_f32_32x32x16_bf16 v[20:35], v[164:167], v[172:175], v[20:35]
	s_waitcnt vmcnt(13)
	ds_write_b128 v184, v[88:91] offset:18432
	global_load_dwordx4 v[80:83], v[106:107], off offset:512
	v_mfma_f32_32x32x16_bf16 v[4:19], v[168:171], v[172:175], v[4:19]
	ds_read_b128 v[160:163], v186 offset:36960
	ds_read_b128 v[164:167], v187 offset:55392
	s_waitcnt lgkmcnt(6)
	v_mfma_f32_32x32x16_bf16 v[52:67], v[148:151], v[144:147], v[52:67]
	ds_read_b128 v[168:171], v187 offset:60000
	ds_read_b128 v[172:175], v186 offset:41568
	s_waitcnt lgkmcnt(7)
	v_mfma_f32_32x32x16_bf16 v[36:51], v[152:155], v[144:147], v[36:51]
	s_waitcnt vmcnt(13)
	ds_write_b128 v184, v[92:95] offset:23040
	global_load_dwordx4 v[84:87], v[176:177], off offset:512
	s_waitcnt lgkmcnt(7)
	v_mfma_f32_32x32x16_bf16 v[20:35], v[148:151], v[156:159], v[20:35]
	s_waitcnt vmcnt(13)
	ds_write_b128 v184, v[96:99] offset:27648
	global_load_dwordx4 v[88:91], v[104:105], off offset:512
	v_mfma_f32_32x32x16_bf16 v[4:19], v[152:155], v[156:159], v[4:19]
	s_waitcnt vmcnt(13)
	ds_write_b128 v184, v[100:103] offset:32256
	global_load_dwordx4 v[92:95], v[178:179], off offset:512
	s_waitcnt lgkmcnt(5)
	v_mfma_f32_32x32x16_bf16 v[52:67], v[164:167], v[160:163], v[52:67]
	global_load_dwordx4 v[96:99], v[180:181], off offset:512
	s_waitcnt lgkmcnt(4)
	v_mfma_f32_32x32x16_bf16 v[36:51], v[168:171], v[160:163], v[36:51]
	global_load_dwordx4 v[100:103], v[182:183], off offset:512
	s_waitcnt lgkmcnt(3)
	v_mfma_f32_32x32x16_bf16 v[20:35], v[164:167], v[172:175], v[20:35]
	v_mfma_f32_32x32x16_bf16 v[4:19], v[168:171], v[172:175], v[4:19]
	s_setprio 0
	s_waitcnt lgkmcnt(0)
	s_barrier
	ds_read_b128 v[144:147], v186
	ds_read_b128 v[148:151], v187 offset:18432
	ds_read_b128 v[152:155], v187 offset:23040
	ds_read_b128 v[156:159], v186 offset:4608
	ds_read_b128 v[160:163], v186 offset:32
	ds_read_b128 v[164:167], v187 offset:18464
	ds_read_b128 v[168:171], v187 offset:23072
	ds_read_b128 v[172:175], v186 offset:4640
	s_setprio 1
	s_waitcnt lgkmcnt(6)
	v_mfma_f32_32x32x16_bf16 v[52:67], v[148:151], v[144:147], v[52:67]
	s_waitcnt vmcnt(15)
	ds_write_b128 v185, v[108:111]
	s_waitcnt lgkmcnt(6)
	v_mfma_f32_32x32x16_bf16 v[36:51], v[152:155], v[144:147], v[36:51]
	s_waitcnt vmcnt(14)
	ds_write_b128 v185, v[112:115] offset:4608
	s_waitcnt lgkmcnt(6)
	v_mfma_f32_32x32x16_bf16 v[20:35], v[148:151], v[156:159], v[20:35]
	s_waitcnt vmcnt(13)
	ds_write_b128 v185, v[116:119] offset:9216
	global_load_dwordx4 v[108:111], v[72:73], off offset:640
	v_mfma_f32_32x32x16_bf16 v[4:19], v[152:155], v[156:159], v[4:19]
	ds_read_b128 v[144:147], v186 offset:64
	ds_read_b128 v[148:151], v187 offset:18496
	s_waitcnt lgkmcnt(7)
	v_mfma_f32_32x32x16_bf16 v[52:67], v[164:167], v[160:163], v[52:67]
	ds_read_b128 v[152:155], v187 offset:23104
	ds_read_b128 v[156:159], v186 offset:4672
	s_waitcnt lgkmcnt(8)
	v_mfma_f32_32x32x16_bf16 v[36:51], v[168:171], v[160:163], v[36:51]
	s_waitcnt vmcnt(13)
	ds_write_b128 v185, v[120:123] offset:13824
	global_load_dwordx4 v[112:115], v[74:75], off offset:640
	s_waitcnt lgkmcnt(8)
	v_mfma_f32_32x32x16_bf16 v[20:35], v[164:167], v[172:175], v[20:35]
	s_waitcnt vmcnt(13)
	ds_write_b128 v185, v[124:127] offset:18432
	global_load_dwordx4 v[116:119], v[106:107], off offset:640
	v_mfma_f32_32x32x16_bf16 v[4:19], v[168:171], v[172:175], v[4:19]
	ds_read_b128 v[160:163], v186 offset:96
	ds_read_b128 v[164:167], v187 offset:18528
	s_waitcnt lgkmcnt(6)
	v_mfma_f32_32x32x16_bf16 v[52:67], v[148:151], v[144:147], v[52:67]
	ds_read_b128 v[168:171], v187 offset:23136
	ds_read_b128 v[172:175], v186 offset:4704
	s_waitcnt lgkmcnt(7)
	v_mfma_f32_32x32x16_bf16 v[36:51], v[152:155], v[144:147], v[36:51]
	s_waitcnt vmcnt(13)
	ds_write_b128 v185, v[128:131] offset:23040
	global_load_dwordx4 v[120:123], v[176:177], off offset:640
	s_waitcnt lgkmcnt(7)
	v_mfma_f32_32x32x16_bf16 v[20:35], v[148:151], v[156:159], v[20:35]
	s_waitcnt vmcnt(13)
	ds_write_b128 v185, v[136:139] offset:27648
	global_load_dwordx4 v[124:127], v[104:105], off offset:640
	v_mfma_f32_32x32x16_bf16 v[4:19], v[152:155], v[156:159], v[4:19]
	s_waitcnt vmcnt(13)
	ds_write_b128 v185, v[140:143] offset:32256
	global_load_dwordx4 v[128:131], v[178:179], off offset:640
	s_waitcnt lgkmcnt(5)
	v_mfma_f32_32x32x16_bf16 v[52:67], v[164:167], v[160:163], v[52:67]
	global_load_dwordx4 v[136:139], v[180:181], off offset:640
	s_waitcnt lgkmcnt(4)
	v_mfma_f32_32x32x16_bf16 v[36:51], v[168:171], v[160:163], v[36:51]
	global_load_dwordx4 v[140:143], v[182:183], off offset:640
	s_waitcnt lgkmcnt(3)
	v_mfma_f32_32x32x16_bf16 v[20:35], v[164:167], v[172:175], v[20:35]
	v_mfma_f32_32x32x16_bf16 v[4:19], v[168:171], v[172:175], v[4:19]
	s_setprio 0
	s_waitcnt lgkmcnt(0)
	s_barrier
	ds_read_b128 v[144:147], v186 offset:36864
	ds_read_b128 v[148:151], v187 offset:55296
	ds_read_b128 v[152:155], v187 offset:59904
	ds_read_b128 v[156:159], v186 offset:41472
	ds_read_b128 v[160:163], v186 offset:36896
	ds_read_b128 v[164:167], v187 offset:55328
	ds_read_b128 v[168:171], v187 offset:59936
	ds_read_b128 v[172:175], v186 offset:41504
	s_setprio 1
	s_waitcnt lgkmcnt(6)
	v_mfma_f32_32x32x16_bf16 v[52:67], v[148:151], v[144:147], v[52:67]
	s_waitcnt vmcnt(15)
	ds_write_b128 v184, v[68:71]
	s_waitcnt lgkmcnt(6)
	v_mfma_f32_32x32x16_bf16 v[36:51], v[152:155], v[144:147], v[36:51]
	s_waitcnt vmcnt(14)
	ds_write_b128 v184, v[76:79] offset:4608
	s_waitcnt lgkmcnt(6)
	v_mfma_f32_32x32x16_bf16 v[20:35], v[148:151], v[156:159], v[20:35]
	s_waitcnt vmcnt(13)
	ds_write_b128 v184, v[80:83] offset:9216
	global_load_dwordx4 v[68:71], v[72:73], off offset:768
	v_mfma_f32_32x32x16_bf16 v[4:19], v[152:155], v[156:159], v[4:19]
	ds_read_b128 v[144:147], v186 offset:36928
	ds_read_b128 v[148:151], v187 offset:55360
	s_waitcnt lgkmcnt(7)
	v_mfma_f32_32x32x16_bf16 v[52:67], v[164:167], v[160:163], v[52:67]
	ds_read_b128 v[152:155], v187 offset:59968
	ds_read_b128 v[156:159], v186 offset:41536
	s_waitcnt lgkmcnt(8)
	v_mfma_f32_32x32x16_bf16 v[36:51], v[168:171], v[160:163], v[36:51]
	s_waitcnt vmcnt(13)
	ds_write_b128 v184, v[84:87] offset:13824
	global_load_dwordx4 v[76:79], v[74:75], off offset:768
	s_waitcnt lgkmcnt(8)
	v_mfma_f32_32x32x16_bf16 v[20:35], v[164:167], v[172:175], v[20:35]
	s_waitcnt vmcnt(13)
	ds_write_b128 v184, v[88:91] offset:18432
	global_load_dwordx4 v[80:83], v[106:107], off offset:768
	v_mfma_f32_32x32x16_bf16 v[4:19], v[168:171], v[172:175], v[4:19]
	ds_read_b128 v[160:163], v186 offset:36960
	ds_read_b128 v[164:167], v187 offset:55392
	s_waitcnt lgkmcnt(6)
	v_mfma_f32_32x32x16_bf16 v[52:67], v[148:151], v[144:147], v[52:67]
	ds_read_b128 v[168:171], v187 offset:60000
	ds_read_b128 v[172:175], v186 offset:41568
	s_waitcnt lgkmcnt(7)
	v_mfma_f32_32x32x16_bf16 v[36:51], v[152:155], v[144:147], v[36:51]
	s_waitcnt vmcnt(13)
	ds_write_b128 v184, v[92:95] offset:23040
	global_load_dwordx4 v[84:87], v[176:177], off offset:768
	s_waitcnt lgkmcnt(7)
	v_mfma_f32_32x32x16_bf16 v[20:35], v[148:151], v[156:159], v[20:35]
	s_waitcnt vmcnt(13)
	ds_write_b128 v184, v[96:99] offset:27648
	global_load_dwordx4 v[88:91], v[104:105], off offset:768
	v_mfma_f32_32x32x16_bf16 v[4:19], v[152:155], v[156:159], v[4:19]
	s_waitcnt vmcnt(13)
	ds_write_b128 v184, v[100:103] offset:32256
	global_load_dwordx4 v[92:95], v[178:179], off offset:768
	s_waitcnt lgkmcnt(5)
	v_mfma_f32_32x32x16_bf16 v[52:67], v[164:167], v[160:163], v[52:67]
	global_load_dwordx4 v[96:99], v[180:181], off offset:768
	s_waitcnt lgkmcnt(4)
	v_mfma_f32_32x32x16_bf16 v[36:51], v[168:171], v[160:163], v[36:51]
	global_load_dwordx4 v[100:103], v[182:183], off offset:768
	s_waitcnt lgkmcnt(3)
	v_mfma_f32_32x32x16_bf16 v[20:35], v[164:167], v[172:175], v[20:35]
	v_mfma_f32_32x32x16_bf16 v[4:19], v[168:171], v[172:175], v[4:19]
	s_setprio 0
	s_waitcnt lgkmcnt(0)
	s_barrier
	ds_read_b128 v[144:147], v186
	ds_read_b128 v[148:151], v187 offset:18432
	ds_read_b128 v[152:155], v187 offset:23040
	ds_read_b128 v[156:159], v186 offset:4608
	ds_read_b128 v[160:163], v186 offset:32
	ds_read_b128 v[164:167], v187 offset:18464
	ds_read_b128 v[168:171], v187 offset:23072
	ds_read_b128 v[172:175], v186 offset:4640
	s_setprio 1
	s_waitcnt lgkmcnt(6)
	v_mfma_f32_32x32x16_bf16 v[52:67], v[148:151], v[144:147], v[52:67]
	s_waitcnt vmcnt(15)
	ds_write_b128 v185, v[108:111]
	s_waitcnt lgkmcnt(6)
	v_mfma_f32_32x32x16_bf16 v[36:51], v[152:155], v[144:147], v[36:51]
	s_waitcnt vmcnt(14)
	ds_write_b128 v185, v[112:115] offset:4608
	s_waitcnt lgkmcnt(6)
	v_mfma_f32_32x32x16_bf16 v[20:35], v[148:151], v[156:159], v[20:35]
	s_waitcnt vmcnt(13)
	ds_write_b128 v185, v[116:119] offset:9216
	global_load_dwordx4 v[108:111], v[72:73], off offset:896
	v_mfma_f32_32x32x16_bf16 v[4:19], v[152:155], v[156:159], v[4:19]
	ds_read_b128 v[144:147], v186 offset:64
	ds_read_b128 v[148:151], v187 offset:18496
	s_waitcnt lgkmcnt(7)
	v_mfma_f32_32x32x16_bf16 v[52:67], v[164:167], v[160:163], v[52:67]
	ds_read_b128 v[152:155], v187 offset:23104
	ds_read_b128 v[156:159], v186 offset:4672
	s_waitcnt lgkmcnt(8)
	v_mfma_f32_32x32x16_bf16 v[36:51], v[168:171], v[160:163], v[36:51]
	s_waitcnt vmcnt(13)
	ds_write_b128 v185, v[120:123] offset:13824
	global_load_dwordx4 v[112:115], v[74:75], off offset:896
	s_waitcnt lgkmcnt(8)
	v_mfma_f32_32x32x16_bf16 v[20:35], v[164:167], v[172:175], v[20:35]
	s_waitcnt vmcnt(13)
	ds_write_b128 v185, v[124:127] offset:18432
	global_load_dwordx4 v[116:119], v[106:107], off offset:896
	v_mfma_f32_32x32x16_bf16 v[4:19], v[168:171], v[172:175], v[4:19]
	ds_read_b128 v[160:163], v186 offset:96
	ds_read_b128 v[164:167], v187 offset:18528
	s_waitcnt lgkmcnt(6)
	v_mfma_f32_32x32x16_bf16 v[52:67], v[148:151], v[144:147], v[52:67]
	ds_read_b128 v[168:171], v187 offset:23136
	ds_read_b128 v[172:175], v186 offset:4704
	s_waitcnt lgkmcnt(7)
	v_mfma_f32_32x32x16_bf16 v[36:51], v[152:155], v[144:147], v[36:51]
	s_waitcnt vmcnt(13)
	ds_write_b128 v185, v[128:131] offset:23040
	global_load_dwordx4 v[120:123], v[176:177], off offset:896
	s_waitcnt lgkmcnt(7)
	v_mfma_f32_32x32x16_bf16 v[20:35], v[148:151], v[156:159], v[20:35]
	s_waitcnt vmcnt(13)
	ds_write_b128 v185, v[136:139] offset:27648
	global_load_dwordx4 v[124:127], v[104:105], off offset:896
	v_mfma_f32_32x32x16_bf16 v[4:19], v[152:155], v[156:159], v[4:19]
	s_waitcnt vmcnt(13)
	ds_write_b128 v185, v[140:143] offset:32256
	global_load_dwordx4 v[128:131], v[178:179], off offset:896
	s_waitcnt lgkmcnt(5)
	v_mfma_f32_32x32x16_bf16 v[52:67], v[164:167], v[160:163], v[52:67]
	global_load_dwordx4 v[136:139], v[180:181], off offset:896
	s_waitcnt lgkmcnt(4)
	v_mfma_f32_32x32x16_bf16 v[36:51], v[168:171], v[160:163], v[36:51]
	global_load_dwordx4 v[140:143], v[182:183], off offset:896
	s_waitcnt lgkmcnt(3)
	v_mfma_f32_32x32x16_bf16 v[20:35], v[164:167], v[172:175], v[20:35]
	v_mfma_f32_32x32x16_bf16 v[4:19], v[168:171], v[172:175], v[4:19]
	s_setprio 0
	s_waitcnt lgkmcnt(0)
	s_barrier
	ds_read_b128 v[144:147], v186 offset:36864
	ds_read_b128 v[148:151], v187 offset:55296
	ds_read_b128 v[152:155], v187 offset:59904
	ds_read_b128 v[156:159], v186 offset:41472
	ds_read_b128 v[160:163], v186 offset:36896
	ds_read_b128 v[164:167], v187 offset:55328
	ds_read_b128 v[168:171], v187 offset:59936
	ds_read_b128 v[172:175], v186 offset:41504
	s_setprio 1
	s_waitcnt lgkmcnt(6)
	v_mfma_f32_32x32x16_bf16 v[52:67], v[148:151], v[144:147], v[52:67]
	s_waitcnt vmcnt(15)
	ds_write_b128 v184, v[68:71]
	s_waitcnt lgkmcnt(6)
	v_mfma_f32_32x32x16_bf16 v[36:51], v[152:155], v[144:147], v[36:51]
	s_waitcnt vmcnt(14)
	ds_write_b128 v184, v[76:79] offset:4608
	s_waitcnt lgkmcnt(6)
	v_mfma_f32_32x32x16_bf16 v[20:35], v[148:151], v[156:159], v[20:35]
	s_waitcnt vmcnt(13)
	ds_write_b128 v184, v[80:83] offset:9216
	global_load_dwordx4 v[68:71], v[72:73], off offset:1024
	v_mfma_f32_32x32x16_bf16 v[4:19], v[152:155], v[156:159], v[4:19]
	ds_read_b128 v[144:147], v186 offset:36928
	ds_read_b128 v[148:151], v187 offset:55360
	s_waitcnt lgkmcnt(7)
	v_mfma_f32_32x32x16_bf16 v[52:67], v[164:167], v[160:163], v[52:67]
	ds_read_b128 v[152:155], v187 offset:59968
	ds_read_b128 v[156:159], v186 offset:41536
	s_waitcnt lgkmcnt(8)
	v_mfma_f32_32x32x16_bf16 v[36:51], v[168:171], v[160:163], v[36:51]
	s_waitcnt vmcnt(13)
	ds_write_b128 v184, v[84:87] offset:13824
	global_load_dwordx4 v[76:79], v[74:75], off offset:1024
	s_waitcnt lgkmcnt(8)
	v_mfma_f32_32x32x16_bf16 v[20:35], v[164:167], v[172:175], v[20:35]
	s_waitcnt vmcnt(13)
	ds_write_b128 v184, v[88:91] offset:18432
	global_load_dwordx4 v[80:83], v[106:107], off offset:1024
	v_mfma_f32_32x32x16_bf16 v[4:19], v[168:171], v[172:175], v[4:19]
	ds_read_b128 v[160:163], v186 offset:36960
	ds_read_b128 v[164:167], v187 offset:55392
	s_waitcnt lgkmcnt(6)
	v_mfma_f32_32x32x16_bf16 v[52:67], v[148:151], v[144:147], v[52:67]
	ds_read_b128 v[168:171], v187 offset:60000
	ds_read_b128 v[172:175], v186 offset:41568
	s_waitcnt lgkmcnt(7)
	v_mfma_f32_32x32x16_bf16 v[36:51], v[152:155], v[144:147], v[36:51]
	s_waitcnt vmcnt(13)
	ds_write_b128 v184, v[92:95] offset:23040
	global_load_dwordx4 v[84:87], v[176:177], off offset:1024
	s_waitcnt lgkmcnt(7)
	v_mfma_f32_32x32x16_bf16 v[20:35], v[148:151], v[156:159], v[20:35]
	s_waitcnt vmcnt(13)
	ds_write_b128 v184, v[96:99] offset:27648
	global_load_dwordx4 v[88:91], v[104:105], off offset:1024
	v_mfma_f32_32x32x16_bf16 v[4:19], v[152:155], v[156:159], v[4:19]
	s_waitcnt vmcnt(13)
	ds_write_b128 v184, v[100:103] offset:32256
	global_load_dwordx4 v[92:95], v[178:179], off offset:1024
	s_waitcnt lgkmcnt(5)
	v_mfma_f32_32x32x16_bf16 v[52:67], v[164:167], v[160:163], v[52:67]
	global_load_dwordx4 v[96:99], v[180:181], off offset:1024
	s_waitcnt lgkmcnt(4)
	v_mfma_f32_32x32x16_bf16 v[36:51], v[168:171], v[160:163], v[36:51]
	global_load_dwordx4 v[100:103], v[182:183], off offset:1024
	s_waitcnt lgkmcnt(3)
	v_mfma_f32_32x32x16_bf16 v[20:35], v[164:167], v[172:175], v[20:35]
	v_mfma_f32_32x32x16_bf16 v[4:19], v[168:171], v[172:175], v[4:19]
	s_setprio 0
	s_waitcnt lgkmcnt(0)
	s_barrier
	ds_read_b128 v[144:147], v186
	ds_read_b128 v[148:151], v187 offset:18432
	ds_read_b128 v[152:155], v187 offset:23040
	ds_read_b128 v[156:159], v186 offset:4608
	ds_read_b128 v[160:163], v186 offset:32
	ds_read_b128 v[164:167], v187 offset:18464
	ds_read_b128 v[168:171], v187 offset:23072
	ds_read_b128 v[172:175], v186 offset:4640
	s_setprio 1
	s_waitcnt lgkmcnt(6)
	v_mfma_f32_32x32x16_bf16 v[52:67], v[148:151], v[144:147], v[52:67]
	s_waitcnt vmcnt(15)
	ds_write_b128 v185, v[108:111]
	s_waitcnt lgkmcnt(6)
	v_mfma_f32_32x32x16_bf16 v[36:51], v[152:155], v[144:147], v[36:51]
	s_waitcnt vmcnt(14)
	ds_write_b128 v185, v[112:115] offset:4608
	s_waitcnt lgkmcnt(6)
	v_mfma_f32_32x32x16_bf16 v[20:35], v[148:151], v[156:159], v[20:35]
	s_waitcnt vmcnt(13)
	ds_write_b128 v185, v[116:119] offset:9216
	global_load_dwordx4 v[108:111], v[72:73], off offset:1152
	v_mfma_f32_32x32x16_bf16 v[4:19], v[152:155], v[156:159], v[4:19]
	ds_read_b128 v[144:147], v186 offset:64
	ds_read_b128 v[148:151], v187 offset:18496
	s_waitcnt lgkmcnt(7)
	v_mfma_f32_32x32x16_bf16 v[52:67], v[164:167], v[160:163], v[52:67]
	ds_read_b128 v[152:155], v187 offset:23104
	ds_read_b128 v[156:159], v186 offset:4672
	s_waitcnt lgkmcnt(8)
	v_mfma_f32_32x32x16_bf16 v[36:51], v[168:171], v[160:163], v[36:51]
	s_waitcnt vmcnt(13)
	ds_write_b128 v185, v[120:123] offset:13824
	global_load_dwordx4 v[112:115], v[74:75], off offset:1152
	s_waitcnt lgkmcnt(8)
	v_mfma_f32_32x32x16_bf16 v[20:35], v[164:167], v[172:175], v[20:35]
	s_waitcnt vmcnt(13)
	ds_write_b128 v185, v[124:127] offset:18432
	global_load_dwordx4 v[116:119], v[106:107], off offset:1152
	v_mfma_f32_32x32x16_bf16 v[4:19], v[168:171], v[172:175], v[4:19]
	ds_read_b128 v[160:163], v186 offset:96
	ds_read_b128 v[164:167], v187 offset:18528
	s_waitcnt lgkmcnt(6)
	v_mfma_f32_32x32x16_bf16 v[52:67], v[148:151], v[144:147], v[52:67]
	ds_read_b128 v[168:171], v187 offset:23136
	ds_read_b128 v[172:175], v186 offset:4704
	s_waitcnt lgkmcnt(7)
	v_mfma_f32_32x32x16_bf16 v[36:51], v[152:155], v[144:147], v[36:51]
	s_waitcnt vmcnt(13)
	ds_write_b128 v185, v[128:131] offset:23040
	global_load_dwordx4 v[120:123], v[176:177], off offset:1152
	s_waitcnt lgkmcnt(7)
	v_mfma_f32_32x32x16_bf16 v[20:35], v[148:151], v[156:159], v[20:35]
	s_waitcnt vmcnt(13)
	ds_write_b128 v185, v[136:139] offset:27648
	global_load_dwordx4 v[124:127], v[104:105], off offset:1152
	v_mfma_f32_32x32x16_bf16 v[4:19], v[152:155], v[156:159], v[4:19]
	s_waitcnt vmcnt(13)
	ds_write_b128 v185, v[140:143] offset:32256
	global_load_dwordx4 v[128:131], v[178:179], off offset:1152
	s_waitcnt lgkmcnt(5)
	v_mfma_f32_32x32x16_bf16 v[52:67], v[164:167], v[160:163], v[52:67]
	global_load_dwordx4 v[136:139], v[180:181], off offset:1152
	s_waitcnt lgkmcnt(4)
	v_mfma_f32_32x32x16_bf16 v[36:51], v[168:171], v[160:163], v[36:51]
	global_load_dwordx4 v[140:143], v[182:183], off offset:1152
	s_waitcnt lgkmcnt(3)
	v_mfma_f32_32x32x16_bf16 v[20:35], v[164:167], v[172:175], v[20:35]
	v_mfma_f32_32x32x16_bf16 v[4:19], v[168:171], v[172:175], v[4:19]
	s_setprio 0
	s_waitcnt lgkmcnt(0)
	s_barrier
	ds_read_b128 v[144:147], v186 offset:36864
	ds_read_b128 v[148:151], v187 offset:55296
	ds_read_b128 v[152:155], v187 offset:59904
	ds_read_b128 v[156:159], v186 offset:41472
	ds_read_b128 v[160:163], v186 offset:36896
	ds_read_b128 v[164:167], v187 offset:55328
	ds_read_b128 v[168:171], v187 offset:59936
	ds_read_b128 v[172:175], v186 offset:41504
	s_setprio 1
	s_waitcnt lgkmcnt(6)
	v_mfma_f32_32x32x16_bf16 v[52:67], v[148:151], v[144:147], v[52:67]
	s_waitcnt vmcnt(15)
	ds_write_b128 v184, v[68:71]
	s_waitcnt lgkmcnt(6)
	v_mfma_f32_32x32x16_bf16 v[36:51], v[152:155], v[144:147], v[36:51]
	s_waitcnt vmcnt(14)
	ds_write_b128 v184, v[76:79] offset:4608
	s_waitcnt lgkmcnt(6)
	v_mfma_f32_32x32x16_bf16 v[20:35], v[148:151], v[156:159], v[20:35]
	s_waitcnt vmcnt(13)
	ds_write_b128 v184, v[80:83] offset:9216
	global_load_dwordx4 v[68:71], v[72:73], off offset:1280
	v_mfma_f32_32x32x16_bf16 v[4:19], v[152:155], v[156:159], v[4:19]
	ds_read_b128 v[144:147], v186 offset:36928
	ds_read_b128 v[148:151], v187 offset:55360
	s_waitcnt lgkmcnt(7)
	v_mfma_f32_32x32x16_bf16 v[52:67], v[164:167], v[160:163], v[52:67]
	ds_read_b128 v[152:155], v187 offset:59968
	ds_read_b128 v[156:159], v186 offset:41536
	s_waitcnt lgkmcnt(8)
	v_mfma_f32_32x32x16_bf16 v[36:51], v[168:171], v[160:163], v[36:51]
	s_waitcnt vmcnt(13)
	ds_write_b128 v184, v[84:87] offset:13824
	global_load_dwordx4 v[76:79], v[74:75], off offset:1280
	s_waitcnt lgkmcnt(8)
	v_mfma_f32_32x32x16_bf16 v[20:35], v[164:167], v[172:175], v[20:35]
	s_waitcnt vmcnt(13)
	ds_write_b128 v184, v[88:91] offset:18432
	global_load_dwordx4 v[80:83], v[106:107], off offset:1280
	v_mfma_f32_32x32x16_bf16 v[4:19], v[168:171], v[172:175], v[4:19]
	ds_read_b128 v[160:163], v186 offset:36960
	ds_read_b128 v[164:167], v187 offset:55392
	s_waitcnt lgkmcnt(6)
	v_mfma_f32_32x32x16_bf16 v[52:67], v[148:151], v[144:147], v[52:67]
	ds_read_b128 v[168:171], v187 offset:60000
	ds_read_b128 v[172:175], v186 offset:41568
	s_waitcnt lgkmcnt(7)
	v_mfma_f32_32x32x16_bf16 v[36:51], v[152:155], v[144:147], v[36:51]
	s_waitcnt vmcnt(13)
	ds_write_b128 v184, v[92:95] offset:23040
	global_load_dwordx4 v[84:87], v[176:177], off offset:1280
	s_waitcnt lgkmcnt(7)
	v_mfma_f32_32x32x16_bf16 v[20:35], v[148:151], v[156:159], v[20:35]
	s_waitcnt vmcnt(13)
	ds_write_b128 v184, v[96:99] offset:27648
	global_load_dwordx4 v[88:91], v[104:105], off offset:1280
	v_mfma_f32_32x32x16_bf16 v[4:19], v[152:155], v[156:159], v[4:19]
	s_waitcnt vmcnt(13)
	ds_write_b128 v184, v[100:103] offset:32256
	global_load_dwordx4 v[92:95], v[178:179], off offset:1280
	s_waitcnt lgkmcnt(5)
	v_mfma_f32_32x32x16_bf16 v[52:67], v[164:167], v[160:163], v[52:67]
	global_load_dwordx4 v[96:99], v[180:181], off offset:1280
	s_waitcnt lgkmcnt(4)
	v_mfma_f32_32x32x16_bf16 v[36:51], v[168:171], v[160:163], v[36:51]
	global_load_dwordx4 v[100:103], v[182:183], off offset:1280
	s_waitcnt lgkmcnt(3)
	v_mfma_f32_32x32x16_bf16 v[20:35], v[164:167], v[172:175], v[20:35]
	v_mfma_f32_32x32x16_bf16 v[4:19], v[168:171], v[172:175], v[4:19]
	s_setprio 0
	s_waitcnt lgkmcnt(0)
	s_barrier
	ds_read_b128 v[144:147], v186
	ds_read_b128 v[148:151], v187 offset:18432
	ds_read_b128 v[152:155], v187 offset:23040
	ds_read_b128 v[156:159], v186 offset:4608
	ds_read_b128 v[160:163], v186 offset:32
	ds_read_b128 v[164:167], v187 offset:18464
	ds_read_b128 v[168:171], v187 offset:23072
	ds_read_b128 v[172:175], v186 offset:4640
	s_setprio 1
	s_waitcnt lgkmcnt(6)
	v_mfma_f32_32x32x16_bf16 v[52:67], v[148:151], v[144:147], v[52:67]
	s_waitcnt vmcnt(15)
	ds_write_b128 v185, v[108:111]
	s_waitcnt lgkmcnt(6)
	v_mfma_f32_32x32x16_bf16 v[36:51], v[152:155], v[144:147], v[36:51]
	s_waitcnt vmcnt(14)
	ds_write_b128 v185, v[112:115] offset:4608
	s_waitcnt lgkmcnt(6)
	v_mfma_f32_32x32x16_bf16 v[20:35], v[148:151], v[156:159], v[20:35]
	s_waitcnt vmcnt(13)
	ds_write_b128 v185, v[116:119] offset:9216
	global_load_dwordx4 v[108:111], v[72:73], off offset:1408
	v_mfma_f32_32x32x16_bf16 v[4:19], v[152:155], v[156:159], v[4:19]
	ds_read_b128 v[144:147], v186 offset:64
	ds_read_b128 v[148:151], v187 offset:18496
	s_waitcnt lgkmcnt(7)
	v_mfma_f32_32x32x16_bf16 v[52:67], v[164:167], v[160:163], v[52:67]
	ds_read_b128 v[152:155], v187 offset:23104
	ds_read_b128 v[156:159], v186 offset:4672
	s_waitcnt lgkmcnt(8)
	v_mfma_f32_32x32x16_bf16 v[36:51], v[168:171], v[160:163], v[36:51]
	s_waitcnt vmcnt(13)
	ds_write_b128 v185, v[120:123] offset:13824
	global_load_dwordx4 v[112:115], v[74:75], off offset:1408
	s_waitcnt lgkmcnt(8)
	v_mfma_f32_32x32x16_bf16 v[20:35], v[164:167], v[172:175], v[20:35]
	s_waitcnt vmcnt(13)
	ds_write_b128 v185, v[124:127] offset:18432
	global_load_dwordx4 v[116:119], v[106:107], off offset:1408
	v_mfma_f32_32x32x16_bf16 v[4:19], v[168:171], v[172:175], v[4:19]
	ds_read_b128 v[160:163], v186 offset:96
	ds_read_b128 v[164:167], v187 offset:18528
	s_waitcnt lgkmcnt(6)
	v_mfma_f32_32x32x16_bf16 v[52:67], v[148:151], v[144:147], v[52:67]
	ds_read_b128 v[168:171], v187 offset:23136
	ds_read_b128 v[172:175], v186 offset:4704
	s_waitcnt lgkmcnt(7)
	v_mfma_f32_32x32x16_bf16 v[36:51], v[152:155], v[144:147], v[36:51]
	s_waitcnt vmcnt(13)
	ds_write_b128 v185, v[128:131] offset:23040
	global_load_dwordx4 v[120:123], v[176:177], off offset:1408
	s_waitcnt lgkmcnt(7)
	v_mfma_f32_32x32x16_bf16 v[20:35], v[148:151], v[156:159], v[20:35]
	s_waitcnt vmcnt(13)
	ds_write_b128 v185, v[136:139] offset:27648
	global_load_dwordx4 v[124:127], v[104:105], off offset:1408
	v_mfma_f32_32x32x16_bf16 v[4:19], v[152:155], v[156:159], v[4:19]
	s_waitcnt vmcnt(13)
	ds_write_b128 v185, v[140:143] offset:32256
	global_load_dwordx4 v[128:131], v[178:179], off offset:1408
	s_waitcnt lgkmcnt(5)
	v_mfma_f32_32x32x16_bf16 v[52:67], v[164:167], v[160:163], v[52:67]
	global_load_dwordx4 v[136:139], v[180:181], off offset:1408
	s_waitcnt lgkmcnt(4)
	v_mfma_f32_32x32x16_bf16 v[36:51], v[168:171], v[160:163], v[36:51]
	global_load_dwordx4 v[140:143], v[182:183], off offset:1408
	s_waitcnt lgkmcnt(3)
	v_mfma_f32_32x32x16_bf16 v[20:35], v[164:167], v[172:175], v[20:35]
	v_mfma_f32_32x32x16_bf16 v[4:19], v[168:171], v[172:175], v[4:19]
	s_setprio 0
	s_waitcnt lgkmcnt(0)
	s_barrier
	ds_read_b128 v[144:147], v186 offset:36864
	ds_read_b128 v[148:151], v187 offset:55296
	ds_read_b128 v[152:155], v187 offset:59904
	ds_read_b128 v[156:159], v186 offset:41472
	ds_read_b128 v[160:163], v186 offset:36896
	ds_read_b128 v[164:167], v187 offset:55328
	ds_read_b128 v[168:171], v187 offset:59936
	ds_read_b128 v[172:175], v186 offset:41504
	s_setprio 1
	s_waitcnt lgkmcnt(6)
	v_mfma_f32_32x32x16_bf16 v[52:67], v[148:151], v[144:147], v[52:67]
	s_waitcnt vmcnt(15)
	ds_write_b128 v184, v[68:71]
	s_waitcnt lgkmcnt(6)
	v_mfma_f32_32x32x16_bf16 v[36:51], v[152:155], v[144:147], v[36:51]
	s_waitcnt vmcnt(14)
	ds_write_b128 v184, v[76:79] offset:4608
	s_waitcnt lgkmcnt(6)
	v_mfma_f32_32x32x16_bf16 v[20:35], v[148:151], v[156:159], v[20:35]
	s_waitcnt vmcnt(13)
	ds_write_b128 v184, v[80:83] offset:9216
	v_mfma_f32_32x32x16_bf16 v[4:19], v[152:155], v[156:159], v[4:19]
	ds_read_b128 v[144:147], v186 offset:36928
	ds_read_b128 v[148:151], v187 offset:55360
	s_waitcnt lgkmcnt(7)
	v_mfma_f32_32x32x16_bf16 v[52:67], v[164:167], v[160:163], v[52:67]
	ds_read_b128 v[152:155], v187 offset:59968
	ds_read_b128 v[156:159], v186 offset:41536
	s_waitcnt lgkmcnt(8)
	v_mfma_f32_32x32x16_bf16 v[36:51], v[168:171], v[160:163], v[36:51]
	s_waitcnt vmcnt(12)
	ds_write_b128 v184, v[84:87] offset:13824
	s_waitcnt lgkmcnt(8)
	v_mfma_f32_32x32x16_bf16 v[20:35], v[164:167], v[172:175], v[20:35]
	s_waitcnt vmcnt(11)
	ds_write_b128 v184, v[88:91] offset:18432
	v_mfma_f32_32x32x16_bf16 v[4:19], v[168:171], v[172:175], v[4:19]
	ds_read_b128 v[160:163], v186 offset:36960
	ds_read_b128 v[164:167], v187 offset:55392
	s_waitcnt lgkmcnt(6)
	v_mfma_f32_32x32x16_bf16 v[52:67], v[148:151], v[144:147], v[52:67]
	ds_read_b128 v[168:171], v187 offset:60000
	ds_read_b128 v[172:175], v186 offset:41568
	s_waitcnt lgkmcnt(7)
	v_mfma_f32_32x32x16_bf16 v[36:51], v[152:155], v[144:147], v[36:51]
	s_waitcnt vmcnt(10)
	ds_write_b128 v184, v[92:95] offset:23040
	s_waitcnt lgkmcnt(7)
	v_mfma_f32_32x32x16_bf16 v[20:35], v[148:151], v[156:159], v[20:35]
	s_waitcnt vmcnt(9)
	ds_write_b128 v184, v[96:99] offset:27648
	v_mfma_f32_32x32x16_bf16 v[4:19], v[152:155], v[156:159], v[4:19]
	s_waitcnt vmcnt(8)
	ds_write_b128 v184, v[100:103] offset:32256
	s_waitcnt lgkmcnt(5)
	v_mfma_f32_32x32x16_bf16 v[52:67], v[164:167], v[160:163], v[52:67]
	s_waitcnt lgkmcnt(4)
	v_mfma_f32_32x32x16_bf16 v[36:51], v[168:171], v[160:163], v[36:51]
	s_waitcnt lgkmcnt(3)
	v_mfma_f32_32x32x16_bf16 v[20:35], v[164:167], v[172:175], v[20:35]
	v_mfma_f32_32x32x16_bf16 v[4:19], v[168:171], v[172:175], v[4:19]
	s_setprio 0
	s_waitcnt lgkmcnt(0)
	s_barrier
	ds_read_b128 v[144:147], v186
	ds_read_b128 v[148:151], v187 offset:18432
	ds_read_b128 v[152:155], v187 offset:23040
	ds_read_b128 v[156:159], v186 offset:4608
	ds_read_b128 v[160:163], v186 offset:32
	ds_read_b128 v[164:167], v187 offset:18464
	ds_read_b128 v[168:171], v187 offset:23072
	ds_read_b128 v[172:175], v186 offset:4640
	s_setprio 1
	s_waitcnt lgkmcnt(6)
	v_mfma_f32_32x32x16_bf16 v[52:67], v[148:151], v[144:147], v[52:67]
	s_waitcnt vmcnt(7)
	ds_write_b128 v185, v[108:111]
	s_waitcnt lgkmcnt(6)
	v_mfma_f32_32x32x16_bf16 v[36:51], v[152:155], v[144:147], v[36:51]
	s_waitcnt vmcnt(6)
	ds_write_b128 v185, v[112:115] offset:4608
	s_waitcnt lgkmcnt(6)
	v_mfma_f32_32x32x16_bf16 v[20:35], v[148:151], v[156:159], v[20:35]
	s_waitcnt vmcnt(5)
	ds_write_b128 v185, v[116:119] offset:9216
	v_mfma_f32_32x32x16_bf16 v[4:19], v[152:155], v[156:159], v[4:19]
	ds_read_b128 v[144:147], v186 offset:64
	ds_read_b128 v[148:151], v187 offset:18496
	s_waitcnt lgkmcnt(7)
	v_mfma_f32_32x32x16_bf16 v[52:67], v[164:167], v[160:163], v[52:67]
	ds_read_b128 v[152:155], v187 offset:23104
	ds_read_b128 v[156:159], v186 offset:4672
	s_waitcnt lgkmcnt(8)
	v_mfma_f32_32x32x16_bf16 v[36:51], v[168:171], v[160:163], v[36:51]
	s_waitcnt vmcnt(4)
	ds_write_b128 v185, v[120:123] offset:13824
	s_waitcnt lgkmcnt(8)
	v_mfma_f32_32x32x16_bf16 v[20:35], v[164:167], v[172:175], v[20:35]
	s_waitcnt vmcnt(3)
	ds_write_b128 v185, v[124:127] offset:18432
	v_mfma_f32_32x32x16_bf16 v[4:19], v[168:171], v[172:175], v[4:19]
	ds_read_b128 v[160:163], v186 offset:96
	ds_read_b128 v[164:167], v187 offset:18528
	s_waitcnt lgkmcnt(6)
	v_mfma_f32_32x32x16_bf16 v[52:67], v[148:151], v[144:147], v[52:67]
	ds_read_b128 v[168:171], v187 offset:23136
	ds_read_b128 v[172:175], v186 offset:4704
	s_waitcnt lgkmcnt(7)
	v_mfma_f32_32x32x16_bf16 v[36:51], v[152:155], v[144:147], v[36:51]
	s_waitcnt vmcnt(2)
	ds_write_b128 v185, v[128:131] offset:23040
	s_waitcnt lgkmcnt(7)
	v_mfma_f32_32x32x16_bf16 v[20:35], v[148:151], v[156:159], v[20:35]
	s_waitcnt vmcnt(1)
	ds_write_b128 v185, v[136:139] offset:27648
	v_mfma_f32_32x32x16_bf16 v[4:19], v[152:155], v[156:159], v[4:19]
	s_waitcnt vmcnt(0)
	ds_write_b128 v185, v[140:143] offset:32256
	s_waitcnt lgkmcnt(5)
	v_mfma_f32_32x32x16_bf16 v[52:67], v[164:167], v[160:163], v[52:67]
	s_waitcnt lgkmcnt(4)
	v_mfma_f32_32x32x16_bf16 v[36:51], v[168:171], v[160:163], v[36:51]
	s_waitcnt lgkmcnt(3)
	v_mfma_f32_32x32x16_bf16 v[20:35], v[164:167], v[172:175], v[20:35]
	v_mfma_f32_32x32x16_bf16 v[4:19], v[168:171], v[172:175], v[4:19]
	s_setprio 0
	s_waitcnt lgkmcnt(0)
	s_barrier
	ds_read_b128 v[144:147], v186 offset:36864
	ds_read_b128 v[148:151], v187 offset:55296
	ds_read_b128 v[152:155], v187 offset:59904
	ds_read_b128 v[156:159], v186 offset:41472
	ds_read_b128 v[160:163], v186 offset:36896
	ds_read_b128 v[164:167], v187 offset:55328
	ds_read_b128 v[168:171], v187 offset:59936
	ds_read_b128 v[172:175], v186 offset:41504
	s_setprio 1
	s_waitcnt lgkmcnt(6)
	v_mfma_f32_32x32x16_bf16 v[52:67], v[148:151], v[144:147], v[52:67]
	s_waitcnt lgkmcnt(5)
	v_mfma_f32_32x32x16_bf16 v[36:51], v[152:155], v[144:147], v[36:51]
	s_waitcnt lgkmcnt(4)
	v_mfma_f32_32x32x16_bf16 v[20:35], v[148:151], v[156:159], v[20:35]
	v_mfma_f32_32x32x16_bf16 v[4:19], v[152:155], v[156:159], v[4:19]
	ds_read_b128 v[144:147], v186 offset:36928
	ds_read_b128 v[148:151], v187 offset:55360
	s_waitcnt lgkmcnt(4)
	v_mfma_f32_32x32x16_bf16 v[52:67], v[164:167], v[160:163], v[52:67]
	ds_read_b128 v[152:155], v187 offset:59968
	ds_read_b128 v[156:159], v186 offset:41536
	s_waitcnt lgkmcnt(5)
	v_mfma_f32_32x32x16_bf16 v[36:51], v[168:171], v[160:163], v[36:51]
	s_waitcnt lgkmcnt(4)
	v_mfma_f32_32x32x16_bf16 v[20:35], v[164:167], v[172:175], v[20:35]
	v_mfma_f32_32x32x16_bf16 v[4:19], v[168:171], v[172:175], v[4:19]
	ds_read_b128 v[160:163], v186 offset:36960
	ds_read_b128 v[164:167], v187 offset:55392
	s_waitcnt lgkmcnt(4)
	v_mfma_f32_32x32x16_bf16 v[52:67], v[148:151], v[144:147], v[52:67]
	ds_read_b128 v[168:171], v187 offset:60000
	ds_read_b128 v[172:175], v186 offset:41568
	s_waitcnt lgkmcnt(5)
	v_mfma_f32_32x32x16_bf16 v[36:51], v[152:155], v[144:147], v[36:51]
	s_waitcnt lgkmcnt(4)
	v_mfma_f32_32x32x16_bf16 v[20:35], v[148:151], v[156:159], v[20:35]
	v_mfma_f32_32x32x16_bf16 v[4:19], v[152:155], v[156:159], v[4:19]
	s_waitcnt lgkmcnt(2)
	v_mfma_f32_32x32x16_bf16 v[52:67], v[164:167], v[160:163], v[52:67]
	s_waitcnt lgkmcnt(1)
	v_mfma_f32_32x32x16_bf16 v[36:51], v[168:171], v[160:163], v[36:51]
	s_waitcnt lgkmcnt(0)
	v_mfma_f32_32x32x16_bf16 v[20:35], v[164:167], v[172:175], v[20:35]
	v_mfma_f32_32x32x16_bf16 v[4:19], v[168:171], v[172:175], v[4:19]
	s_setprio 0
	s_barrier
	s_nop 7
	s_nop 4
	s_branch .LBB0_574
